# P4 pipelined + residual-tile touch-prefetch at the 4 residual GEMM epilogues (aligned)
# baseline (speedup 1.0000x reference)
; __device__ __forceinline__ void p4_gn_gate(Frame& F) {
;     ...
;     for (int t = gw; t < M * NH; t += NGW) {
;         const int r = t >> 3, h = t & 7; const size_t off = (size_t)r * HV + h * DV + 8 * F.lane;
;         const u32x4 ov = *(const u32x4*)(O + off), gv = *(const u32x4*)(G + off);
;         float o[8], g[8];
; #pragma unroll
;         for (int i = 0; i < 4; ++i) { o[2 * i] = __uint_as_float(ov[i] << 16); o[2 * i + 1] = __uint_as_float(ov[i] & 0xffff0000u); g[2 * i] = __uint_as_float(gv[i] << 16); g[2 * i + 1] = __uint_as_float(gv[i] & 0xffff0000u); }
;         float s = 0.f;
; #pragma unroll
;         for (int i = 0; i < 8; ++i) s += o[i];
;         const float mu = wave_sum(s) * (1.0f / DV); float q = 0.f;
; #pragma unroll
;         for (int i = 0; i < 8; ++i) { o[i] -= mu; q += o[i] * o[i]; }
;         const float rstd = 1.0f / sqrtf(wave_sum(q) * (1.0f / DV) + 1e-6f);
.Lp4_loop:
	s_cmp_lt_i32 s10, 0x12000
	s_cbranch_scc0 .Lp4_done
	s_min_u32 s0, s10, 0x11fff
	s_lshr_b32 s0, s0, 3
	s_lshl_b32 s0, s0, 12
	s_add_u32 s46, s8, s0
	s_addc_u32 s47, s9, 0
	s_add_i32 s14, s10, s16
	s_min_u32 s14, s14, 0x11fff
	s_lshr_b32 s14, s14, 3
	s_lshl_b32 s14, s14, 12
	s_add_u32 s50, s8, s14
	s_addc_u32 s51, s9, 0
	s_waitcnt vmcnt(12)
	v_lshlrev_b32_e32 v224, 16, v16
	v_lshlrev_b32_e32 v232, 16, v24
	v_and_b32_e32 v16, 0xffff0000, v16
	v_and_b32_e32 v24, 0xffff0000, v24
	v_add_f32_e32 v143, 0, v224
	v_add_f32_e32 v210, 0, v232
	v_lshlrev_b32_e32 v225, 16, v17
	v_lshlrev_b32_e32 v233, 16, v25
	v_add_f32_e32 v143, v143, v16
	v_add_f32_e32 v210, v210, v24
	v_and_b32_e32 v17, 0xffff0000, v17
	v_and_b32_e32 v25, 0xffff0000, v25
	v_add_f32_e32 v143, v143, v225
	v_add_f32_e32 v210, v210, v233
	v_lshlrev_b32_e32 v226, 16, v18
	v_lshlrev_b32_e32 v234, 16, v26
	v_add_f32_e32 v143, v143, v17
	v_add_f32_e32 v210, v210, v25
	v_and_b32_e32 v18, 0xffff0000, v18
	v_and_b32_e32 v26, 0xffff0000, v26
	v_add_f32_e32 v143, v143, v226
	v_add_f32_e32 v210, v210, v234
	v_lshlrev_b32_e32 v227, 16, v19
	v_lshlrev_b32_e32 v235, 16, v27
	v_add_f32_e32 v143, v143, v18
	v_add_f32_e32 v210, v210, v26
	v_and_b32_e32 v19, 0xffff0000, v19
	v_and_b32_e32 v27, 0xffff0000, v27
	v_add_f32_e32 v143, v143, v227
	v_add_f32_e32 v210, v210, v235
	v_add_f32_e32 v143, v143, v19
	v_add_f32_e32 v210, v210, v27
	ds_bpermute_b32 v153, v1, v143
	ds_bpermute_b32 v211, v1, v210
	v_lshlrev_b32_e32 v228, 16, v20
	v_lshlrev_b32_e32 v236, 16, v28
	v_and_b32_e32 v20, 0xffff0000, v20
	s_waitcnt lgkmcnt(1)
	v_add_f32_e32 v143, v143, v153
	s_waitcnt lgkmcnt(0)
	v_add_f32_e32 v210, v210, v211
	ds_bpermute_b32 v153, v3, v143
	ds_bpermute_b32 v211, v3, v210
	v_and_b32_e32 v28, 0xffff0000, v28
	v_lshlrev_b32_e32 v229, 16, v21
	v_lshlrev_b32_e32 v237, 16, v29
	s_waitcnt lgkmcnt(1)
	v_add_f32_e32 v143, v143, v153
	s_waitcnt lgkmcnt(0)
	v_add_f32_e32 v210, v210, v211
	ds_bpermute_b32 v153, v6, v143
	ds_bpermute_b32 v211, v6, v210
	v_and_b32_e32 v21, 0xffff0000, v21
	v_and_b32_e32 v29, 0xffff0000, v29
	v_lshlrev_b32_e32 v230, 16, v22
	s_waitcnt lgkmcnt(1)
	v_add_f32_e32 v143, v143, v153
	s_waitcnt lgkmcnt(0)
	v_add_f32_e32 v210, v210, v211
	ds_bpermute_b32 v153, v7, v143
	ds_bpermute_b32 v211, v7, v210
	v_lshlrev_b32_e32 v238, 16, v30
	v_and_b32_e32 v22, 0xffff0000, v22
	v_and_b32_e32 v30, 0xffff0000, v30
	s_waitcnt lgkmcnt(1)
	v_add_f32_e32 v143, v143, v153
	s_waitcnt lgkmcnt(0)
	v_add_f32_e32 v210, v210, v211
	ds_bpermute_b32 v153, v8, v143
	ds_bpermute_b32 v211, v8, v210
	v_lshlrev_b32_e32 v231, 16, v23
	v_lshlrev_b32_e32 v239, 16, v31
	v_and_b32_e32 v23, 0xffff0000, v23
	s_waitcnt lgkmcnt(1)
	v_add_f32_e32 v143, v143, v153
	s_waitcnt lgkmcnt(0)
	v_add_f32_e32 v210, v210, v211
	ds_bpermute_b32 v153, v9, v143
	ds_bpermute_b32 v211, v9, v210
	v_and_b32_e32 v31, 0xffff0000, v31
	s_waitcnt lgkmcnt(1)
	v_add_f32_e32 v143, v143, v153
	s_waitcnt lgkmcnt(0)
	v_add_f32_e32 v210, v210, v211
	v_fmac_f32_e32 v16, 0xbb000000, v143
	v_fmac_f32_e32 v24, 0xbb000000, v210
	v_fmac_f32_e32 v224, 0xbb000000, v143
	v_fmac_f32_e32 v232, 0xbb000000, v210
	v_fmac_f32_e32 v225, 0xbb000000, v143
	v_fmac_f32_e32 v233, 0xbb000000, v210
	v_fmac_f32_e32 v17, 0xbb000000, v143
	v_fmac_f32_e32 v25, 0xbb000000, v210
	v_fmac_f32_e32 v226, 0xbb000000, v143
	v_fmac_f32_e32 v234, 0xbb000000, v210
	v_fmac_f32_e32 v18, 0xbb000000, v143
	v_fmac_f32_e32 v26, 0xbb000000, v210
	v_fmac_f32_e32 v227, 0xbb000000, v143
	v_fmac_f32_e32 v235, 0xbb000000, v210
	v_fmac_f32_e32 v19, 0xbb000000, v143
	v_fmac_f32_e32 v27, 0xbb000000, v210
	v_mul_f32_e32 v143, v16, v16
	v_mul_f32_e32 v210, v24, v24
	v_fmac_f32_e32 v143, v224, v224
	v_fmac_f32_e32 v210, v232, v232
	v_fmac_f32_e32 v143, v225, v225
	v_fmac_f32_e32 v210, v233, v233
	v_fmac_f32_e32 v143, v17, v17
	v_fmac_f32_e32 v210, v25, v25
	v_fmac_f32_e32 v143, v226, v226
	v_fmac_f32_e32 v210, v234, v234
	v_fmac_f32_e32 v143, v18, v18
	v_fmac_f32_e32 v210, v26, v26
	v_fmac_f32_e32 v143, v227, v227
	v_fmac_f32_e32 v210, v235, v235
	v_fmac_f32_e32 v143, v19, v19
	v_fmac_f32_e32 v210, v27, v27
	ds_bpermute_b32 v153, v1, v143
	ds_bpermute_b32 v211, v1, v210
	s_waitcnt lgkmcnt(1)
	v_add_f32_e32 v143, v143, v153
	s_waitcnt lgkmcnt(0)
	v_add_f32_e32 v210, v210, v211
	ds_bpermute_b32 v153, v3, v143
	ds_bpermute_b32 v211, v3, v210
	s_waitcnt lgkmcnt(1)
	v_add_f32_e32 v143, v143, v153
	s_waitcnt lgkmcnt(0)
	v_add_f32_e32 v210, v210, v211
	ds_bpermute_b32 v153, v6, v143
	ds_bpermute_b32 v211, v6, v210
	s_waitcnt lgkmcnt(1)
	v_add_f32_e32 v143, v143, v153
	s_waitcnt lgkmcnt(0)
	v_add_f32_e32 v210, v210, v211
	ds_bpermute_b32 v153, v7, v143
	ds_bpermute_b32 v211, v7, v210
	s_waitcnt lgkmcnt(1)
	v_add_f32_e32 v143, v143, v153
	s_waitcnt lgkmcnt(0)
	v_add_f32_e32 v210, v210, v211
	ds_bpermute_b32 v153, v8, v143
	ds_bpermute_b32 v211, v8, v210
	s_waitcnt lgkmcnt(1)
	v_add_f32_e32 v143, v143, v153
	s_waitcnt lgkmcnt(0)
	v_add_f32_e32 v210, v210, v211
	ds_bpermute_b32 v153, v9, v143
	ds_bpermute_b32 v211, v9, v210
	s_waitcnt lgkmcnt(1)
	v_add_f32_e32 v143, v143, v153
	s_waitcnt lgkmcnt(0)
; __device__ __forceinline__ unsigned pk2(float lo, float hi) { unsigned r; asm("v_cvt_pk_bf16_f32 %0, %1, %2" : "=v"(r) : "v"(lo), "v"(hi)); return r; }
; __device__ __forceinline__ void p4_gn_gate(Frame& F) {
;     ...
;         const float rstd = 1.0f / sqrtf(wave_sum(q) * (1.0f / DV) + 1e-6f);
;         const f32x4 w0 = *(const f32x4*)(F.ret_gn_g + h * DV + 8 * F.lane), w1 = *(const f32x4*)(F.ret_gn_g + h * DV + 8 * F.lane + 4);
;         float y[8];
; #pragma unroll
;         for (int i = 0; i < 4; ++i) { y[i] = g[i] * (o[i] * rstd * w0[i]); y[i + 4] = g[i + 4] * (o[i + 4] * rstd * w1[i]); }
;         if (FP8O) { u32x2 out; out.x = pk4_fp8(y[0] * S_A2, y[1] * S_A2, y[2] * S_A2, y[3] * S_A2); out.y = pk4_fp8(y[4] * S_A2, y[5] * S_A2, y[6] * S_A2, y[7] * S_A2); *(u32x2*)((unsigned char*)A2 + off) = out; }
;         else { u32x4 out; out.x = pk2(y[0], y[1]); out.y = pk2(y[2], y[3]); out.z = pk2(y[4], y[5]); out.w = pk2(y[6], y[7]); *(u32x4*)(A2 + off) = out; }
	v_add_f32_e32 v210, v210, v211
	v_fmamk_f32 v143, v143, 0x3b000000, v10
	v_mul_f32_e32 v153, 0x4f800000, v143
	v_cmp_gt_f32_e32 vcc, s19, v143
	s_nop 1
	v_cndmask_b32_e32 v143, v143, v153, vcc
	v_sqrt_f32_e32 v153, v143
	s_nop 0
	v_add_u32_e32 v155, -1, v153
	v_add_u32_e32 v159, 1, v153
	v_fma_f32 v221, -v155, v153, v143
	v_fma_f32 v46, -v159, v153, v143
	v_cmp_ge_f32_e64 s[56:57], 0, v221
	s_nop 1
	v_cndmask_b32_e64 v153, v153, v155, s[56:57]
	v_cmp_lt_f32_e64 s[56:57], 0, v46
	s_nop 1
	v_cndmask_b32_e64 v153, v153, v159, s[56:57]
	v_mul_f32_e32 v155, 0x37800000, v153
	v_cndmask_b32_e32 v153, v153, v155, vcc
	v_cmp_class_f32_e32 vcc, v143, v11
	s_nop 1
	v_cndmask_b32_e32 v143, v153, v143, vcc
	v_div_scale_f32 v153, s[56:57], v143, v143, 1.0
	v_rcp_f32_e32 v159, v153
	v_div_scale_f32 v155, vcc, 1.0, v143, 1.0
	v_fma_f32 v221, -v153, v159, 1.0
	v_fmac_f32_e32 v159, v221, v159
	v_mul_f32_e32 v221, v155, v159
	v_fma_f32 v46, -v153, v221, v155
	v_fmac_f32_e32 v221, v46, v159
	v_fma_f32 v153, -v153, v221, v155
	v_div_fmas_f32 v153, v153, v159, v221
	v_div_fixup_f32 v143, v153, v143, 1.0
	v_fmamk_f32 v210, v210, 0x3b000000, v10
	v_mul_f32_e32 v211, 0x4f800000, v210
	v_cmp_gt_f32_e32 vcc, s19, v210
	s_nop 1
	v_cndmask_b32_e32 v210, v210, v211, vcc
	v_sqrt_f32_e32 v211, v210
	s_nop 0
	v_add_u32_e32 v192, -1, v211
	v_add_u32_e32 v193, 1, v211
	v_fma_f32 v222, -v192, v211, v210
	v_fma_f32 v223, -v193, v211, v210
	v_cmp_ge_f32_e64 s[58:59], 0, v222
	s_nop 1
	v_cndmask_b32_e64 v211, v211, v192, s[58:59]
	v_cmp_lt_f32_e64 s[58:59], 0, v223
	s_nop 1
	v_cndmask_b32_e64 v211, v211, v193, s[58:59]
	v_mul_f32_e32 v192, 0x37800000, v211
	v_cndmask_b32_e32 v211, v211, v192, vcc
	v_cmp_class_f32_e32 vcc, v210, v11
	s_nop 1
	v_cndmask_b32_e32 v210, v211, v210, vcc
	v_div_scale_f32 v211, s[58:59], v210, v210, 1.0
	v_rcp_f32_e32 v193, v211
	v_div_scale_f32 v192, vcc, 1.0, v210, 1.0
	v_fma_f32 v222, -v211, v193, 1.0
	v_fmac_f32_e32 v193, v222, v193
	v_mul_f32_e32 v222, v192, v193
	v_fma_f32 v223, -v211, v222, v192
	v_fmac_f32_e32 v222, v223, v193
	v_fma_f32 v211, -v211, v222, v192
	v_div_fmas_f32 v211, v211, v193, v222
	v_div_fixup_f32 v210, v211, v210, 1.0
	v_mul_f32_e32 v224, v224, v143
	v_mul_f32_e32 v232, v232, v210
	v_mul_f32_e32 v16, v16, v143
	v_mul_f32_e32 v24, v24, v210
	v_mul_f32_e32 v226, v226, v143
	v_mul_f32_e32 v234, v234, v210
	v_mul_f32_e32 v18, v18, v143
	v_mul_f32_e32 v26, v26, v210
	v_mul_f32_e32 v224, v212, v224
	v_mul_f32_e32 v232, v212, v232
	v_mul_f32_e32 v16, v213, v16
	v_mul_f32_e32 v24, v213, v24
	v_mul_f32_e32 v226, v216, v226
	v_mul_f32_e32 v234, v216, v234
	v_mul_f32_e32 v18, v217, v18
	v_mul_f32_e32 v26, v217, v26
	v_mul_f32_e32 v224, v224, v228
	v_mul_f32_e32 v232, v232, v236
	v_mul_f32_e32 v16, v16, v20
	v_mul_f32_e32 v24, v24, v28
	v_mul_f32_e32 v226, v226, v230
	v_mul_f32_e32 v234, v234, v238
	v_mul_f32_e32 v18, v18, v22
	v_mul_f32_e32 v26, v26, v30
	v_mul_f32_e32 v224, 0x41000000, v224
	v_mul_f32_e32 v232, 0x41000000, v232
	v_mul_f32_e32 v16, 0x41000000, v16
	v_mul_f32_e32 v24, 0x41000000, v24
	v_mul_f32_e32 v226, 0x41000000, v226
	v_mul_f32_e32 v234, 0x41000000, v234
	v_mul_f32_e32 v18, 0x41000000, v18
	v_mul_f32_e32 v26, 0x41000000, v26
	v_med3_f32 v224, v224, s20, v12
	v_med3_f32 v232, v232, s20, v12
	v_med3_f32 v16, v16, s20, v12
	v_med3_f32 v24, v24, s20, v12
	v_med3_f32 v226, v226, s20, v12
	v_med3_f32 v234, v234, s20, v12
	v_med3_f32 v18, v18, s20, v12
	v_med3_f32 v26, v26, s20, v12
	v_cvt_pk_fp8_f32 v44, v224, v16
	v_cvt_pk_fp8_f32 v70, v232, v24
	v_cvt_pk_fp8_f32 v45, v226, v18
	v_cvt_pk_fp8_f32 v71, v234, v26
	v_mul_f32_e32 v225, v225, v143
	v_mul_f32_e32 v233, v233, v210
	v_mul_f32_e32 v17, v17, v143
	v_mul_f32_e32 v25, v25, v210
	v_mul_f32_e32 v227, v227, v143
	v_mul_f32_e32 v235, v235, v210
	v_mul_f32_e32 v19, v19, v143
	v_mul_f32_e32 v27, v27, v210
	v_mul_f32_e32 v225, v214, v225
	v_mul_f32_e32 v233, v214, v233
	v_mul_f32_e32 v17, v215, v17
	v_mul_f32_e32 v25, v215, v25
	v_mul_f32_e32 v227, v218, v227
	v_mul_f32_e32 v235, v218, v235
	v_mul_f32_e32 v19, v219, v19
	v_mul_f32_e32 v27, v219, v27
	v_mul_f32_e32 v225, v225, v229
	v_mul_f32_e32 v233, v233, v237
	v_mul_f32_e32 v17, v17, v21
	v_mul_f32_e32 v25, v25, v29
	v_mul_f32_e32 v227, v227, v231
	v_mul_f32_e32 v235, v235, v239
	v_mul_f32_e32 v19, v19, v23
	v_mul_f32_e32 v27, v27, v31
	v_mul_f32_e32 v225, 0x41000000, v225
	v_mul_f32_e32 v233, 0x41000000, v233
	v_mul_f32_e32 v17, 0x41000000, v17
	v_mul_f32_e32 v25, 0x41000000, v25
	v_mul_f32_e32 v227, 0x41000000, v227
	v_mul_f32_e32 v235, 0x41000000, v235
	v_mul_f32_e32 v19, 0x41000000, v19
	v_mul_f32_e32 v27, 0x41000000, v27
	v_med3_f32 v225, v225, s20, v12
	v_med3_f32 v233, v233, s20, v12
	v_med3_f32 v17, v17, s20, v12
	v_med3_f32 v25, v25, s20, v12
	v_med3_f32 v227, v227, s20, v12
	v_med3_f32 v235, v235, s20, v12
	v_med3_f32 v19, v19, s20, v12
	v_med3_f32 v27, v27, s20, v12
	v_cvt_pk_fp8_f32 v44, v225, v17 op_sel:[0,0,1]
	v_cvt_pk_fp8_f32 v70, v233, v25 op_sel:[0,0,1]
	v_cvt_pk_fp8_f32 v45, v227, v19 op_sel:[0,0,1]
	v_cvt_pk_fp8_f32 v71, v235, v27 op_sel:[0,0,1]
	s_add_i32 s10, s10, s16
	s_add_i32 s10, s10, s16
	global_store_dwordx2 v15, v[44:45], s[46:47]
	global_store_dwordx2 v15, v[70:71], s[50:51]
	s_min_u32 s0, s1, 0x11fff
	s_lshr_b32 s0, s0, 3
	s_lshl_b32 s0, s0, 13
	s_add_u32 s32, s4, s0
	s_addc_u32 s33, s5, 0
	s_add_u32 s40, s6, s0
	s_addc_u32 s41, s7, 0
	global_load_dwordx4 v[16:19], v13, s[32:33]
	global_load_dwordx4 v[20:23], v13, s[40:41]
	s_add_i32 s1, s1, s16
	s_min_u32 s0, s1, 0x11fff
	s_lshr_b32 s0, s0, 3
	s_lshl_b32 s0, s0, 13
	s_add_u32 s32, s4, s0
	s_addc_u32 s33, s5, 0
	s_add_u32 s40, s6, s0
	s_addc_u32 s41, s7, 0
	global_load_dwordx4 v[24:27], v13, s[32:33]
	global_load_dwordx4 v[28:31], v13, s[40:41]
	s_add_i32 s1, s1, s16
	s_cmp_lt_i32 s10, 0x12000
	s_cbranch_scc0 .Lp4_done
; __device__ __forceinline__ void p4_gn_gate(Frame& F) {
;     ...
;     for (int t = gw; t < M * NH; t += NGW) {
;         const int r = t >> 3, h = t & 7; const size_t off = (size_t)r * HV + h * DV + 8 * F.lane;
;         const u32x4 ov = *(const u32x4*)(O + off), gv = *(const u32x4*)(G + off);
;         float o[8], g[8];
; #pragma unroll
;         for (int i = 0; i < 4; ++i) { o[2 * i] = __uint_as_float(ov[i] << 16); o[2 * i + 1] = __uint_as_float(ov[i] & 0xffff0000u); g[2 * i] = __uint_as_float(gv[i] << 16); g[2 * i + 1] = __uint_as_float(gv[i] & 0xffff0000u); }
;         float s = 0.f;
; #pragma unroll
;         for (int i = 0; i < 8; ++i) s += o[i];
;         const float mu = wave_sum(s) * (1.0f / DV); float q = 0.f;
; #pragma unroll
;         for (int i = 0; i < 8; ++i) { o[i] -= mu; q += o[i] * o[i]; }
;         const float rstd = 1.0f / sqrtf(wave_sum(q) * (1.0f / DV) + 1e-6f);
	s_min_u32 s0, s10, 0x11fff
	s_lshr_b32 s0, s0, 3
	s_lshl_b32 s0, s0, 12
	s_add_u32 s46, s8, s0
	s_addc_u32 s47, s9, 0
	s_add_i32 s14, s10, s16
	s_min_u32 s14, s14, 0x11fff
	s_lshr_b32 s14, s14, 3
	s_lshl_b32 s14, s14, 12
	s_add_u32 s50, s8, s14
	s_addc_u32 s51, s9, 0
	s_waitcnt vmcnt(12)
	v_lshlrev_b32_e32 v224, 16, v32
	v_lshlrev_b32_e32 v232, 16, v40
	v_and_b32_e32 v32, 0xffff0000, v32
	v_and_b32_e32 v40, 0xffff0000, v40
	v_add_f32_e32 v143, 0, v224
	v_add_f32_e32 v210, 0, v232
	v_lshlrev_b32_e32 v225, 16, v33
	v_lshlrev_b32_e32 v233, 16, v41
	v_add_f32_e32 v143, v143, v32
	v_add_f32_e32 v210, v210, v40
	v_and_b32_e32 v33, 0xffff0000, v33
	v_and_b32_e32 v41, 0xffff0000, v41
	v_add_f32_e32 v143, v143, v225
	v_add_f32_e32 v210, v210, v233
	v_lshlrev_b32_e32 v226, 16, v34
	v_lshlrev_b32_e32 v234, 16, v42
	v_add_f32_e32 v143, v143, v33
	v_add_f32_e32 v210, v210, v41
	v_and_b32_e32 v34, 0xffff0000, v34
	v_and_b32_e32 v42, 0xffff0000, v42
	v_add_f32_e32 v143, v143, v226
	v_add_f32_e32 v210, v210, v234
	v_lshlrev_b32_e32 v227, 16, v35
	v_lshlrev_b32_e32 v235, 16, v43
	v_add_f32_e32 v143, v143, v34
	v_add_f32_e32 v210, v210, v42
	v_and_b32_e32 v35, 0xffff0000, v35
	v_and_b32_e32 v43, 0xffff0000, v43
	v_add_f32_e32 v143, v143, v227
	v_add_f32_e32 v210, v210, v235
	v_add_f32_e32 v143, v143, v35
	v_add_f32_e32 v210, v210, v43
	ds_bpermute_b32 v153, v1, v143
	ds_bpermute_b32 v211, v1, v210
	v_lshlrev_b32_e32 v228, 16, v36
	v_lshlrev_b32_e32 v236, 16, v48
	v_and_b32_e32 v36, 0xffff0000, v36
	s_waitcnt lgkmcnt(1)
	v_add_f32_e32 v143, v143, v153
	s_waitcnt lgkmcnt(0)
	v_add_f32_e32 v210, v210, v211
	ds_bpermute_b32 v153, v3, v143
	ds_bpermute_b32 v211, v3, v210
	v_and_b32_e32 v48, 0xffff0000, v48
	v_lshlrev_b32_e32 v229, 16, v37
	v_lshlrev_b32_e32 v237, 16, v49
	s_waitcnt lgkmcnt(1)
	v_add_f32_e32 v143, v143, v153
	s_waitcnt lgkmcnt(0)
	v_add_f32_e32 v210, v210, v211
	ds_bpermute_b32 v153, v6, v143
	ds_bpermute_b32 v211, v6, v210
	v_and_b32_e32 v37, 0xffff0000, v37
	v_and_b32_e32 v49, 0xffff0000, v49
	v_lshlrev_b32_e32 v230, 16, v38
	s_waitcnt lgkmcnt(1)
	v_add_f32_e32 v143, v143, v153
	s_waitcnt lgkmcnt(0)
	v_add_f32_e32 v210, v210, v211
	ds_bpermute_b32 v153, v7, v143
	ds_bpermute_b32 v211, v7, v210
	v_lshlrev_b32_e32 v238, 16, v50
	v_and_b32_e32 v38, 0xffff0000, v38
	v_and_b32_e32 v50, 0xffff0000, v50
	s_waitcnt lgkmcnt(1)
	v_add_f32_e32 v143, v143, v153
	s_waitcnt lgkmcnt(0)
	v_add_f32_e32 v210, v210, v211
	ds_bpermute_b32 v153, v8, v143
	ds_bpermute_b32 v211, v8, v210
	v_lshlrev_b32_e32 v231, 16, v39
	v_lshlrev_b32_e32 v239, 16, v51
	v_and_b32_e32 v39, 0xffff0000, v39
	s_waitcnt lgkmcnt(1)
	v_add_f32_e32 v143, v143, v153
	s_waitcnt lgkmcnt(0)
	v_add_f32_e32 v210, v210, v211
	ds_bpermute_b32 v153, v9, v143
	ds_bpermute_b32 v211, v9, v210
	v_and_b32_e32 v51, 0xffff0000, v51
	s_waitcnt lgkmcnt(1)
	v_add_f32_e32 v143, v143, v153
	s_waitcnt lgkmcnt(0)
	v_add_f32_e32 v210, v210, v211
	v_fmac_f32_e32 v32, 0xbb000000, v143
	v_fmac_f32_e32 v40, 0xbb000000, v210
	v_fmac_f32_e32 v224, 0xbb000000, v143
	v_fmac_f32_e32 v232, 0xbb000000, v210
	v_fmac_f32_e32 v225, 0xbb000000, v143
	v_fmac_f32_e32 v233, 0xbb000000, v210
	v_fmac_f32_e32 v33, 0xbb000000, v143
	v_fmac_f32_e32 v41, 0xbb000000, v210
	v_fmac_f32_e32 v226, 0xbb000000, v143
	v_fmac_f32_e32 v234, 0xbb000000, v210
	v_fmac_f32_e32 v34, 0xbb000000, v143
	v_fmac_f32_e32 v42, 0xbb000000, v210
	v_fmac_f32_e32 v227, 0xbb000000, v143
	v_fmac_f32_e32 v235, 0xbb000000, v210
	v_fmac_f32_e32 v35, 0xbb000000, v143
	v_fmac_f32_e32 v43, 0xbb000000, v210
	v_mul_f32_e32 v143, v32, v32
	v_mul_f32_e32 v210, v40, v40
	v_fmac_f32_e32 v143, v224, v224
	v_fmac_f32_e32 v210, v232, v232
	v_fmac_f32_e32 v143, v225, v225
	v_fmac_f32_e32 v210, v233, v233
	v_fmac_f32_e32 v143, v33, v33
	v_fmac_f32_e32 v210, v41, v41
	v_fmac_f32_e32 v143, v226, v226
	v_fmac_f32_e32 v210, v234, v234
	v_fmac_f32_e32 v143, v34, v34
	v_fmac_f32_e32 v210, v42, v42
	v_fmac_f32_e32 v143, v227, v227
	v_fmac_f32_e32 v210, v235, v235
	v_fmac_f32_e32 v143, v35, v35
	v_fmac_f32_e32 v210, v43, v43
	ds_bpermute_b32 v153, v1, v143
	ds_bpermute_b32 v211, v1, v210
	s_waitcnt lgkmcnt(1)
	v_add_f32_e32 v143, v143, v153
	s_waitcnt lgkmcnt(0)
	v_add_f32_e32 v210, v210, v211
	ds_bpermute_b32 v153, v3, v143
	ds_bpermute_b32 v211, v3, v210
	s_waitcnt lgkmcnt(1)
	v_add_f32_e32 v143, v143, v153
	s_waitcnt lgkmcnt(0)
	v_add_f32_e32 v210, v210, v211
	ds_bpermute_b32 v153, v6, v143
	ds_bpermute_b32 v211, v6, v210
	s_waitcnt lgkmcnt(1)
	v_add_f32_e32 v143, v143, v153
	s_waitcnt lgkmcnt(0)
	v_add_f32_e32 v210, v210, v211
	ds_bpermute_b32 v153, v7, v143
	ds_bpermute_b32 v211, v7, v210
	s_waitcnt lgkmcnt(1)
	v_add_f32_e32 v143, v143, v153
	s_waitcnt lgkmcnt(0)
	v_add_f32_e32 v210, v210, v211
	ds_bpermute_b32 v153, v8, v143
	ds_bpermute_b32 v211, v8, v210
	s_waitcnt lgkmcnt(1)
	v_add_f32_e32 v143, v143, v153
	s_waitcnt lgkmcnt(0)
	v_add_f32_e32 v210, v210, v211
	ds_bpermute_b32 v153, v9, v143
	ds_bpermute_b32 v211, v9, v210
	s_waitcnt lgkmcnt(1)
	v_add_f32_e32 v143, v143, v153
	s_waitcnt lgkmcnt(0)
; __device__ __forceinline__ unsigned pk2(float lo, float hi) { unsigned r; asm("v_cvt_pk_bf16_f32 %0, %1, %2" : "=v"(r) : "v"(lo), "v"(hi)); return r; }
; __device__ __forceinline__ void p4_gn_gate(Frame& F) {
;     ...
;         const float rstd = 1.0f / sqrtf(wave_sum(q) * (1.0f / DV) + 1e-6f);
;         const f32x4 w0 = *(const f32x4*)(F.ret_gn_g + h * DV + 8 * F.lane), w1 = *(const f32x4*)(F.ret_gn_g + h * DV + 8 * F.lane + 4);
;         float y[8];
; #pragma unroll
;         for (int i = 0; i < 4; ++i) { y[i] = g[i] * (o[i] * rstd * w0[i]); y[i + 4] = g[i + 4] * (o[i + 4] * rstd * w1[i]); }
;         if (FP8O) { u32x2 out; out.x = pk4_fp8(y[0] * S_A2, y[1] * S_A2, y[2] * S_A2, y[3] * S_A2); out.y = pk4_fp8(y[4] * S_A2, y[5] * S_A2, y[6] * S_A2, y[7] * S_A2); *(u32x2*)((unsigned char*)A2 + off) = out; }
;         else { u32x4 out; out.x = pk2(y[0], y[1]); out.y = pk2(y[2], y[3]); out.z = pk2(y[4], y[5]); out.w = pk2(y[6], y[7]); *(u32x4*)(A2 + off) = out; }
	v_add_f32_e32 v210, v210, v211
	v_fmamk_f32 v143, v143, 0x3b000000, v10
	v_mul_f32_e32 v153, 0x4f800000, v143
	v_cmp_gt_f32_e32 vcc, s19, v143
	s_nop 1
	v_cndmask_b32_e32 v143, v143, v153, vcc
	v_sqrt_f32_e32 v153, v143
	s_nop 0
	v_add_u32_e32 v155, -1, v153
	v_add_u32_e32 v159, 1, v153
	v_fma_f32 v221, -v155, v153, v143
	v_fma_f32 v46, -v159, v153, v143
	v_cmp_ge_f32_e64 s[56:57], 0, v221
	s_nop 1
	v_cndmask_b32_e64 v153, v153, v155, s[56:57]
	v_cmp_lt_f32_e64 s[56:57], 0, v46
	s_nop 1
	v_cndmask_b32_e64 v153, v153, v159, s[56:57]
	v_mul_f32_e32 v155, 0x37800000, v153
	v_cndmask_b32_e32 v153, v153, v155, vcc
	v_cmp_class_f32_e32 vcc, v143, v11
	s_nop 1
	v_cndmask_b32_e32 v143, v153, v143, vcc
	v_div_scale_f32 v153, s[56:57], v143, v143, 1.0
	v_rcp_f32_e32 v159, v153
	v_div_scale_f32 v155, vcc, 1.0, v143, 1.0
	v_fma_f32 v221, -v153, v159, 1.0
	v_fmac_f32_e32 v159, v221, v159
	v_mul_f32_e32 v221, v155, v159
	v_fma_f32 v46, -v153, v221, v155
	v_fmac_f32_e32 v221, v46, v159
	v_fma_f32 v153, -v153, v221, v155
	v_div_fmas_f32 v153, v153, v159, v221
	v_div_fixup_f32 v143, v153, v143, 1.0
	v_fmamk_f32 v210, v210, 0x3b000000, v10
	v_mul_f32_e32 v211, 0x4f800000, v210
	v_cmp_gt_f32_e32 vcc, s19, v210
	s_nop 1
	v_cndmask_b32_e32 v210, v210, v211, vcc
	v_sqrt_f32_e32 v211, v210
	s_nop 0
	v_add_u32_e32 v192, -1, v211
	v_add_u32_e32 v193, 1, v211
	v_fma_f32 v222, -v192, v211, v210
	v_fma_f32 v223, -v193, v211, v210
	v_cmp_ge_f32_e64 s[58:59], 0, v222
	s_nop 1
	v_cndmask_b32_e64 v211, v211, v192, s[58:59]
	v_cmp_lt_f32_e64 s[58:59], 0, v223
	s_nop 1
	v_cndmask_b32_e64 v211, v211, v193, s[58:59]
	v_mul_f32_e32 v192, 0x37800000, v211
	v_cndmask_b32_e32 v211, v211, v192, vcc
	v_cmp_class_f32_e32 vcc, v210, v11
	s_nop 1
	v_cndmask_b32_e32 v210, v211, v210, vcc
	v_div_scale_f32 v211, s[58:59], v210, v210, 1.0
	v_rcp_f32_e32 v193, v211
	v_div_scale_f32 v192, vcc, 1.0, v210, 1.0
	v_fma_f32 v222, -v211, v193, 1.0
	v_fmac_f32_e32 v193, v222, v193
	v_mul_f32_e32 v222, v192, v193
	v_fma_f32 v223, -v211, v222, v192
	v_fmac_f32_e32 v222, v223, v193
	v_fma_f32 v211, -v211, v222, v192
	v_div_fmas_f32 v211, v211, v193, v222
	v_div_fixup_f32 v210, v211, v210, 1.0
	v_mul_f32_e32 v224, v224, v143
	v_mul_f32_e32 v232, v232, v210
	v_mul_f32_e32 v32, v32, v143
	v_mul_f32_e32 v40, v40, v210
	v_mul_f32_e32 v226, v226, v143
	v_mul_f32_e32 v234, v234, v210
	v_mul_f32_e32 v34, v34, v143
	v_mul_f32_e32 v42, v42, v210
	v_mul_f32_e32 v224, v212, v224
	v_mul_f32_e32 v232, v212, v232
	v_mul_f32_e32 v32, v213, v32
	v_mul_f32_e32 v40, v213, v40
	v_mul_f32_e32 v226, v216, v226
	v_mul_f32_e32 v234, v216, v234
	v_mul_f32_e32 v34, v217, v34
	v_mul_f32_e32 v42, v217, v42
	v_mul_f32_e32 v224, v224, v228
	v_mul_f32_e32 v232, v232, v236
	v_mul_f32_e32 v32, v32, v36
	v_mul_f32_e32 v40, v40, v48
	v_mul_f32_e32 v226, v226, v230
	v_mul_f32_e32 v234, v234, v238
	v_mul_f32_e32 v34, v34, v38
	v_mul_f32_e32 v42, v42, v50
	v_mul_f32_e32 v224, 0x41000000, v224
	v_mul_f32_e32 v232, 0x41000000, v232
	v_mul_f32_e32 v32, 0x41000000, v32
	v_mul_f32_e32 v40, 0x41000000, v40
	v_mul_f32_e32 v226, 0x41000000, v226
	v_mul_f32_e32 v234, 0x41000000, v234
	v_mul_f32_e32 v34, 0x41000000, v34
	v_mul_f32_e32 v42, 0x41000000, v42
	v_med3_f32 v224, v224, s20, v12
	v_med3_f32 v232, v232, s20, v12
	v_med3_f32 v32, v32, s20, v12
	v_med3_f32 v40, v40, s20, v12
	v_med3_f32 v226, v226, s20, v12
	v_med3_f32 v234, v234, s20, v12
	v_med3_f32 v34, v34, s20, v12
	v_med3_f32 v42, v42, s20, v12
	v_cvt_pk_fp8_f32 v44, v224, v32
	v_cvt_pk_fp8_f32 v70, v232, v40
	v_cvt_pk_fp8_f32 v45, v226, v34
	v_cvt_pk_fp8_f32 v71, v234, v42
	v_mul_f32_e32 v225, v225, v143
	v_mul_f32_e32 v233, v233, v210
	v_mul_f32_e32 v33, v33, v143
	v_mul_f32_e32 v41, v41, v210
	v_mul_f32_e32 v227, v227, v143
	v_mul_f32_e32 v235, v235, v210
	v_mul_f32_e32 v35, v35, v143
	v_mul_f32_e32 v43, v43, v210
	v_mul_f32_e32 v225, v214, v225
	v_mul_f32_e32 v233, v214, v233
	v_mul_f32_e32 v33, v215, v33
	v_mul_f32_e32 v41, v215, v41
	v_mul_f32_e32 v227, v218, v227
	v_mul_f32_e32 v235, v218, v235
	v_mul_f32_e32 v35, v219, v35
	v_mul_f32_e32 v43, v219, v43
	v_mul_f32_e32 v225, v225, v229
	v_mul_f32_e32 v233, v233, v237
	v_mul_f32_e32 v33, v33, v37
	v_mul_f32_e32 v41, v41, v49
	v_mul_f32_e32 v227, v227, v231
	v_mul_f32_e32 v235, v235, v239
	v_mul_f32_e32 v35, v35, v39
	v_mul_f32_e32 v43, v43, v51
	v_mul_f32_e32 v225, 0x41000000, v225
	v_mul_f32_e32 v233, 0x41000000, v233
	v_mul_f32_e32 v33, 0x41000000, v33
	v_mul_f32_e32 v41, 0x41000000, v41
	v_mul_f32_e32 v227, 0x41000000, v227
	v_mul_f32_e32 v235, 0x41000000, v235
	v_mul_f32_e32 v35, 0x41000000, v35
	v_mul_f32_e32 v43, 0x41000000, v43
	v_med3_f32 v225, v225, s20, v12
	v_med3_f32 v233, v233, s20, v12
	v_med3_f32 v33, v33, s20, v12
	v_med3_f32 v41, v41, s20, v12
	v_med3_f32 v227, v227, s20, v12
	v_med3_f32 v235, v235, s20, v12
	v_med3_f32 v35, v35, s20, v12
	v_med3_f32 v43, v43, s20, v12
	v_cvt_pk_fp8_f32 v44, v225, v33 op_sel:[0,0,1]
	v_cvt_pk_fp8_f32 v70, v233, v41 op_sel:[0,0,1]
	v_cvt_pk_fp8_f32 v45, v227, v35 op_sel:[0,0,1]
	v_cvt_pk_fp8_f32 v71, v235, v43 op_sel:[0,0,1]
	s_add_i32 s10, s10, s16
	s_add_i32 s10, s10, s16
	global_store_dwordx2 v15, v[44:45], s[46:47]
	global_store_dwordx2 v15, v[70:71], s[50:51]
	s_min_u32 s0, s1, 0x11fff
	s_lshr_b32 s0, s0, 3
	s_lshl_b32 s0, s0, 13
	s_add_u32 s32, s4, s0
	s_addc_u32 s33, s5, 0
	s_add_u32 s40, s6, s0
	s_addc_u32 s41, s7, 0
	global_load_dwordx4 v[32:35], v13, s[32:33]
	global_load_dwordx4 v[36:39], v13, s[40:41]
	s_add_i32 s1, s1, s16
	s_min_u32 s0, s1, 0x11fff
	s_lshr_b32 s0, s0, 3
	s_lshl_b32 s0, s0, 13
	s_add_u32 s32, s4, s0
	s_addc_u32 s33, s5, 0
	s_add_u32 s40, s6, s0
	s_addc_u32 s41, s7, 0
	global_load_dwordx4 v[40:43], v13, s[32:33]
	global_load_dwordx4 v[48:51], v13, s[40:41]
	s_add_i32 s1, s1, s16
	s_cmp_lt_i32 s10, 0x12000
	s_cbranch_scc0 .Lp4_done
; __device__ __forceinline__ void p4_gn_gate(Frame& F) {
;     ...
;     for (int t = gw; t < M * NH; t += NGW) {
;         const int r = t >> 3, h = t & 7; const size_t off = (size_t)r * HV + h * DV + 8 * F.lane;
;         const u32x4 ov = *(const u32x4*)(O + off), gv = *(const u32x4*)(G + off);
;         float o[8], g[8];
; #pragma unroll
;         for (int i = 0; i < 4; ++i) { o[2 * i] = __uint_as_float(ov[i] << 16); o[2 * i + 1] = __uint_as_float(ov[i] & 0xffff0000u); g[2 * i] = __uint_as_float(gv[i] << 16); g[2 * i + 1] = __uint_as_float(gv[i] & 0xffff0000u); }
;         float s = 0.f;
; #pragma unroll
;         for (int i = 0; i < 8; ++i) s += o[i];
;         const float mu = wave_sum(s) * (1.0f / DV); float q = 0.f;
; #pragma unroll
;         for (int i = 0; i < 8; ++i) { o[i] -= mu; q += o[i] * o[i]; }
;         const float rstd = 1.0f / sqrtf(wave_sum(q) * (1.0f / DV) + 1e-6f);
	s_min_u32 s0, s10, 0x11fff
	s_lshr_b32 s0, s0, 3
	s_lshl_b32 s0, s0, 12
	s_add_u32 s46, s8, s0
	s_addc_u32 s47, s9, 0
	s_add_i32 s14, s10, s16
	s_min_u32 s14, s14, 0x11fff
	s_lshr_b32 s14, s14, 3
	s_lshl_b32 s14, s14, 12
	s_add_u32 s50, s8, s14
	s_addc_u32 s51, s9, 0
	s_waitcnt vmcnt(12)
	v_lshlrev_b32_e32 v224, 16, v52
	v_lshlrev_b32_e32 v232, 16, v60
	v_and_b32_e32 v52, 0xffff0000, v52
	v_and_b32_e32 v60, 0xffff0000, v60
	v_add_f32_e32 v143, 0, v224
	v_add_f32_e32 v210, 0, v232
	v_lshlrev_b32_e32 v225, 16, v53
	v_lshlrev_b32_e32 v233, 16, v61
	v_add_f32_e32 v143, v143, v52
	v_add_f32_e32 v210, v210, v60
	v_and_b32_e32 v53, 0xffff0000, v53
	v_and_b32_e32 v61, 0xffff0000, v61
	v_add_f32_e32 v143, v143, v225
	v_add_f32_e32 v210, v210, v233
	v_lshlrev_b32_e32 v226, 16, v54
	v_lshlrev_b32_e32 v234, 16, v62
	v_add_f32_e32 v143, v143, v53
	v_add_f32_e32 v210, v210, v61
	v_and_b32_e32 v54, 0xffff0000, v54
	v_and_b32_e32 v62, 0xffff0000, v62
	v_add_f32_e32 v143, v143, v226
	v_add_f32_e32 v210, v210, v234
	v_lshlrev_b32_e32 v227, 16, v55
	v_lshlrev_b32_e32 v235, 16, v63
	v_add_f32_e32 v143, v143, v54
	v_add_f32_e32 v210, v210, v62
	v_and_b32_e32 v55, 0xffff0000, v55
	v_and_b32_e32 v63, 0xffff0000, v63
	v_add_f32_e32 v143, v143, v227
	v_add_f32_e32 v210, v210, v235
	v_add_f32_e32 v143, v143, v55
	v_add_f32_e32 v210, v210, v63
	ds_bpermute_b32 v153, v1, v143
	ds_bpermute_b32 v211, v1, v210
	v_lshlrev_b32_e32 v228, 16, v56
	v_lshlrev_b32_e32 v236, 16, v64
	v_and_b32_e32 v56, 0xffff0000, v56
	s_waitcnt lgkmcnt(1)
	v_add_f32_e32 v143, v143, v153
	s_waitcnt lgkmcnt(0)
	v_add_f32_e32 v210, v210, v211
	ds_bpermute_b32 v153, v3, v143
	ds_bpermute_b32 v211, v3, v210
	v_and_b32_e32 v64, 0xffff0000, v64
	v_lshlrev_b32_e32 v229, 16, v57
	v_lshlrev_b32_e32 v237, 16, v65
	s_waitcnt lgkmcnt(1)
	v_add_f32_e32 v143, v143, v153
	s_waitcnt lgkmcnt(0)
	v_add_f32_e32 v210, v210, v211
	ds_bpermute_b32 v153, v6, v143
	ds_bpermute_b32 v211, v6, v210
	v_and_b32_e32 v57, 0xffff0000, v57
	v_and_b32_e32 v65, 0xffff0000, v65
	v_lshlrev_b32_e32 v230, 16, v58
	s_waitcnt lgkmcnt(1)
	v_add_f32_e32 v143, v143, v153
	s_waitcnt lgkmcnt(0)
	v_add_f32_e32 v210, v210, v211
	ds_bpermute_b32 v153, v7, v143
	ds_bpermute_b32 v211, v7, v210
	v_lshlrev_b32_e32 v238, 16, v66
	v_and_b32_e32 v58, 0xffff0000, v58
	v_and_b32_e32 v66, 0xffff0000, v66
	s_waitcnt lgkmcnt(1)
	v_add_f32_e32 v143, v143, v153
	s_waitcnt lgkmcnt(0)
	v_add_f32_e32 v210, v210, v211
	ds_bpermute_b32 v153, v8, v143
	ds_bpermute_b32 v211, v8, v210
	v_lshlrev_b32_e32 v231, 16, v59
	v_lshlrev_b32_e32 v239, 16, v67
	v_and_b32_e32 v59, 0xffff0000, v59
	s_waitcnt lgkmcnt(1)
	v_add_f32_e32 v143, v143, v153
	s_waitcnt lgkmcnt(0)
	v_add_f32_e32 v210, v210, v211
	ds_bpermute_b32 v153, v9, v143
	ds_bpermute_b32 v211, v9, v210
	v_and_b32_e32 v67, 0xffff0000, v67
	s_waitcnt lgkmcnt(1)
	v_add_f32_e32 v143, v143, v153
	s_waitcnt lgkmcnt(0)
	v_add_f32_e32 v210, v210, v211
	v_fmac_f32_e32 v52, 0xbb000000, v143
	v_fmac_f32_e32 v60, 0xbb000000, v210
	v_fmac_f32_e32 v224, 0xbb000000, v143
	v_fmac_f32_e32 v232, 0xbb000000, v210
	v_fmac_f32_e32 v225, 0xbb000000, v143
	v_fmac_f32_e32 v233, 0xbb000000, v210
	v_fmac_f32_e32 v53, 0xbb000000, v143
	v_fmac_f32_e32 v61, 0xbb000000, v210
	v_fmac_f32_e32 v226, 0xbb000000, v143
	v_fmac_f32_e32 v234, 0xbb000000, v210
	v_fmac_f32_e32 v54, 0xbb000000, v143
	v_fmac_f32_e32 v62, 0xbb000000, v210
	v_fmac_f32_e32 v227, 0xbb000000, v143
	v_fmac_f32_e32 v235, 0xbb000000, v210
	v_fmac_f32_e32 v55, 0xbb000000, v143
	v_fmac_f32_e32 v63, 0xbb000000, v210
	v_mul_f32_e32 v143, v52, v52
	v_mul_f32_e32 v210, v60, v60
	v_fmac_f32_e32 v143, v224, v224
	v_fmac_f32_e32 v210, v232, v232
	v_fmac_f32_e32 v143, v225, v225
	v_fmac_f32_e32 v210, v233, v233
	v_fmac_f32_e32 v143, v53, v53
	v_fmac_f32_e32 v210, v61, v61
	v_fmac_f32_e32 v143, v226, v226
	v_fmac_f32_e32 v210, v234, v234
	v_fmac_f32_e32 v143, v54, v54
	v_fmac_f32_e32 v210, v62, v62
	v_fmac_f32_e32 v143, v227, v227
	v_fmac_f32_e32 v210, v235, v235
	v_fmac_f32_e32 v143, v55, v55
	v_fmac_f32_e32 v210, v63, v63
	ds_bpermute_b32 v153, v1, v143
	ds_bpermute_b32 v211, v1, v210
	s_waitcnt lgkmcnt(1)
	v_add_f32_e32 v143, v143, v153
	s_waitcnt lgkmcnt(0)
	v_add_f32_e32 v210, v210, v211
	ds_bpermute_b32 v153, v3, v143
	ds_bpermute_b32 v211, v3, v210
	s_waitcnt lgkmcnt(1)
	v_add_f32_e32 v143, v143, v153
	s_waitcnt lgkmcnt(0)
	v_add_f32_e32 v210, v210, v211
	ds_bpermute_b32 v153, v6, v143
	ds_bpermute_b32 v211, v6, v210
	s_waitcnt lgkmcnt(1)
	v_add_f32_e32 v143, v143, v153
	s_waitcnt lgkmcnt(0)
	v_add_f32_e32 v210, v210, v211
	ds_bpermute_b32 v153, v7, v143
	ds_bpermute_b32 v211, v7, v210
	s_waitcnt lgkmcnt(1)
	v_add_f32_e32 v143, v143, v153
	s_waitcnt lgkmcnt(0)
	v_add_f32_e32 v210, v210, v211
	ds_bpermute_b32 v153, v8, v143
	ds_bpermute_b32 v211, v8, v210
	s_waitcnt lgkmcnt(1)
	v_add_f32_e32 v143, v143, v153
	s_waitcnt lgkmcnt(0)
	v_add_f32_e32 v210, v210, v211
	ds_bpermute_b32 v153, v9, v143
	ds_bpermute_b32 v211, v9, v210
	s_waitcnt lgkmcnt(1)
	v_add_f32_e32 v143, v143, v153
	s_waitcnt lgkmcnt(0)
; __device__ __forceinline__ unsigned pk2(float lo, float hi) { unsigned r; asm("v_cvt_pk_bf16_f32 %0, %1, %2" : "=v"(r) : "v"(lo), "v"(hi)); return r; }
; __device__ __forceinline__ void p4_gn_gate(Frame& F) {
;     ...
;         const float rstd = 1.0f / sqrtf(wave_sum(q) * (1.0f / DV) + 1e-6f);
;         const f32x4 w0 = *(const f32x4*)(F.ret_gn_g + h * DV + 8 * F.lane), w1 = *(const f32x4*)(F.ret_gn_g + h * DV + 8 * F.lane + 4);
;         float y[8];
; #pragma unroll
;         for (int i = 0; i < 4; ++i) { y[i] = g[i] * (o[i] * rstd * w0[i]); y[i + 4] = g[i + 4] * (o[i + 4] * rstd * w1[i]); }
;         if (FP8O) { u32x2 out; out.x = pk4_fp8(y[0] * S_A2, y[1] * S_A2, y[2] * S_A2, y[3] * S_A2); out.y = pk4_fp8(y[4] * S_A2, y[5] * S_A2, y[6] * S_A2, y[7] * S_A2); *(u32x2*)((unsigned char*)A2 + off) = out; }
;         else { u32x4 out; out.x = pk2(y[0], y[1]); out.y = pk2(y[2], y[3]); out.z = pk2(y[4], y[5]); out.w = pk2(y[6], y[7]); *(u32x4*)(A2 + off) = out; }
;     }
	v_add_f32_e32 v210, v210, v211
	v_fmamk_f32 v143, v143, 0x3b000000, v10
	v_mul_f32_e32 v153, 0x4f800000, v143
	v_cmp_gt_f32_e32 vcc, s19, v143
	s_nop 1
	v_cndmask_b32_e32 v143, v143, v153, vcc
	v_sqrt_f32_e32 v153, v143
	s_nop 0
	v_add_u32_e32 v155, -1, v153
	v_add_u32_e32 v159, 1, v153
	v_fma_f32 v221, -v155, v153, v143
	v_fma_f32 v46, -v159, v153, v143
	v_cmp_ge_f32_e64 s[56:57], 0, v221
	s_nop 1
	v_cndmask_b32_e64 v153, v153, v155, s[56:57]
	v_cmp_lt_f32_e64 s[56:57], 0, v46
	s_nop 1
	v_cndmask_b32_e64 v153, v153, v159, s[56:57]
	v_mul_f32_e32 v155, 0x37800000, v153
	v_cndmask_b32_e32 v153, v153, v155, vcc
	v_cmp_class_f32_e32 vcc, v143, v11
	s_nop 1
	v_cndmask_b32_e32 v143, v153, v143, vcc
	v_div_scale_f32 v153, s[56:57], v143, v143, 1.0
	v_rcp_f32_e32 v159, v153
	v_div_scale_f32 v155, vcc, 1.0, v143, 1.0
	v_fma_f32 v221, -v153, v159, 1.0
	v_fmac_f32_e32 v159, v221, v159
	v_mul_f32_e32 v221, v155, v159
	v_fma_f32 v46, -v153, v221, v155
	v_fmac_f32_e32 v221, v46, v159
	v_fma_f32 v153, -v153, v221, v155
	v_div_fmas_f32 v153, v153, v159, v221
	v_div_fixup_f32 v143, v153, v143, 1.0
	v_fmamk_f32 v210, v210, 0x3b000000, v10
	v_mul_f32_e32 v211, 0x4f800000, v210
	v_cmp_gt_f32_e32 vcc, s19, v210
	s_nop 1
	v_cndmask_b32_e32 v210, v210, v211, vcc
	v_sqrt_f32_e32 v211, v210
	s_nop 0
	v_add_u32_e32 v192, -1, v211
	v_add_u32_e32 v193, 1, v211
	v_fma_f32 v222, -v192, v211, v210
	v_fma_f32 v223, -v193, v211, v210
	v_cmp_ge_f32_e64 s[58:59], 0, v222
	s_nop 1
	v_cndmask_b32_e64 v211, v211, v192, s[58:59]
	v_cmp_lt_f32_e64 s[58:59], 0, v223
	s_nop 1
	v_cndmask_b32_e64 v211, v211, v193, s[58:59]
	v_mul_f32_e32 v192, 0x37800000, v211
	v_cndmask_b32_e32 v211, v211, v192, vcc
	v_cmp_class_f32_e32 vcc, v210, v11
	s_nop 1
	v_cndmask_b32_e32 v210, v211, v210, vcc
	v_div_scale_f32 v211, s[58:59], v210, v210, 1.0
	v_rcp_f32_e32 v193, v211
	v_div_scale_f32 v192, vcc, 1.0, v210, 1.0
	v_fma_f32 v222, -v211, v193, 1.0
	v_fmac_f32_e32 v193, v222, v193
	v_mul_f32_e32 v222, v192, v193
	v_fma_f32 v223, -v211, v222, v192
	v_fmac_f32_e32 v222, v223, v193
	v_fma_f32 v211, -v211, v222, v192
	v_div_fmas_f32 v211, v211, v193, v222
	v_div_fixup_f32 v210, v211, v210, 1.0
	v_mul_f32_e32 v224, v224, v143
	v_mul_f32_e32 v232, v232, v210
	v_mul_f32_e32 v52, v52, v143
	v_mul_f32_e32 v60, v60, v210
	v_mul_f32_e32 v226, v226, v143
	v_mul_f32_e32 v234, v234, v210
	v_mul_f32_e32 v54, v54, v143
	v_mul_f32_e32 v62, v62, v210
	v_mul_f32_e32 v224, v212, v224
	v_mul_f32_e32 v232, v212, v232
	v_mul_f32_e32 v52, v213, v52
	v_mul_f32_e32 v60, v213, v60
	v_mul_f32_e32 v226, v216, v226
	v_mul_f32_e32 v234, v216, v234
	v_mul_f32_e32 v54, v217, v54
	v_mul_f32_e32 v62, v217, v62
	v_mul_f32_e32 v224, v224, v228
	v_mul_f32_e32 v232, v232, v236
	v_mul_f32_e32 v52, v52, v56
	v_mul_f32_e32 v60, v60, v64
	v_mul_f32_e32 v226, v226, v230
	v_mul_f32_e32 v234, v234, v238
	v_mul_f32_e32 v54, v54, v58
	v_mul_f32_e32 v62, v62, v66
	v_mul_f32_e32 v224, 0x41000000, v224
	v_mul_f32_e32 v232, 0x41000000, v232
	v_mul_f32_e32 v52, 0x41000000, v52
	v_mul_f32_e32 v60, 0x41000000, v60
	v_mul_f32_e32 v226, 0x41000000, v226
	v_mul_f32_e32 v234, 0x41000000, v234
	v_mul_f32_e32 v54, 0x41000000, v54
	v_mul_f32_e32 v62, 0x41000000, v62
	v_med3_f32 v224, v224, s20, v12
	v_med3_f32 v232, v232, s20, v12
	v_med3_f32 v52, v52, s20, v12
	v_med3_f32 v60, v60, s20, v12
	v_med3_f32 v226, v226, s20, v12
	v_med3_f32 v234, v234, s20, v12
	v_med3_f32 v54, v54, s20, v12
	v_med3_f32 v62, v62, s20, v12
	v_cvt_pk_fp8_f32 v44, v224, v52
	v_cvt_pk_fp8_f32 v70, v232, v60
	v_cvt_pk_fp8_f32 v45, v226, v54
	v_cvt_pk_fp8_f32 v71, v234, v62
	v_mul_f32_e32 v225, v225, v143
	v_mul_f32_e32 v233, v233, v210
	v_mul_f32_e32 v53, v53, v143
	v_mul_f32_e32 v61, v61, v210
	v_mul_f32_e32 v227, v227, v143
	v_mul_f32_e32 v235, v235, v210
	v_mul_f32_e32 v55, v55, v143
	v_mul_f32_e32 v63, v63, v210
	v_mul_f32_e32 v225, v214, v225
	v_mul_f32_e32 v233, v214, v233
	v_mul_f32_e32 v53, v215, v53
	v_mul_f32_e32 v61, v215, v61
	v_mul_f32_e32 v227, v218, v227
	v_mul_f32_e32 v235, v218, v235
	v_mul_f32_e32 v55, v219, v55
	v_mul_f32_e32 v63, v219, v63
	v_mul_f32_e32 v225, v225, v229
	v_mul_f32_e32 v233, v233, v237
	v_mul_f32_e32 v53, v53, v57
	v_mul_f32_e32 v61, v61, v65
	v_mul_f32_e32 v227, v227, v231
	v_mul_f32_e32 v235, v235, v239
	v_mul_f32_e32 v55, v55, v59
	v_mul_f32_e32 v63, v63, v67
	v_mul_f32_e32 v225, 0x41000000, v225
	v_mul_f32_e32 v233, 0x41000000, v233
	v_mul_f32_e32 v53, 0x41000000, v53
	v_mul_f32_e32 v61, 0x41000000, v61
	v_mul_f32_e32 v227, 0x41000000, v227
	v_mul_f32_e32 v235, 0x41000000, v235
	v_mul_f32_e32 v55, 0x41000000, v55
	v_mul_f32_e32 v63, 0x41000000, v63
	v_med3_f32 v225, v225, s20, v12
	v_med3_f32 v233, v233, s20, v12
	v_med3_f32 v53, v53, s20, v12
	v_med3_f32 v61, v61, s20, v12
	v_med3_f32 v227, v227, s20, v12
	v_med3_f32 v235, v235, s20, v12
	v_med3_f32 v55, v55, s20, v12
	v_med3_f32 v63, v63, s20, v12
	v_cvt_pk_fp8_f32 v44, v225, v53 op_sel:[0,0,1]
	v_cvt_pk_fp8_f32 v70, v233, v61 op_sel:[0,0,1]
	v_cvt_pk_fp8_f32 v45, v227, v55 op_sel:[0,0,1]
	v_cvt_pk_fp8_f32 v71, v235, v63 op_sel:[0,0,1]
	s_add_i32 s10, s10, s16
	s_add_i32 s10, s10, s16
	global_store_dwordx2 v15, v[44:45], s[46:47]
	global_store_dwordx2 v15, v[70:71], s[50:51]
	s_min_u32 s0, s1, 0x11fff
	s_lshr_b32 s0, s0, 3
	s_lshl_b32 s0, s0, 13
	s_add_u32 s32, s4, s0
	s_addc_u32 s33, s5, 0
	s_add_u32 s40, s6, s0
	s_addc_u32 s41, s7, 0
	global_load_dwordx4 v[52:55], v13, s[32:33]
	global_load_dwordx4 v[56:59], v13, s[40:41]
	s_add_i32 s1, s1, s16
	s_min_u32 s0, s1, 0x11fff
	s_lshr_b32 s0, s0, 3
	s_lshl_b32 s0, s0, 13
	s_add_u32 s32, s4, s0
	s_addc_u32 s33, s5, 0
	s_add_u32 s40, s6, s0
	s_addc_u32 s41, s7, 0
	global_load_dwordx4 v[60:63], v13, s[32:33]
	global_load_dwordx4 v[64:67], v13, s[40:41]
	s_add_i32 s1, s1, s16
	s_branch .Lp4_loop
	s_nop 0
	s_nop 0
	s_nop 0
	s_nop 0
	s_nop 0
	s_nop 0
	s_nop 0
	s_nop 0
	s_nop 0
	s_nop 0
	s_nop 0
	s_nop 0
	s_nop 0
	s_nop 0
	s_nop 0
	s_nop 0
	s_nop 0
	s_nop 0
	s_nop 0
	s_nop 0
	s_nop 0
	s_nop 0
	s_nop 0
	s_nop 0
	s_nop 0

;     __device__ __forceinline__ void operator()(const f32x4 (&acc)[2][2][4][2], const Unit& u, int wr, int wc, int fr, int fq) const {
;         const int row0 = u.pm * BM + wr * 64 + fr, col0 = u.pn * BM + wc * 32 + 8 * fq;
;         if (u.part >= 0) {
;             bf16* sp = slab + ((ptrdiff_t)u.part * mk::MS - mk::MP) * (ptrdiff_t)mk::D + col0;
; #pragma unroll
;             for (int ai = 0; ai < 2; ++ai)
; #pragma unroll
;                 for (int m = 0; m < 4; ++m) { bf16* rowp = sp + (ptrdiff_t)(row0 + ai * HALF + m * 16) * mk::D;
; #pragma unroll
;                     for (int bj = 0; bj < 2; ++bj) { const f32x4 v0 = acc[ai][bj][m][0] * ascale, v1 = acc[ai][bj][m][1] * ascale;
;                         u32x4 w; w.x = mk::pk2(v0[0], v0[1]); w.y = mk::pk2(v0[2], v0[3]); w.z = mk::pk2(v1[0], v1[1]); w.w = mk::pk2(v1[2], v1[3]); *(u32x4*)(rowp + bj * HALF) = w; } }
;             return;
;         }
; #pragma unroll
;         for (int ai = 0; ai < 2; ++ai)
; #pragma unroll
;             for (int m = 0; m < 4; ++m) { const int r = row0 + ai * HALF + m * 16; const size_t off = (size_t)r * mk::D + col0; const float* gp = gate + (size_t)mk::seq_of(r) * mk::NMOD + col0;
;                 float ss = 0.f;
; #pragma unroll
;                 for (int bj = 0; bj < 2; ++bj) { const int o = bj * HALF;
;                     f32x4 x0, x1;
;                     if constexpr (XIF32) { x0 = *(const f32x4*)((const float*)xi + off + o); x1 = *(const f32x4*)((const float*)xi + off + o + 4); }
;                     else { const u32x4 w = *(const u32x4*)((const bf16*)xi + off + o);
;                         x0 = (f32x4){__uint_as_float(w.x << 16), __uint_as_float(w.x & 0xffff0000u), __uint_as_float(w.y << 16), __uint_as_float(w.y & 0xffff0000u)};
;                         x1 = (f32x4){__uint_as_float(w.z << 16), __uint_as_float(w.z & 0xffff0000u), __uint_as_float(w.w << 16), __uint_as_float(w.w & 0xffff0000u)}; }
;                     f32x4 v0 = acc[ai][bj][m][0] * ascale, v1 = acc[ai][bj][m][1] * ascale;
;                     if constexpr (MODE == 1) { v0 *= *(const f32x4*)(extra + col0 + o); v1 *= *(const f32x4*)(extra + col0 + o + 4); }
;                     const f32x4 y0 = x0 + *(const f32x4*)(gp + o) * v0, y1 = x1 + *(const f32x4*)(gp + o + 4) * v1;
.LBB0_807:
	s_lshl_b32 s10, s68, 8
	s_add_i32 s10, s10, s82
	s_nop 15
	s_nop 15
	v_or_b32_e32 v8, s10, v1
	v_lshl_or_b32 v10, s69, 8, v183
	v_or_b32_e32 v6, 16, v8
	v_or_b32_e32 v4, 32, v8
	v_or_b32_e32 v2, 48, v8
	s_mov_b64 s[60:61], -1
	s_cmp_gt_i32 s4, -1
	v_ashrrev_i32_e32 v11, 31, v10
	v_ashrrev_i32_e32 v9, 31, v8
	v_ashrrev_i32_e32 v7, 31, v6
	v_ashrrev_i32_e32 v5, 31, v4
	v_ashrrev_i32_e32 v3, 31, v2
	s_cbranch_scc1 .LBB0_810
	v_readlane_b32 s40, v240, 27
	v_readlane_b32 s41, v240, 28
	v_lshl_add_u32 v12, v8, 11, v10
	v_lshlrev_b32_e32 v12, 2, v12
	s_nop 3
	global_load_dword v30, v12, s[40:41]
	global_load_dword v30, v12, s[40:41] offset:512
	v_add_u32_e32 v13, 0x20000, v12
	global_load_dword v30, v13, s[40:41]
	global_load_dword v30, v13, s[40:41] offset:512
	v_add_u32_e32 v13, 0x40000, v12
	global_load_dword v30, v13, s[40:41]
	global_load_dword v30, v13, s[40:41] offset:512
	v_add_u32_e32 v13, 0x60000, v12
	global_load_dword v30, v13, s[40:41]
	global_load_dword v30, v13, s[40:41] offset:512
	v_add_u32_e32 v13, 0x100000, v12
	global_load_dword v30, v13, s[40:41]
	global_load_dword v30, v13, s[40:41] offset:512
	v_add_u32_e32 v13, 0x120000, v12
	global_load_dword v30, v13, s[40:41]
	global_load_dword v30, v13, s[40:41] offset:512
	v_add_u32_e32 v13, 0x140000, v12
	global_load_dword v30, v13, s[40:41]
	global_load_dword v30, v13, s[40:41] offset:512
	v_add_u32_e32 v13, 0x160000, v12
	global_load_dword v30, v13, s[40:41]
	global_load_dword v30, v13, s[40:41] offset:512
	s_nop 0
	s_nop 0
	s_nop 0
	s_nop 0
	s_nop 0
	s_nop 0
	s_nop 0
	s_nop 0
	s_nop 0
	s_nop 0
	v_lshlrev_b64 v[12:13], 11, v[8:9]
	v_lshl_add_u64 v[16:17], v[12:13], 0, v[10:11]
	v_add_u32_e32 v12, 0xffffe000, v8
	s_ashr_i32 s10, s10, 11
	v_lshrrev_b32_e32 v12, 3, v12
	v_or_b32_e32 v12, 4, v12
	v_mov_b32_e32 v196, s10
	v_cmp_gt_i32_e32 vcc, s81, v8
	v_pk_mul_f32 v[178:179], v[160:161], s[36:37] op_sel_hi:[1,0]
	v_pk_mul_f32 v[180:181], v[158:159], s[36:37] op_sel_hi:[1,0]
	v_cndmask_b32_e32 v14, v12, v196, vcc
	v_mov_b64_e32 v[12:13], s[16:17]
	v_mad_i64_i32 v[18:19], s[52:53], v14, s87, v[12:13]
	v_lshlrev_b64 v[14:15], 2, v[10:11]
	v_readlane_b32 s40, v240, 27
	v_lshl_add_u64 v[174:175], v[18:19], 0, v[14:15]
	v_readlane_b32 s41, v240, 28
	v_pk_mul_f32 v[188:189], v[156:157], s[36:37] op_sel_hi:[1,0]
	v_pk_mul_f32 v[190:191], v[154:155], s[36:37] op_sel_hi:[1,0]
	v_lshl_add_u64 v[176:177], v[16:17], 2, s[40:41]
	global_load_dwordx4 v[18:21], v[174:175], off
	global_load_dwordx4 v[22:25], v[176:177], off
	global_load_dwordx4 v[26:29], v[176:177], off offset:16
	global_load_dwordx4 v[30:33], v[174:175], off offset:16
	v_lshl_add_u64 v[192:193], v[16:17], 1, s[8:9]
	v_cmp_gt_i32_e32 vcc, s81, v6
	v_readlane_b32 s52, v240, 39
	v_readlane_b32 s53, v240, 40
	s_movk_i32 s10, 0x1f80
	v_readlane_b32 s44, v240, 31
	v_readlane_b32 s45, v240, 32
	v_readlane_b32 s44, v240, 44
	v_readlane_b32 s42, v240, 29
	v_readlane_b32 s43, v240, 30
	v_readlane_b32 s46, v240, 33
	v_readlane_b32 s47, v240, 34
	v_readlane_b32 s48, v240, 35
	v_readlane_b32 s49, v240, 36
	v_readlane_b32 s50, v240, 37
	v_readlane_b32 s51, v240, 38
	v_readlane_b32 s54, v240, 41
	v_readlane_b32 s55, v240, 42
	v_readlane_b32 s45, v240, 45
	s_waitcnt vmcnt(0)
	v_pk_fma_f32 v[20:21], v[178:179], v[20:21], v[24:25]
	v_pk_fma_f32 v[18:19], v[180:181], v[18:19], v[22:23]
	v_pk_fma_f32 v[22:23], v[188:189], v[32:33], v[28:29]
	v_pk_fma_f32 v[24:25], v[190:191], v[30:31], v[26:27]
	v_cvt_pk_bf16_f32 v18, v18, v19
	v_cvt_pk_bf16_f32 v19, v20, v21
	v_cvt_pk_bf16_f32 v21, v22, v23
	v_add_u32_e32 v190, 0xffffe010, v8
	v_cvt_pk_bf16_f32 v20, v24, v25
	global_store_dwordx4 v[192:193], v[18:21], off
	global_load_dwordx4 v[18:21], v[174:175], off offset:512
	s_nop 0
	global_load_dwordx4 v[22:25], v[176:177], off offset:512
	global_load_dwordx4 v[26:29], v[176:177], off offset:528
	global_load_dwordx4 v[30:33], v[174:175], off offset:528
	v_lshrrev_b32_e32 v190, 3, v190
	v_pk_mul_f32 v[174:175], v[152:153], s[36:37] op_sel_hi:[1,0]
	v_pk_mul_f32 v[176:177], v[150:151], s[36:37] op_sel_hi:[1,0]
	v_or_b32_e32 v194, 4, v190
	v_pk_mul_f32 v[178:179], v[144:145], s[36:37] op_sel_hi:[1,0]
	v_pk_mul_f32 v[180:181], v[142:143], s[36:37] op_sel_hi:[1,0]
	v_cndmask_b32_e32 v194, v194, v196, vcc
	v_lshlrev_b64 v[188:189], 11, v[6:7]
	v_mad_i64_i32 v[194:195], s[52:53], v194, s87, v[12:13]
	v_lshl_add_u64 v[188:189], v[188:189], 0, v[10:11]
	v_lshl_add_u64 v[194:195], v[194:195], 0, v[14:15]
	v_lshl_add_u64 v[190:191], v[188:189], 2, s[40:41]
	v_lshl_add_u64 v[188:189], v[188:189], 1, s[8:9]
	v_cmp_gt_i32_e32 vcc, s81, v4
	s_waitcnt vmcnt(2)
	v_pk_fma_f32 v[20:21], v[174:175], v[20:21], v[24:25]
	v_pk_fma_f32 v[18:19], v[176:177], v[18:19], v[22:23]
	s_waitcnt vmcnt(0)
	v_pk_fma_f32 v[22:23], v[178:179], v[32:33], v[28:29]
	v_pk_fma_f32 v[24:25], v[180:181], v[30:31], v[26:27]
	v_cvt_pk_bf16_f32 v18, v18, v19
	v_cvt_pk_bf16_f32 v19, v20, v21
	v_cvt_pk_bf16_f32 v21, v22, v23
	v_pk_mul_f32 v[174:175], v[148:149], s[36:37] op_sel_hi:[1,0]
	v_cvt_pk_bf16_f32 v20, v24, v25
	global_store_dwordx4 v[192:193], v[18:21], off offset:256
	global_load_dwordx4 v[18:21], v[194:195], off
	global_load_dwordx4 v[22:25], v[190:191], off
	global_load_dwordx4 v[26:29], v[190:191], off offset:16
	global_load_dwordx4 v[30:33], v[194:195], off offset:16
	v_pk_mul_f32 v[176:177], v[146:147], s[36:37] op_sel_hi:[1,0]
	v_pk_mul_f32 v[178:179], v[140:141], s[36:37] op_sel_hi:[1,0]
	v_pk_mul_f32 v[180:181], v[138:139], s[36:37] op_sel_hi:[1,0]
	v_add_u32_e32 v192, 0xffffe020, v8
	v_lshrrev_b32_e32 v192, 3, v192
	s_waitcnt vmcnt(2)
; __device__ __forceinline__ unsigned pk2(float lo, float hi) { unsigned r; asm("v_cvt_pk_bf16_f32 %0, %1, %2" : "=v"(r) : "v"(lo), "v"(hi)); return r; }
;     __device__ __forceinline__ void operator()(const f32x4 (&acc)[2][2][4][2], const Unit& u, int wr, int wc, int fr, int fq) const {
;     ...
;         for (int ai = 0; ai < 2; ++ai)
; #pragma unroll
;             for (int m = 0; m < 4; ++m) { const int r = row0 + ai * HALF + m * 16; const size_t off = (size_t)r * mk::D + col0; const float* gp = gate + (size_t)mk::seq_of(r) * mk::NMOD + col0;
;                 float ss = 0.f;
; #pragma unroll
;                 for (int bj = 0; bj < 2; ++bj) { const int o = bj * HALF;
;                     f32x4 x0, x1;
;                     if constexpr (XIF32) { x0 = *(const f32x4*)((const float*)xi + off + o); x1 = *(const f32x4*)((const float*)xi + off + o + 4); }
;                     else { const u32x4 w = *(const u32x4*)((const bf16*)xi + off + o);
;                         x0 = (f32x4){__uint_as_float(w.x << 16), __uint_as_float(w.x & 0xffff0000u), __uint_as_float(w.y << 16), __uint_as_float(w.y & 0xffff0000u)};
;                         x1 = (f32x4){__uint_as_float(w.z << 16), __uint_as_float(w.z & 0xffff0000u), __uint_as_float(w.w << 16), __uint_as_float(w.w & 0xffff0000u)}; }
;                     f32x4 v0 = acc[ai][bj][m][0] * ascale, v1 = acc[ai][bj][m][1] * ascale;
;                     if constexpr (MODE == 1) { v0 *= *(const f32x4*)(extra + col0 + o); v1 *= *(const f32x4*)(extra + col0 + o + 4); }
;                     const f32x4 y0 = x0 + *(const f32x4*)(gp + o) * v0, y1 = x1 + *(const f32x4*)(gp + o + 4) * v1;
;                     u32x4 w; w.x = mk::pk2(y0[0], y0[1]); w.y = mk::pk2(y0[2], y0[3]); w.z = mk::pk2(y1[0], y1[1]); w.w = mk::pk2(y1[2], y1[3]); *(u32x4*)(xo + off + o) = w;
	v_pk_fma_f32 v[20:21], v[174:175], v[20:21], v[24:25]
	v_pk_fma_f32 v[18:19], v[176:177], v[18:19], v[22:23]
	s_waitcnt vmcnt(0)
	v_pk_fma_f32 v[22:23], v[178:179], v[32:33], v[28:29]
	v_pk_fma_f32 v[24:25], v[180:181], v[30:31], v[26:27]
	v_cvt_pk_bf16_f32 v18, v18, v19
	v_cvt_pk_bf16_f32 v19, v20, v21
	v_cvt_pk_bf16_f32 v21, v22, v23
	v_pk_mul_f32 v[174:175], v[136:137], s[36:37] op_sel_hi:[1,0]
	v_cvt_pk_bf16_f32 v20, v24, v25
	global_store_dwordx4 v[188:189], v[18:21], off
	global_load_dwordx4 v[18:21], v[194:195], off offset:512
	s_nop 0
	global_load_dwordx4 v[22:25], v[190:191], off offset:512
	global_load_dwordx4 v[26:29], v[190:191], off offset:528
	global_load_dwordx4 v[30:33], v[194:195], off offset:528
	v_pk_mul_f32 v[176:177], v[134:135], s[36:37] op_sel_hi:[1,0]
	v_add_u32_e32 v194, 4, v192
	v_pk_mul_f32 v[178:179], v[128:129], s[36:37] op_sel_hi:[1,0]
	v_pk_mul_f32 v[180:181], v[126:127], s[36:37] op_sel_hi:[1,0]
	v_cndmask_b32_e32 v194, v194, v196, vcc
	v_lshlrev_b64 v[190:191], 11, v[4:5]
	v_mad_i64_i32 v[194:195], s[52:53], v194, s87, v[12:13]
	v_lshl_add_u64 v[190:191], v[190:191], 0, v[10:11]
	v_lshl_add_u64 v[194:195], v[194:195], 0, v[14:15]
	v_lshl_add_u64 v[192:193], v[190:191], 2, s[40:41]
	v_cmp_gt_i32_e32 vcc, s81, v2
	s_waitcnt vmcnt(2)
	v_pk_fma_f32 v[20:21], v[174:175], v[20:21], v[24:25]
	v_pk_fma_f32 v[18:19], v[176:177], v[18:19], v[22:23]
	s_waitcnt vmcnt(0)
	v_pk_fma_f32 v[22:23], v[178:179], v[32:33], v[28:29]
	v_pk_fma_f32 v[24:25], v[180:181], v[30:31], v[26:27]
	v_cvt_pk_bf16_f32 v18, v18, v19
	v_cvt_pk_bf16_f32 v19, v20, v21
	v_cvt_pk_bf16_f32 v21, v22, v23
	v_pk_mul_f32 v[174:175], v[132:133], s[36:37] op_sel_hi:[1,0]
	v_cvt_pk_bf16_f32 v20, v24, v25
	global_store_dwordx4 v[188:189], v[18:21], off offset:256
	global_load_dwordx4 v[18:21], v[194:195], off
	global_load_dwordx4 v[22:25], v[192:193], off
	global_load_dwordx4 v[26:29], v[192:193], off offset:16
	global_load_dwordx4 v[30:33], v[194:195], off offset:16
	v_pk_mul_f32 v[176:177], v[130:131], s[36:37] op_sel_hi:[1,0]
	v_pk_mul_f32 v[178:179], v[124:125], s[36:37] op_sel_hi:[1,0]
	v_pk_mul_f32 v[180:181], v[122:123], s[36:37] op_sel_hi:[1,0]
	v_lshl_add_u64 v[188:189], v[190:191], 1, s[8:9]
	v_lshlrev_b64 v[190:191], 11, v[2:3]
	v_lshl_add_u64 v[190:191], v[190:191], 0, v[10:11]
	s_waitcnt vmcnt(2)
	v_pk_fma_f32 v[20:21], v[174:175], v[20:21], v[24:25]
	v_pk_fma_f32 v[18:19], v[176:177], v[18:19], v[22:23]
	s_waitcnt vmcnt(0)
	v_pk_fma_f32 v[22:23], v[178:179], v[32:33], v[28:29]
	v_pk_fma_f32 v[24:25], v[180:181], v[30:31], v[26:27]
	v_cvt_pk_bf16_f32 v18, v18, v19
	v_cvt_pk_bf16_f32 v19, v20, v21
	v_cvt_pk_bf16_f32 v21, v22, v23
	v_pk_mul_f32 v[174:175], v[120:121], s[36:37] op_sel_hi:[1,0]
	v_cvt_pk_bf16_f32 v20, v24, v25
	global_store_dwordx4 v[188:189], v[18:21], off
	global_load_dwordx4 v[18:21], v[194:195], off offset:512
	s_nop 0
	global_load_dwordx4 v[22:25], v[192:193], off offset:512
	global_load_dwordx4 v[26:29], v[192:193], off offset:528
	global_load_dwordx4 v[30:33], v[194:195], off offset:528
	v_add_u32_e32 v192, 0xffffe030, v8
	v_lshrrev_b32_e32 v192, 3, v192
	v_pk_mul_f32 v[176:177], v[118:119], s[36:37] op_sel_hi:[1,0]
	v_add_u32_e32 v194, 4, v192
	v_pk_mul_f32 v[178:179], v[112:113], s[36:37] op_sel_hi:[1,0]
	v_pk_mul_f32 v[180:181], v[110:111], s[36:37] op_sel_hi:[1,0]
	v_cndmask_b32_e32 v194, v194, v196, vcc
	v_mad_i64_i32 v[194:195], s[52:53], v194, s87, v[12:13]
	v_lshl_add_u64 v[194:195], v[194:195], 0, v[14:15]
	v_lshl_add_u64 v[192:193], v[190:191], 2, s[40:41]
	v_cmp_gt_i32_e32 vcc, s10, v8
	s_movk_i32 s10, 0x1f70
	s_waitcnt vmcnt(2)
	v_pk_fma_f32 v[20:21], v[174:175], v[20:21], v[24:25]
	v_pk_fma_f32 v[18:19], v[176:177], v[18:19], v[22:23]
	s_waitcnt vmcnt(0)
	v_pk_fma_f32 v[22:23], v[178:179], v[32:33], v[28:29]
	v_pk_fma_f32 v[24:25], v[180:181], v[30:31], v[26:27]
	v_cvt_pk_bf16_f32 v18, v18, v19
	v_cvt_pk_bf16_f32 v19, v20, v21
	v_cvt_pk_bf16_f32 v21, v22, v23
	v_pk_mul_f32 v[174:175], v[116:117], s[36:37] op_sel_hi:[1,0]
	v_cvt_pk_bf16_f32 v20, v24, v25
	global_store_dwordx4 v[188:189], v[18:21], off offset:256
	global_load_dwordx4 v[18:21], v[194:195], off
	global_load_dwordx4 v[22:25], v[192:193], off
	global_load_dwordx4 v[26:29], v[192:193], off offset:16
	global_load_dwordx4 v[30:33], v[194:195], off offset:16
	v_pk_mul_f32 v[176:177], v[114:115], s[36:37] op_sel_hi:[1,0]
	v_pk_mul_f32 v[178:179], v[108:109], s[36:37] op_sel_hi:[1,0]
	v_pk_mul_f32 v[180:181], v[106:107], s[36:37] op_sel_hi:[1,0]
	v_lshl_add_u64 v[188:189], v[190:191], 1, s[8:9]
	v_add_u32_e32 v190, 0x80, v8
	v_ashrrev_i32_e32 v196, 11, v190
	v_ashrrev_i32_e32 v191, 31, v190
	v_lshlrev_b64 v[190:191], 11, v[190:191]
	v_lshl_add_u64 v[190:191], v[190:191], 0, v[10:11]
	s_waitcnt vmcnt(2)
	v_pk_fma_f32 v[20:21], v[174:175], v[20:21], v[24:25]
	v_pk_fma_f32 v[18:19], v[176:177], v[18:19], v[22:23]
	s_waitcnt vmcnt(0)
	v_pk_fma_f32 v[22:23], v[178:179], v[32:33], v[28:29]
	v_pk_fma_f32 v[24:25], v[180:181], v[30:31], v[26:27]
	v_cvt_pk_bf16_f32 v18, v18, v19
	v_cvt_pk_bf16_f32 v19, v20, v21
	v_cvt_pk_bf16_f32 v21, v22, v23
	v_pk_mul_f32 v[174:175], v[104:105], s[36:37] op_sel_hi:[1,0]
	v_cvt_pk_bf16_f32 v20, v24, v25
	global_store_dwordx4 v[188:189], v[18:21], off
	global_load_dwordx4 v[18:21], v[194:195], off offset:512
	s_nop 0
	global_load_dwordx4 v[22:25], v[192:193], off offset:512
	global_load_dwordx4 v[26:29], v[192:193], off offset:528
	global_load_dwordx4 v[30:33], v[194:195], off offset:528
	v_add_u32_e32 v192, 0xffffe080, v8
	v_lshrrev_b32_e32 v192, 3, v192
	v_pk_mul_f32 v[176:177], v[102:103], s[36:37] op_sel_hi:[1,0]
	v_or_b32_e32 v192, 4, v192
	v_pk_mul_f32 v[178:179], v[100:101], s[36:37] op_sel_hi:[1,0]
	v_pk_mul_f32 v[180:181], v[98:99], s[36:37] op_sel_hi:[1,0]
	v_cndmask_b32_e32 v192, v192, v196, vcc
	v_mad_i64_i32 v[192:193], s[52:53], v192, s87, v[12:13]
	v_lshl_add_u64 v[192:193], v[192:193], 0, v[14:15]
	v_lshl_add_u64 v[194:195], v[190:191], 2, s[40:41]
	v_cmp_gt_i32_e32 vcc, s10, v8
	s_mov_b64 s[52:53], 0x48000
	s_movk_i32 s10, 0x1f60
	s_waitcnt vmcnt(2)
; __device__ __forceinline__ unsigned pk2(float lo, float hi) { unsigned r; asm("v_cvt_pk_bf16_f32 %0, %1, %2" : "=v"(r) : "v"(lo), "v"(hi)); return r; }
;     __device__ __forceinline__ void operator()(const f32x4 (&acc)[2][2][4][2], const Unit& u, int wr, int wc, int fr, int fq) const {
;     ...
;         for (int ai = 0; ai < 2; ++ai)
; #pragma unroll
;             for (int m = 0; m < 4; ++m) { const int r = row0 + ai * HALF + m * 16; const size_t off = (size_t)r * mk::D + col0; const float* gp = gate + (size_t)mk::seq_of(r) * mk::NMOD + col0;
;                 float ss = 0.f;
; #pragma unroll
;                 for (int bj = 0; bj < 2; ++bj) { const int o = bj * HALF;
;                     f32x4 x0, x1;
;                     if constexpr (XIF32) { x0 = *(const f32x4*)((const float*)xi + off + o); x1 = *(const f32x4*)((const float*)xi + off + o + 4); }
;                     else { const u32x4 w = *(const u32x4*)((const bf16*)xi + off + o);
;                         x0 = (f32x4){__uint_as_float(w.x << 16), __uint_as_float(w.x & 0xffff0000u), __uint_as_float(w.y << 16), __uint_as_float(w.y & 0xffff0000u)};
;                         x1 = (f32x4){__uint_as_float(w.z << 16), __uint_as_float(w.z & 0xffff0000u), __uint_as_float(w.w << 16), __uint_as_float(w.w & 0xffff0000u)}; }
;                     f32x4 v0 = acc[ai][bj][m][0] * ascale, v1 = acc[ai][bj][m][1] * ascale;
;                     if constexpr (MODE == 1) { v0 *= *(const f32x4*)(extra + col0 + o); v1 *= *(const f32x4*)(extra + col0 + o + 4); }
;                     const f32x4 y0 = x0 + *(const f32x4*)(gp + o) * v0, y1 = x1 + *(const f32x4*)(gp + o + 4) * v1;
;                     u32x4 w; w.x = mk::pk2(y0[0], y0[1]); w.y = mk::pk2(y0[2], y0[3]); w.z = mk::pk2(y1[0], y1[1]); w.w = mk::pk2(y1[2], y1[3]); *(u32x4*)(xo + off + o) = w;
	v_pk_fma_f32 v[20:21], v[174:175], v[20:21], v[24:25]
	v_pk_fma_f32 v[18:19], v[176:177], v[18:19], v[22:23]
	s_waitcnt vmcnt(0)
	v_pk_fma_f32 v[22:23], v[178:179], v[32:33], v[28:29]
	v_pk_fma_f32 v[24:25], v[180:181], v[30:31], v[26:27]
	v_cvt_pk_bf16_f32 v18, v18, v19
	v_cvt_pk_bf16_f32 v19, v20, v21
	v_cvt_pk_bf16_f32 v21, v22, v23
	v_pk_mul_f32 v[174:175], v[96:97], s[36:37] op_sel_hi:[1,0]
	v_cvt_pk_bf16_f32 v20, v24, v25
	global_store_dwordx4 v[188:189], v[18:21], off offset:256
	global_load_dwordx4 v[18:21], v[192:193], off
	global_load_dwordx4 v[22:25], v[194:195], off
	global_load_dwordx4 v[26:29], v[194:195], off offset:16
	global_load_dwordx4 v[30:33], v[192:193], off offset:16
	v_pk_mul_f32 v[176:177], v[94:95], s[36:37] op_sel_hi:[1,0]
	v_pk_mul_f32 v[178:179], v[92:93], s[36:37] op_sel_hi:[1,0]
	v_pk_mul_f32 v[180:181], v[90:91], s[36:37] op_sel_hi:[1,0]
	v_lshl_add_u64 v[188:189], v[190:191], 1, s[8:9]
	v_add_u32_e32 v190, 0xffffe090, v8
	s_waitcnt vmcnt(2)
	v_pk_fma_f32 v[20:21], v[174:175], v[20:21], v[24:25]
	v_pk_fma_f32 v[18:19], v[176:177], v[18:19], v[22:23]
	s_waitcnt vmcnt(0)
	v_pk_fma_f32 v[22:23], v[178:179], v[32:33], v[28:29]
	v_pk_fma_f32 v[24:25], v[180:181], v[30:31], v[26:27]
	v_cvt_pk_bf16_f32 v18, v18, v19
	v_cvt_pk_bf16_f32 v19, v20, v21
	v_cvt_pk_bf16_f32 v21, v22, v23
	v_pk_mul_f32 v[174:175], v[88:89], s[36:37] op_sel_hi:[1,0]
	v_cvt_pk_bf16_f32 v20, v24, v25
	global_store_dwordx4 v[188:189], v[18:21], off
	global_load_dwordx4 v[18:21], v[192:193], off offset:512
	s_nop 0
	global_load_dwordx4 v[22:25], v[194:195], off offset:512
	global_load_dwordx4 v[26:29], v[194:195], off offset:528
	global_load_dwordx4 v[30:33], v[192:193], off offset:528
	v_lshrrev_b32_e32 v192, 3, v190
	v_pk_mul_f32 v[176:177], v[86:87], s[36:37] op_sel_hi:[1,0]
	v_or_b32_e32 v192, 4, v192
	v_pk_mul_f32 v[178:179], v[80:81], s[36:37] op_sel_hi:[1,0]
	v_pk_mul_f32 v[180:181], v[78:79], s[36:37] op_sel_hi:[1,0]
	v_cndmask_b32_e32 v194, v192, v196, vcc
	v_lshl_add_u64 v[190:191], v[16:17], 0, s[52:53]
	v_mad_i64_i32 v[194:195], s[52:53], v194, s87, v[12:13]
	v_lshl_add_u64 v[194:195], v[194:195], 0, v[14:15]
	v_lshl_add_u64 v[192:193], v[190:191], 2, s[40:41]
	v_cmp_gt_i32_e32 vcc, s10, v8
	s_mov_b64 s[52:53], 0x50000
	s_movk_i32 s10, 0x1f50
	s_waitcnt vmcnt(2)
	v_pk_fma_f32 v[20:21], v[174:175], v[20:21], v[24:25]
	v_pk_fma_f32 v[18:19], v[176:177], v[18:19], v[22:23]
	s_waitcnt vmcnt(0)
	v_pk_fma_f32 v[22:23], v[178:179], v[32:33], v[28:29]
	v_pk_fma_f32 v[24:25], v[180:181], v[30:31], v[26:27]
	v_cvt_pk_bf16_f32 v18, v18, v19
	v_cvt_pk_bf16_f32 v19, v20, v21
	v_cvt_pk_bf16_f32 v21, v22, v23
	v_pk_mul_f32 v[174:175], v[84:85], s[36:37] op_sel_hi:[1,0]
	v_cvt_pk_bf16_f32 v20, v24, v25
	global_store_dwordx4 v[188:189], v[18:21], off offset:256
	global_load_dwordx4 v[18:21], v[194:195], off
	global_load_dwordx4 v[22:25], v[192:193], off
	global_load_dwordx4 v[26:29], v[192:193], off offset:16
	global_load_dwordx4 v[30:33], v[194:195], off offset:16
	v_pk_mul_f32 v[176:177], v[82:83], s[36:37] op_sel_hi:[1,0]
	v_pk_mul_f32 v[178:179], v[76:77], s[36:37] op_sel_hi:[1,0]
	v_pk_mul_f32 v[180:181], v[74:75], s[36:37] op_sel_hi:[1,0]
	v_lshl_add_u64 v[188:189], v[190:191], 1, s[8:9]
	v_add_u32_e32 v190, 0xffffe0a0, v8
	s_waitcnt vmcnt(2)
	v_pk_fma_f32 v[20:21], v[174:175], v[20:21], v[24:25]
	v_pk_fma_f32 v[18:19], v[176:177], v[18:19], v[22:23]
	s_waitcnt vmcnt(0)
	v_pk_fma_f32 v[22:23], v[178:179], v[32:33], v[28:29]
	v_pk_fma_f32 v[24:25], v[180:181], v[30:31], v[26:27]
	v_cvt_pk_bf16_f32 v18, v18, v19
	v_cvt_pk_bf16_f32 v19, v20, v21
	v_cvt_pk_bf16_f32 v21, v22, v23
	v_pk_mul_f32 v[174:175], v[72:73], s[36:37] op_sel_hi:[1,0]
	v_cvt_pk_bf16_f32 v20, v24, v25
	global_store_dwordx4 v[188:189], v[18:21], off
	global_load_dwordx4 v[18:21], v[194:195], off offset:512
	s_nop 0
	global_load_dwordx4 v[22:25], v[192:193], off offset:512
	global_load_dwordx4 v[26:29], v[192:193], off offset:528
	global_load_dwordx4 v[30:33], v[194:195], off offset:528
	v_lshrrev_b32_e32 v192, 3, v190
	v_pk_mul_f32 v[176:177], v[70:71], s[36:37] op_sel_hi:[1,0]
	v_add_u32_e32 v192, 4, v192
	v_pk_mul_f32 v[178:179], v[64:65], s[36:37] op_sel_hi:[1,0]
	v_pk_mul_f32 v[180:181], v[62:63], s[36:37] op_sel_hi:[1,0]
	v_cndmask_b32_e32 v194, v192, v196, vcc
	v_lshl_add_u64 v[190:191], v[16:17], 0, s[52:53]
	v_mad_i64_i32 v[194:195], s[52:53], v194, s87, v[12:13]
	v_lshl_add_u64 v[194:195], v[194:195], 0, v[14:15]
	v_lshl_add_u64 v[192:193], v[190:191], 2, s[40:41]
	s_mov_b64 s[52:53], 0x58000
	v_cmp_gt_i32_e32 vcc, s10, v8
	s_waitcnt vmcnt(2)
; __device__ __forceinline__ unsigned pk2(float lo, float hi) { unsigned r; asm("v_cvt_pk_bf16_f32 %0, %1, %2" : "=v"(r) : "v"(lo), "v"(hi)); return r; }
;     __device__ __forceinline__ void operator()(const f32x4 (&acc)[2][2][4][2], const Unit& u, int wr, int wc, int fr, int fq) const {
;     ...
;         for (int ai = 0; ai < 2; ++ai)
; #pragma unroll
;             for (int m = 0; m < 4; ++m) { const int r = row0 + ai * HALF + m * 16; const size_t off = (size_t)r * mk::D + col0; const float* gp = gate + (size_t)mk::seq_of(r) * mk::NMOD + col0;
;                 float ss = 0.f;
; #pragma unroll
;                 for (int bj = 0; bj < 2; ++bj) { const int o = bj * HALF;
;                     f32x4 x0, x1;
;                     if constexpr (XIF32) { x0 = *(const f32x4*)((const float*)xi + off + o); x1 = *(const f32x4*)((const float*)xi + off + o + 4); }
;                     else { const u32x4 w = *(const u32x4*)((const bf16*)xi + off + o);
;                         x0 = (f32x4){__uint_as_float(w.x << 16), __uint_as_float(w.x & 0xffff0000u), __uint_as_float(w.y << 16), __uint_as_float(w.y & 0xffff0000u)};
;                         x1 = (f32x4){__uint_as_float(w.z << 16), __uint_as_float(w.z & 0xffff0000u), __uint_as_float(w.w << 16), __uint_as_float(w.w & 0xffff0000u)}; }
;                     f32x4 v0 = acc[ai][bj][m][0] * ascale, v1 = acc[ai][bj][m][1] * ascale;
;                     if constexpr (MODE == 1) { v0 *= *(const f32x4*)(extra + col0 + o); v1 *= *(const f32x4*)(extra + col0 + o + 4); }
;                     const f32x4 y0 = x0 + *(const f32x4*)(gp + o) * v0, y1 = x1 + *(const f32x4*)(gp + o + 4) * v1;
;                     u32x4 w; w.x = mk::pk2(y0[0], y0[1]); w.y = mk::pk2(y0[2], y0[3]); w.z = mk::pk2(y1[0], y1[1]); w.w = mk::pk2(y1[2], y1[3]); *(u32x4*)(xo + off + o) = w;
	v_pk_fma_f32 v[20:21], v[174:175], v[20:21], v[24:25]
	v_pk_fma_f32 v[18:19], v[176:177], v[18:19], v[22:23]
	s_waitcnt vmcnt(0)
	v_pk_fma_f32 v[22:23], v[178:179], v[32:33], v[28:29]
	v_pk_fma_f32 v[24:25], v[180:181], v[30:31], v[26:27]
	v_cvt_pk_bf16_f32 v18, v18, v19
	v_cvt_pk_bf16_f32 v19, v20, v21
	v_cvt_pk_bf16_f32 v21, v22, v23
	v_pk_mul_f32 v[174:175], v[68:69], s[36:37] op_sel_hi:[1,0]
	v_cvt_pk_bf16_f32 v20, v24, v25
	global_store_dwordx4 v[188:189], v[18:21], off offset:256
	global_load_dwordx4 v[18:21], v[194:195], off
	global_load_dwordx4 v[22:25], v[192:193], off
	global_load_dwordx4 v[26:29], v[192:193], off offset:16
	global_load_dwordx4 v[30:33], v[194:195], off offset:16
	v_pk_mul_f32 v[176:177], v[66:67], s[36:37] op_sel_hi:[1,0]
	v_pk_mul_f32 v[178:179], v[60:61], s[36:37] op_sel_hi:[1,0]
	v_pk_mul_f32 v[180:181], v[58:59], s[36:37] op_sel_hi:[1,0]
	v_lshl_add_u64 v[188:189], v[190:191], 1, s[8:9]
	v_add_u32_e32 v190, 0xffffe0b0, v8
	s_waitcnt vmcnt(2)
	v_pk_fma_f32 v[20:21], v[174:175], v[20:21], v[24:25]
	v_pk_fma_f32 v[18:19], v[176:177], v[18:19], v[22:23]
	s_waitcnt vmcnt(0)
	v_pk_fma_f32 v[22:23], v[178:179], v[32:33], v[28:29]
	v_pk_fma_f32 v[24:25], v[180:181], v[30:31], v[26:27]
	v_cvt_pk_bf16_f32 v18, v18, v19
	v_cvt_pk_bf16_f32 v19, v20, v21
	v_cvt_pk_bf16_f32 v21, v22, v23
	v_pk_mul_f32 v[174:175], v[56:57], s[36:37] op_sel_hi:[1,0]
	v_cvt_pk_bf16_f32 v20, v24, v25
	global_store_dwordx4 v[188:189], v[18:21], off
	global_load_dwordx4 v[18:21], v[194:195], off offset:512
	s_nop 0
	global_load_dwordx4 v[22:25], v[192:193], off offset:512
	global_load_dwordx4 v[26:29], v[192:193], off offset:528
	global_load_dwordx4 v[30:33], v[194:195], off offset:528
	v_lshrrev_b32_e32 v192, 3, v190
	v_lshl_add_u64 v[190:191], v[16:17], 0, s[52:53]
	v_add_u32_e32 v16, 4, v192
	v_cndmask_b32_e32 v16, v16, v196, vcc
	v_pk_mul_f32 v[176:177], v[54:55], s[36:37] op_sel_hi:[1,0]
	v_mad_i64_i32 v[12:13], s[52:53], v16, s87, v[12:13]
	v_pk_mul_f32 v[178:179], v[48:49], s[36:37] op_sel_hi:[1,0]
	v_pk_mul_f32 v[180:181], v[46:47], s[36:37] op_sel_hi:[1,0]
	v_lshl_add_u64 v[194:195], v[12:13], 0, v[14:15]
	v_lshl_add_u64 v[192:193], v[190:191], 2, s[40:41]
	s_waitcnt vmcnt(2)
	v_pk_fma_f32 v[14:15], v[174:175], v[20:21], v[24:25]
	v_pk_fma_f32 v[12:13], v[176:177], v[18:19], v[22:23]
	s_waitcnt vmcnt(0)
	v_pk_fma_f32 v[16:17], v[178:179], v[32:33], v[28:29]
	v_pk_fma_f32 v[18:19], v[180:181], v[30:31], v[26:27]
	v_cvt_pk_bf16_f32 v12, v12, v13
	v_cvt_pk_bf16_f32 v13, v14, v15
	v_cvt_pk_bf16_f32 v15, v16, v17
	v_pk_mul_f32 v[28:29], v[52:53], s[36:37] op_sel_hi:[1,0]
	v_cvt_pk_bf16_f32 v14, v18, v19
	global_store_dwordx4 v[188:189], v[12:15], off offset:256
	global_load_dwordx4 v[12:15], v[194:195], off
	global_load_dwordx4 v[16:19], v[192:193], off
	global_load_dwordx4 v[20:23], v[192:193], off offset:16
	global_load_dwordx4 v[24:27], v[194:195], off offset:16
	v_pk_mul_f32 v[30:31], v[50:51], s[36:37] op_sel_hi:[1,0]
	v_pk_mul_f32 v[32:33], v[44:45], s[36:37] op_sel_hi:[1,0]
	v_pk_mul_f32 v[174:175], v[42:43], s[36:37] op_sel_hi:[1,0]
	v_lshl_add_u64 v[176:177], v[190:191], 1, s[8:9]
	s_waitcnt vmcnt(2)
	v_pk_fma_f32 v[14:15], v[28:29], v[14:15], v[18:19]
	v_pk_fma_f32 v[12:13], v[30:31], v[12:13], v[16:17]
	s_waitcnt vmcnt(0)
	v_pk_fma_f32 v[16:17], v[32:33], v[26:27], v[22:23]
	v_pk_fma_f32 v[18:19], v[174:175], v[24:25], v[20:21]
	v_cvt_pk_bf16_f32 v12, v12, v13
	v_cvt_pk_bf16_f32 v13, v14, v15
	v_cvt_pk_bf16_f32 v15, v16, v17
	v_pk_mul_f32 v[28:29], v[40:41], s[36:37] op_sel_hi:[1,0]
	v_cvt_pk_bf16_f32 v14, v18, v19
	global_store_dwordx4 v[176:177], v[12:15], off
	global_load_dwordx4 v[12:15], v[194:195], off offset:512
	s_nop 0
	global_load_dwordx4 v[16:19], v[192:193], off offset:512
	global_load_dwordx4 v[20:23], v[192:193], off offset:528
	global_load_dwordx4 v[24:27], v[194:195], off offset:528
	v_pk_mul_f32 v[30:31], v[38:39], s[36:37] op_sel_hi:[1,0]
	v_pk_mul_f32 v[32:33], v[36:37], s[36:37] op_sel_hi:[1,0]
	v_pk_mul_f32 v[174:175], v[34:35], s[36:37] op_sel_hi:[1,0]
	s_waitcnt vmcnt(2)
	v_pk_fma_f32 v[14:15], v[28:29], v[14:15], v[18:19]
	v_pk_fma_f32 v[12:13], v[30:31], v[12:13], v[16:17]
	s_waitcnt vmcnt(0)
	v_pk_fma_f32 v[16:17], v[32:33], v[26:27], v[22:23]
	v_pk_fma_f32 v[18:19], v[174:175], v[24:25], v[20:21]
	v_cvt_pk_bf16_f32 v12, v12, v13
	v_cvt_pk_bf16_f32 v13, v14, v15
	v_cvt_pk_bf16_f32 v15, v16, v17
	s_nop 0
	v_cvt_pk_bf16_f32 v14, v18, v19
	global_store_dwordx4 v[176:177], v[12:15], off offset:256
	s_cbranch_execz .LBB0_811

;     __device__ __forceinline__ void operator()(const f32x4 (&acc)[2][2][4][2], const Unit& u, int wr, int wc, int fr, int fq) const {
;         const int row0 = u.pm * BM + wr * 64 + fr, col0 = u.pn * BM + wc * 32 + 8 * fq;
;         if (u.part >= 0) {
;             bf16* sp = slab + ((ptrdiff_t)u.part * mk::MS - mk::MP) * (ptrdiff_t)mk::D + col0;
; #pragma unroll
;             for (int ai = 0; ai < 2; ++ai)
; #pragma unroll
;                 for (int m = 0; m < 4; ++m) { bf16* rowp = sp + (ptrdiff_t)(row0 + ai * HALF + m * 16) * mk::D;
; #pragma unroll
;                     for (int bj = 0; bj < 2; ++bj) { const f32x4 v0 = acc[ai][bj][m][0] * ascale, v1 = acc[ai][bj][m][1] * ascale;
;                         u32x4 w; w.x = mk::pk2(v0[0], v0[1]); w.y = mk::pk2(v0[2], v0[3]); w.z = mk::pk2(v1[0], v1[1]); w.w = mk::pk2(v1[2], v1[3]); *(u32x4*)(rowp + bj * HALF) = w; } }
;             return;
;         }
; #pragma unroll
;         for (int ai = 0; ai < 2; ++ai)
; #pragma unroll
;             for (int m = 0; m < 4; ++m) { const int r = row0 + ai * HALF + m * 16; const size_t off = (size_t)r * mk::D + col0; const float* gp = gate + (size_t)mk::seq_of(r) * mk::NMOD + col0;
;                 float ss = 0.f;
; #pragma unroll
;                 for (int bj = 0; bj < 2; ++bj) { const int o = bj * HALF;
;                     f32x4 x0, x1;
;                     if constexpr (XIF32) { x0 = *(const f32x4*)((const float*)xi + off + o); x1 = *(const f32x4*)((const float*)xi + off + o + 4); }
;                     else { const u32x4 w = *(const u32x4*)((const bf16*)xi + off + o);
;                         x0 = (f32x4){__uint_as_float(w.x << 16), __uint_as_float(w.x & 0xffff0000u), __uint_as_float(w.y << 16), __uint_as_float(w.y & 0xffff0000u)};
;                         x1 = (f32x4){__uint_as_float(w.z << 16), __uint_as_float(w.z & 0xffff0000u), __uint_as_float(w.w << 16), __uint_as_float(w.w & 0xffff0000u)}; }
;                     f32x4 v0 = acc[ai][bj][m][0] * ascale, v1 = acc[ai][bj][m][1] * ascale;
;                     if constexpr (MODE == 1) { v0 *= *(const f32x4*)(extra + col0 + o); v1 *= *(const f32x4*)(extra + col0 + o + 4); }
;                     const f32x4 y0 = x0 + *(const f32x4*)(gp + o) * v0, y1 = x1 + *(const f32x4*)(gp + o + 4) * v1;
.LBB0_1140:
	s_lshl_b32 s10, s68, 8
	s_nop 15
	s_nop 15
	s_add_i32 s10, s10, s81
	v_or_b32_e32 v6, s10, v1
	v_lshl_or_b32 v8, s69, 8, v183
	s_mov_b64 s[60:61], -1
	s_cmp_gt_i32 s18, -1
	v_ashrrev_i32_e32 v9, 31, v8
	v_ashrrev_i32_e32 v7, 31, v6
	s_cbranch_scc1 .LBB0_1159
	v_lshl_add_u32 v10, v6, 11, v8
	v_lshlrev_b32_e32 v10, 1, v10
	global_load_dword v22, v10, s[8:9]
	global_load_dword v22, v10, s[8:9] offset:256
	v_add_u32_e32 v11, 0x10000, v10
	global_load_dword v22, v11, s[8:9]
	global_load_dword v22, v11, s[8:9] offset:256
	v_add_u32_e32 v11, 0x20000, v10
	global_load_dword v22, v11, s[8:9]
	global_load_dword v22, v11, s[8:9] offset:256
	v_add_u32_e32 v11, 0x30000, v10
	global_load_dword v22, v11, s[8:9]
	global_load_dword v22, v11, s[8:9] offset:256
	v_add_u32_e32 v11, 0x80000, v10
	global_load_dword v22, v11, s[8:9]
	global_load_dword v22, v11, s[8:9] offset:256
	v_add_u32_e32 v11, 0x90000, v10
	global_load_dword v22, v11, s[8:9]
	global_load_dword v22, v11, s[8:9] offset:256
	v_add_u32_e32 v11, 0xa0000, v10
	global_load_dword v22, v11, s[8:9]
	global_load_dword v22, v11, s[8:9] offset:256
	v_add_u32_e32 v11, 0xb0000, v10
	global_load_dword v22, v11, s[8:9]
	global_load_dword v22, v11, s[8:9] offset:256
	s_nop 0
	s_nop 0
	s_nop 0
	s_nop 0
	s_nop 0
	s_nop 0
	s_nop 0
	s_nop 0
	s_nop 0
	s_nop 0
	s_nop 0
	s_nop 0
	s_nop 0
	s_nop 0
	s_nop 0
	v_add_u32_e32 v4, 0xffffe000, v6
	s_ashr_i32 s72, s10, 11
	v_lshlrev_b64 v[2:3], 11, v[6:7]
	v_lshrrev_b32_e32 v4, 3, v4
	v_lshl_add_u64 v[2:3], v[2:3], 0, v[8:9]
	v_or_b32_e32 v4, 4, v4
	v_mov_b32_e32 v5, s72
	v_cmp_gt_i32_e32 vcc, s80, v6
	v_lshlrev_b64 v[10:11], 1, v[2:3]
	v_lshl_add_u64 v[2:3], s[8:9], 0, v[10:11]
	v_cndmask_b32_e32 v12, v4, v5, vcc
	v_mov_b64_e32 v[4:5], s[22:23]
	v_mad_i64_i32 v[4:5], s[60:61], v12, s86, v[4:5]
	global_load_dwordx4 v[14:17], v[2:3], off
	v_lshl_add_u64 v[12:13], v[8:9], 2, v[4:5]
	global_load_dwordx4 v[18:21], v[12:13], off
	global_load_dwordx4 v[22:25], v[12:13], off offset:16
	v_pk_mul_f32 v[26:27], v[160:161], s[54:55] op_sel_hi:[1,0]
	v_pk_mul_f32 v[28:29], v[158:159], s[54:55] op_sel_hi:[1,0]
	v_pk_mul_f32 v[30:31], v[156:157], s[54:55] op_sel_hi:[1,0]
	v_pk_mul_f32 v[32:33], v[154:155], s[54:55] op_sel_hi:[1,0]
	v_lshl_add_u64 v[10:11], s[14:15], 0, v[10:11]
	global_load_dwordx4 v[2:5], v[2:3], off offset:256
	s_waitcnt vmcnt(0)
	v_lshlrev_b32_e32 v174, 16, v14
	v_and_b32_e32 v175, 0xffff0000, v14
	v_lshlrev_b32_e32 v14, 16, v15
	v_and_b32_e32 v15, 0xffff0000, v15
	v_lshlrev_b32_e32 v176, 16, v16
	v_and_b32_e32 v177, 0xffff0000, v16
	v_lshlrev_b32_e32 v16, 16, v17
	v_and_b32_e32 v17, 0xffff0000, v17
	v_pk_fma_f32 v[14:15], v[26:27], v[20:21], v[14:15]
	v_pk_fma_f32 v[18:19], v[28:29], v[18:19], v[174:175]
	v_pk_fma_f32 v[16:17], v[30:31], v[24:25], v[16:17]
	v_pk_fma_f32 v[20:21], v[32:33], v[22:23], v[176:177]
	v_cvt_pk_bf16_f32 v22, v18, v19
	v_cvt_pk_bf16_f32 v23, v14, v15
	v_cvt_pk_bf16_f32 v25, v16, v17
	v_mul_f32_e32 v19, v19, v19
	v_cvt_pk_bf16_f32 v24, v20, v21
	global_store_dwordx4 v[10:11], v[22:25], off
	global_load_dwordx4 v[22:25], v[12:13], off offset:512
	s_nop 0
	global_load_dwordx4 v[26:29], v[12:13], off offset:528
	v_mul_f32_e32 v15, v15, v15
	v_mul_f32_e32 v21, v21, v21
	v_mul_f32_e32 v17, v17, v17
	v_pk_mul_f32 v[30:31], v[152:153], s[54:55] op_sel_hi:[1,0]
	v_pk_mul_f32 v[32:33], v[150:151], s[54:55] op_sel_hi:[1,0]
	v_pk_mul_f32 v[174:175], v[144:145], s[54:55] op_sel_hi:[1,0]
	v_pk_mul_f32 v[176:177], v[142:143], s[54:55] op_sel_hi:[1,0]
	v_lshlrev_b32_e32 v178, 16, v2
	v_and_b32_e32 v179, 0xffff0000, v2
	v_lshlrev_b32_e32 v2, 16, v3
	v_and_b32_e32 v3, 0xffff0000, v3
	v_lshlrev_b32_e32 v180, 16, v4
	v_and_b32_e32 v181, 0xffff0000, v4
	v_lshlrev_b32_e32 v4, 16, v5
	v_and_b32_e32 v5, 0xffff0000, v5
	v_fmac_f32_e32 v19, v18, v18
	v_fmac_f32_e32 v15, v14, v14
	v_fmac_f32_e32 v21, v20, v20
	v_fmac_f32_e32 v17, v16, v16
	v_add_f32_e32 v14, v19, v15
	v_add_f32_e32 v15, v21, v17
	v_and_b32_e32 v13, 64, v188
	v_add_f32_e32 v14, v14, v15
	v_xor_b32_e32 v12, 16, v188
	v_add_u32_e32 v13, 64, v13
	v_cmp_lt_i32_e32 vcc, v12, v13
	s_waitcnt vmcnt(1)
	v_pk_fma_f32 v[16:17], v[30:31], v[24:25], v[2:3]
	v_pk_fma_f32 v[2:3], v[32:33], v[22:23], v[178:179]
	s_waitcnt vmcnt(0)
	v_pk_fma_f32 v[4:5], v[174:175], v[28:29], v[4:5]
	v_pk_fma_f32 v[18:19], v[176:177], v[26:27], v[180:181]
	v_mul_f32_e32 v15, v3, v3
	v_mul_f32_e32 v20, v17, v17
	v_mul_f32_e32 v21, v19, v19
	v_mul_f32_e32 v22, v5, v5
	v_fmac_f32_e32 v15, v2, v2
	v_fmac_f32_e32 v20, v16, v16
	v_fmac_f32_e32 v21, v18, v18
	v_fmac_f32_e32 v22, v4, v4
	v_add_f32_e32 v15, v15, v20
	v_add_f32_e32 v20, v21, v22
	v_cndmask_b32_e32 v12, v188, v12, vcc
	v_add_f32_e32 v15, v15, v20
	v_lshlrev_b32_e32 v12, 2, v12
	v_add_f32_e32 v15, v14, v15
	ds_bpermute_b32 v20, v12, v15
	v_xor_b32_e32 v14, 32, v188
	v_cmp_lt_i32_e32 vcc, v14, v13
	s_nop 1
	v_cndmask_b32_e32 v13, v188, v14, vcc
	v_cvt_pk_bf16_f32 v14, v2, v3
	s_waitcnt lgkmcnt(0)
	v_add_f32_e32 v2, v15, v20
	v_lshlrev_b32_e32 v13, 2, v13
	ds_bpermute_b32 v3, v13, v2
	v_cvt_pk_bf16_f32 v15, v16, v17
	v_cvt_pk_bf16_f32 v16, v18, v19
	v_cvt_pk_bf16_f32 v17, v4, v5
	global_store_dwordx4 v[10:11], v[14:17], off offset:256
	s_and_saveexec_b64 s[60:61], s[0:1]
	s_cbranch_execz .LBB0_1143
	v_lshl_add_u64 v[4:5], v[6:7], 2, s[36:37]
	s_waitcnt lgkmcnt(0)
	v_add_f32_e32 v2, v2, v3
	global_atomic_add_f32 v[4:5], v2, off

;     __device__ __forceinline__ void operator()(const f32x4 (&acc)[2][2][4][2], const Unit& u, int wr, int wc, int fr, int fq) const {
;         const int row0 = u.pm * BM + wr * 64 + fr, col0 = u.pn * BM + wc * 32 + 8 * fq;
;         if (u.part >= 0) {
;             bf16* sp = slab + ((ptrdiff_t)u.part * mk::MS - mk::MP) * (ptrdiff_t)mk::D + col0;
; #pragma unroll
;             for (int ai = 0; ai < 2; ++ai)
; #pragma unroll
;                 for (int m = 0; m < 4; ++m) { bf16* rowp = sp + (ptrdiff_t)(row0 + ai * HALF + m * 16) * mk::D;
; #pragma unroll
;                     for (int bj = 0; bj < 2; ++bj) { const f32x4 v0 = acc[ai][bj][m][0] * ascale, v1 = acc[ai][bj][m][1] * ascale;
;                         u32x4 w; w.x = mk::pk2(v0[0], v0[1]); w.y = mk::pk2(v0[2], v0[3]); w.z = mk::pk2(v1[0], v1[1]); w.w = mk::pk2(v1[2], v1[3]); *(u32x4*)(rowp + bj * HALF) = w; } }
;             return;
;         }
; #pragma unroll
;         for (int ai = 0; ai < 2; ++ai)
; #pragma unroll
;             for (int m = 0; m < 4; ++m) { const int r = row0 + ai * HALF + m * 16; const size_t off = (size_t)r * mk::D + col0; const float* gp = gate + (size_t)mk::seq_of(r) * mk::NMOD + col0;
;                 float ss = 0.f;
; #pragma unroll
;                 for (int bj = 0; bj < 2; ++bj) { const int o = bj * HALF;
;                     f32x4 x0, x1;
;                     if constexpr (XIF32) { x0 = *(const f32x4*)((const float*)xi + off + o); x1 = *(const f32x4*)((const float*)xi + off + o + 4); }
;                     else { const u32x4 w = *(const u32x4*)((const bf16*)xi + off + o);
;                         x0 = (f32x4){__uint_as_float(w.x << 16), __uint_as_float(w.x & 0xffff0000u), __uint_as_float(w.y << 16), __uint_as_float(w.y & 0xffff0000u)};
;                         x1 = (f32x4){__uint_as_float(w.z << 16), __uint_as_float(w.z & 0xffff0000u), __uint_as_float(w.w << 16), __uint_as_float(w.w & 0xffff0000u)}; }
;                     f32x4 v0 = acc[ai][bj][m][0] * ascale, v1 = acc[ai][bj][m][1] * ascale;
;                     if constexpr (MODE == 1) { v0 *= *(const f32x4*)(extra + col0 + o); v1 *= *(const f32x4*)(extra + col0 + o + 4); }
;                     const f32x4 y0 = x0 + *(const f32x4*)(gp + o) * v0, y1 = x1 + *(const f32x4*)(gp + o + 4) * v1;
.LBB0_1678:
	s_lshl_b32 s10, s68, 8
	s_add_i32 s10, s10, s76
	v_or_b32_e32 v148, s10, v1
	v_lshl_or_b32 v150, s69, 8, v161
	v_or_b32_e32 v146, 16, v148
	v_or_b32_e32 v144, 32, v148
	v_or_b32_e32 v142, 48, v148
	s_mov_b64 s[58:59], -1
	s_cmp_gt_i32 s2, -1
	v_ashrrev_i32_e32 v151, 31, v150
	v_ashrrev_i32_e32 v149, 31, v148
	v_ashrrev_i32_e32 v147, 31, v146
	v_ashrrev_i32_e32 v145, 31, v144
	v_ashrrev_i32_e32 v143, 31, v142
	s_cbranch_scc1 .LBB0_1681
	v_lshl_add_u32 v152, v148, 11, v150
	v_lshlrev_b32_e32 v152, 1, v152
	global_load_dword v166, v152, s[14:15]
	global_load_dword v166, v152, s[14:15] offset:256
	v_add_u32_e32 v153, 0x10000, v152
	global_load_dword v166, v153, s[14:15]
	global_load_dword v166, v153, s[14:15] offset:256
	v_add_u32_e32 v153, 0x20000, v152
	global_load_dword v166, v153, s[14:15]
	global_load_dword v166, v153, s[14:15] offset:256
	v_add_u32_e32 v153, 0x30000, v152
	global_load_dword v166, v153, s[14:15]
	global_load_dword v166, v153, s[14:15] offset:256
	v_add_u32_e32 v153, 0x80000, v152
	global_load_dword v166, v153, s[14:15]
	global_load_dword v166, v153, s[14:15] offset:256
	v_add_u32_e32 v153, 0x90000, v152
	global_load_dword v166, v153, s[14:15]
	global_load_dword v166, v153, s[14:15] offset:256
	v_add_u32_e32 v153, 0xa0000, v152
	global_load_dword v166, v153, s[14:15]
	global_load_dword v166, v153, s[14:15] offset:256
	v_add_u32_e32 v153, 0xb0000, v152
	global_load_dword v166, v153, s[14:15]
	global_load_dword v166, v153, s[14:15] offset:256
	s_nop 0
	s_nop 0
	s_nop 0
	s_nop 0
	s_nop 0
	s_nop 0
	s_nop 0
	s_nop 0
	s_nop 0
	s_nop 0
	s_nop 0
	s_nop 0
	s_nop 0
	s_nop 0
	s_nop 0
	v_lshlrev_b64 v[152:153], 11, v[148:149]
	v_lshl_add_u64 v[156:157], v[152:153], 0, v[150:151]
	v_add_u32_e32 v152, 0xffffe000, v148
	s_ashr_i32 s10, s10, 11
	v_lshrrev_b32_e32 v158, 3, v152
	v_readlane_b32 s36, v240, 7
	v_or_b32_e32 v178, 4, v158
	v_mov_b32_e32 v165, s10
	v_cmp_gt_i32_e32 vcc, s75, v148
	v_lshlrev_b64 v[154:155], 2, v[150:151]
	v_readlane_b32 s48, v240, 19
	v_readlane_b32 s49, v240, 20
	v_lshlrev_b64 v[158:159], 1, v[156:157]
	v_cndmask_b32_e32 v178, v178, v165, vcc
	v_mov_b64_e32 v[156:157], s[16:17]
	v_lshl_add_u64 v[152:153], s[48:49], 0, v[154:155]
	v_lshl_add_u64 v[186:187], s[14:15], 0, v[158:159]
	v_mad_i64_i32 v[178:179], s[58:59], v178, s81, v[156:157]
	global_load_dwordx4 v[166:169], v[152:153], off offset:16
	global_load_dwordx4 v[170:173], v[152:153], off
	global_load_dwordx4 v[174:177], v[186:187], off
	v_lshl_add_u64 v[190:191], v[178:179], 0, v[154:155]
	global_load_dwordx4 v[178:181], v[190:191], off
	global_load_dwordx4 v[182:185], v[190:191], off offset:16
	v_lshl_add_u64 v[192:193], s[8:9], 0, v[158:159]
	global_load_dwordx4 v[186:189], v[186:187], off offset:256
	v_cmp_gt_i32_e32 vcc, s75, v146
	v_add_u32_e32 v198, 0xffffe080, v148
	s_movk_i32 s10, 0x1f80
	v_readlane_b32 s44, v240, 15
	v_readlane_b32 s45, v240, 16
	v_readlane_b32 s44, v240, 44
	v_readlane_b32 s37, v240, 8
	v_readlane_b32 s38, v240, 9
	v_readlane_b32 s39, v240, 10
	v_readlane_b32 s40, v240, 11
	v_readlane_b32 s41, v240, 12
	v_readlane_b32 s42, v240, 13
	v_readlane_b32 s43, v240, 14
	v_readlane_b32 s46, v240, 17
	v_readlane_b32 s47, v240, 18
	v_readlane_b32 s50, v240, 21
	v_readlane_b32 s51, v240, 22
	v_readlane_b32 s45, v240, 45
	s_waitcnt vmcnt(0)
	v_pk_mul_f32 v[168:169], v[124:125], v[168:169]
	v_pk_mul_f32 v[172:173], v[128:129], v[172:173]
	v_pk_mul_f32 v[166:167], v[122:123], v[166:167]
	v_lshlrev_b32_e32 v194, 16, v174
	v_and_b32_e32 v195, 0xffff0000, v174
	v_lshlrev_b32_e32 v174, 16, v175
	v_and_b32_e32 v175, 0xffff0000, v175
	v_lshlrev_b32_e32 v196, 16, v176
	v_and_b32_e32 v197, 0xffff0000, v176
	v_lshlrev_b32_e32 v176, 16, v177
	v_and_b32_e32 v177, 0xffff0000, v177
	v_pk_mul_f32 v[170:171], v[126:127], v[170:171]
	v_pk_fma_f32 v[172:173], v[172:173], v[180:181], v[174:175]
	v_pk_fma_f32 v[174:175], v[168:169], v[184:185], v[176:177]
	v_pk_fma_f32 v[168:169], v[166:167], v[182:183], v[196:197]
	v_pk_fma_f32 v[170:171], v[170:171], v[178:179], v[194:195]
	v_cvt_pk_bf16_f32 v167, v172, v173
	v_cvt_pk_bf16_f32 v168, v168, v169
	v_cvt_pk_bf16_f32 v169, v174, v175
	v_lshlrev_b64 v[182:183], 11, v[146:147]
	v_cvt_pk_bf16_f32 v166, v170, v171
	global_store_dwordx4 v[192:193], v[166:169], off
	global_load_dwordx4 v[166:169], v[152:153], off offset:512
	s_nop 0
	global_load_dwordx4 v[170:173], v[152:153], off offset:528
	global_load_dwordx4 v[174:177], v[190:191], off offset:512
	global_load_dwordx4 v[178:181], v[190:191], off offset:528
	v_lshl_add_u64 v[182:183], v[182:183], 0, v[150:151]
	v_lshlrev_b64 v[190:191], 1, v[182:183]
	v_lshlrev_b32_e32 v182, 16, v186
	v_and_b32_e32 v183, 0xffff0000, v186
	v_lshlrev_b32_e32 v184, 16, v187
	v_and_b32_e32 v185, 0xffff0000, v187
	v_lshlrev_b32_e32 v186, 16, v188
	v_and_b32_e32 v187, 0xffff0000, v188
	v_lshlrev_b32_e32 v188, 16, v189
	v_and_b32_e32 v189, 0xffff0000, v189
	v_lshl_add_u64 v[194:195], s[14:15], 0, v[190:191]
	v_lshl_add_u64 v[190:191], s[8:9], 0, v[190:191]
	s_waitcnt vmcnt(3)
	v_pk_mul_f32 v[168:169], v[116:117], v[168:169]
	v_pk_mul_f32 v[166:167], v[114:115], v[166:167]
	s_waitcnt vmcnt(2)
	v_pk_mul_f32 v[170:171], v[106:107], v[170:171]
	s_waitcnt vmcnt(1)
	v_pk_fma_f32 v[168:169], v[168:169], v[176:177], v[184:185]
	v_pk_fma_f32 v[166:167], v[166:167], v[174:175], v[182:183]
	s_waitcnt vmcnt(0)
; __device__ __forceinline__ unsigned pk2(float lo, float hi) { unsigned r; asm("v_cvt_pk_bf16_f32 %0, %1, %2" : "=v"(r) : "v"(lo), "v"(hi)); return r; }
;     __device__ __forceinline__ void operator()(const f32x4 (&acc)[2][2][4][2], const Unit& u, int wr, int wc, int fr, int fq) const {
;     ...
;         for (int ai = 0; ai < 2; ++ai)
; #pragma unroll
;             for (int m = 0; m < 4; ++m) { const int r = row0 + ai * HALF + m * 16; const size_t off = (size_t)r * mk::D + col0; const float* gp = gate + (size_t)mk::seq_of(r) * mk::NMOD + col0;
;                 float ss = 0.f;
; #pragma unroll
;                 for (int bj = 0; bj < 2; ++bj) { const int o = bj * HALF;
;                     f32x4 x0, x1;
;                     if constexpr (XIF32) { x0 = *(const f32x4*)((const float*)xi + off + o); x1 = *(const f32x4*)((const float*)xi + off + o + 4); }
;                     else { const u32x4 w = *(const u32x4*)((const bf16*)xi + off + o);
;                         x0 = (f32x4){__uint_as_float(w.x << 16), __uint_as_float(w.x & 0xffff0000u), __uint_as_float(w.y << 16), __uint_as_float(w.y & 0xffff0000u)};
;                         x1 = (f32x4){__uint_as_float(w.z << 16), __uint_as_float(w.z & 0xffff0000u), __uint_as_float(w.w << 16), __uint_as_float(w.w & 0xffff0000u)}; }
;                     f32x4 v0 = acc[ai][bj][m][0] * ascale, v1 = acc[ai][bj][m][1] * ascale;
;                     if constexpr (MODE == 1) { v0 *= *(const f32x4*)(extra + col0 + o); v1 *= *(const f32x4*)(extra + col0 + o + 4); }
;                     const f32x4 y0 = x0 + *(const f32x4*)(gp + o) * v0, y1 = x1 + *(const f32x4*)(gp + o + 4) * v1;
;                     u32x4 w; w.x = mk::pk2(y0[0], y0[1]); w.y = mk::pk2(y0[2], y0[3]); w.z = mk::pk2(y1[0], y1[1]); w.w = mk::pk2(y1[2], y1[3]); *(u32x4*)(xo + off + o) = w;
	v_pk_fma_f32 v[170:171], v[170:171], v[178:179], v[186:187]
	v_cvt_pk_bf16_f32 v166, v166, v167
	v_cvt_pk_bf16_f32 v167, v168, v169
	v_pk_mul_f32 v[172:173], v[108:109], v[172:173]
	v_cvt_pk_bf16_f32 v168, v170, v171
	v_add_u32_e32 v170, 0xffffe010, v148
	v_lshrrev_b32_e32 v170, 3, v170
	v_or_b32_e32 v170, 4, v170
	v_pk_fma_f32 v[172:173], v[172:173], v[180:181], v[188:189]
	v_cndmask_b32_e32 v178, v170, v165, vcc
	v_cvt_pk_bf16_f32 v169, v172, v173
	global_store_dwordx4 v[192:193], v[166:169], off offset:256
	v_mad_i64_i32 v[178:179], s[58:59], v178, s81, v[156:157]
	global_load_dwordx4 v[166:169], v[194:195], off
	global_load_dwordx4 v[170:173], v[152:153], off offset:16
	global_load_dwordx4 v[174:177], v[152:153], off
	v_lshl_add_u64 v[192:193], v[178:179], 0, v[154:155]
	global_load_dwordx4 v[178:181], v[192:193], off
	global_load_dwordx4 v[182:185], v[192:193], off offset:16
	global_load_dwordx4 v[186:189], v[194:195], off offset:256
	v_cmp_gt_i32_e32 vcc, s75, v144
	s_waitcnt vmcnt(5)
	v_lshlrev_b32_e32 v194, 16, v166
	v_and_b32_e32 v195, 0xffff0000, v166
	v_lshlrev_b32_e32 v166, 16, v167
	v_and_b32_e32 v167, 0xffff0000, v167
	v_lshlrev_b32_e32 v196, 16, v168
	v_and_b32_e32 v197, 0xffff0000, v168
	v_lshlrev_b32_e32 v168, 16, v169
	v_and_b32_e32 v169, 0xffff0000, v169
	s_waitcnt vmcnt(3)
	v_pk_mul_f32 v[176:177], v[120:121], v[176:177]
	v_pk_mul_f32 v[174:175], v[118:119], v[174:175]
	v_pk_mul_f32 v[172:173], v[112:113], v[172:173]
	v_pk_mul_f32 v[170:171], v[110:111], v[170:171]
	s_waitcnt vmcnt(2)
	v_pk_fma_f32 v[176:177], v[176:177], v[180:181], v[166:167]
	v_pk_fma_f32 v[166:167], v[174:175], v[178:179], v[194:195]
	s_waitcnt vmcnt(1)
	v_pk_fma_f32 v[172:173], v[172:173], v[184:185], v[168:169]
	v_pk_fma_f32 v[168:169], v[170:171], v[182:183], v[196:197]
	v_cvt_pk_bf16_f32 v166, v166, v167
	v_cvt_pk_bf16_f32 v167, v176, v177
	v_lshlrev_b64 v[182:183], 11, v[144:145]
	v_cvt_pk_bf16_f32 v168, v168, v169
	v_cvt_pk_bf16_f32 v169, v172, v173
	global_store_dwordx4 v[190:191], v[166:169], off
	global_load_dwordx4 v[166:169], v[152:153], off offset:512
	s_nop 0
	global_load_dwordx4 v[170:173], v[152:153], off offset:528
	global_load_dwordx4 v[174:177], v[192:193], off offset:512
	global_load_dwordx4 v[178:181], v[192:193], off offset:528
	v_lshl_add_u64 v[182:183], v[182:183], 0, v[150:151]
	v_lshlrev_b64 v[192:193], 1, v[182:183]
	s_waitcnt vmcnt(5)
	v_lshlrev_b32_e32 v182, 16, v186
	v_and_b32_e32 v183, 0xffff0000, v186
	v_lshlrev_b32_e32 v184, 16, v187
	v_and_b32_e32 v185, 0xffff0000, v187
	v_lshlrev_b32_e32 v186, 16, v188
	v_and_b32_e32 v187, 0xffff0000, v188
	v_lshlrev_b32_e32 v188, 16, v189
	v_and_b32_e32 v189, 0xffff0000, v189
	v_lshl_add_u64 v[194:195], s[14:15], 0, v[192:193]
	v_lshl_add_u64 v[192:193], s[8:9], 0, v[192:193]
	s_waitcnt vmcnt(3)
	v_pk_mul_f32 v[168:169], v[100:101], v[168:169]
	v_pk_mul_f32 v[166:167], v[98:99], v[166:167]
	s_waitcnt vmcnt(2)
	v_pk_mul_f32 v[170:171], v[90:91], v[170:171]
	s_waitcnt vmcnt(1)
	v_pk_fma_f32 v[168:169], v[168:169], v[176:177], v[184:185]
	v_pk_fma_f32 v[166:167], v[166:167], v[174:175], v[182:183]
	s_waitcnt vmcnt(0)
	v_pk_fma_f32 v[170:171], v[170:171], v[178:179], v[186:187]
	v_cvt_pk_bf16_f32 v166, v166, v167
	v_cvt_pk_bf16_f32 v167, v168, v169
	v_pk_mul_f32 v[172:173], v[92:93], v[172:173]
	v_cvt_pk_bf16_f32 v168, v170, v171
	v_add_u32_e32 v170, 0xffffe020, v148
	v_lshrrev_b32_e32 v170, 3, v170
	v_add_u32_e32 v170, 4, v170
	v_pk_fma_f32 v[172:173], v[172:173], v[180:181], v[188:189]
	v_cndmask_b32_e32 v178, v170, v165, vcc
	v_cvt_pk_bf16_f32 v169, v172, v173
	global_store_dwordx4 v[190:191], v[166:169], off offset:256
	v_mad_i64_i32 v[178:179], s[58:59], v178, s81, v[156:157]
	global_load_dwordx4 v[166:169], v[194:195], off
	global_load_dwordx4 v[170:173], v[152:153], off offset:16
	global_load_dwordx4 v[174:177], v[152:153], off
	v_lshl_add_u64 v[190:191], v[178:179], 0, v[154:155]
	global_load_dwordx4 v[178:181], v[190:191], off
	global_load_dwordx4 v[182:185], v[190:191], off offset:16
	global_load_dwordx4 v[186:189], v[194:195], off offset:256
	v_cmp_gt_i32_e32 vcc, s75, v142
	s_waitcnt vmcnt(5)
	v_lshlrev_b32_e32 v194, 16, v166
	v_and_b32_e32 v195, 0xffff0000, v166
	v_lshlrev_b32_e32 v166, 16, v167
	v_and_b32_e32 v167, 0xffff0000, v167
	v_lshlrev_b32_e32 v196, 16, v168
	v_and_b32_e32 v197, 0xffff0000, v168
	v_lshlrev_b32_e32 v168, 16, v169
	v_and_b32_e32 v169, 0xffff0000, v169
	s_waitcnt vmcnt(3)
	v_pk_mul_f32 v[176:177], v[104:105], v[176:177]
	v_pk_mul_f32 v[174:175], v[102:103], v[174:175]
	v_pk_mul_f32 v[172:173], v[96:97], v[172:173]
	v_pk_mul_f32 v[170:171], v[94:95], v[170:171]
	s_waitcnt vmcnt(2)
	v_pk_fma_f32 v[176:177], v[176:177], v[180:181], v[166:167]
	v_pk_fma_f32 v[166:167], v[174:175], v[178:179], v[194:195]
	s_waitcnt vmcnt(1)
	v_pk_fma_f32 v[172:173], v[172:173], v[184:185], v[168:169]
	v_pk_fma_f32 v[168:169], v[170:171], v[182:183], v[196:197]
	v_cvt_pk_bf16_f32 v166, v166, v167
	v_cvt_pk_bf16_f32 v167, v176, v177
	v_lshlrev_b64 v[182:183], 11, v[142:143]
	v_cvt_pk_bf16_f32 v168, v168, v169
	v_cvt_pk_bf16_f32 v169, v172, v173
	global_store_dwordx4 v[192:193], v[166:169], off
	global_load_dwordx4 v[166:169], v[152:153], off offset:512
	s_nop 0
	global_load_dwordx4 v[170:173], v[152:153], off offset:528
	global_load_dwordx4 v[174:177], v[190:191], off offset:512
	global_load_dwordx4 v[178:181], v[190:191], off offset:528
	v_lshl_add_u64 v[182:183], v[182:183], 0, v[150:151]
	v_lshlrev_b64 v[190:191], 1, v[182:183]
	s_waitcnt vmcnt(5)
; __device__ __forceinline__ unsigned pk2(float lo, float hi) { unsigned r; asm("v_cvt_pk_bf16_f32 %0, %1, %2" : "=v"(r) : "v"(lo), "v"(hi)); return r; }
;     __device__ __forceinline__ void operator()(const f32x4 (&acc)[2][2][4][2], const Unit& u, int wr, int wc, int fr, int fq) const {
;     ...
;         for (int ai = 0; ai < 2; ++ai)
; #pragma unroll
;             for (int m = 0; m < 4; ++m) { const int r = row0 + ai * HALF + m * 16; const size_t off = (size_t)r * mk::D + col0; const float* gp = gate + (size_t)mk::seq_of(r) * mk::NMOD + col0;
;                 float ss = 0.f;
; #pragma unroll
;                 for (int bj = 0; bj < 2; ++bj) { const int o = bj * HALF;
;                     f32x4 x0, x1;
;                     if constexpr (XIF32) { x0 = *(const f32x4*)((const float*)xi + off + o); x1 = *(const f32x4*)((const float*)xi + off + o + 4); }
;                     else { const u32x4 w = *(const u32x4*)((const bf16*)xi + off + o);
;                         x0 = (f32x4){__uint_as_float(w.x << 16), __uint_as_float(w.x & 0xffff0000u), __uint_as_float(w.y << 16), __uint_as_float(w.y & 0xffff0000u)};
;                         x1 = (f32x4){__uint_as_float(w.z << 16), __uint_as_float(w.z & 0xffff0000u), __uint_as_float(w.w << 16), __uint_as_float(w.w & 0xffff0000u)}; }
;                     f32x4 v0 = acc[ai][bj][m][0] * ascale, v1 = acc[ai][bj][m][1] * ascale;
;                     if constexpr (MODE == 1) { v0 *= *(const f32x4*)(extra + col0 + o); v1 *= *(const f32x4*)(extra + col0 + o + 4); }
;                     const f32x4 y0 = x0 + *(const f32x4*)(gp + o) * v0, y1 = x1 + *(const f32x4*)(gp + o + 4) * v1;
;                     u32x4 w; w.x = mk::pk2(y0[0], y0[1]); w.y = mk::pk2(y0[2], y0[3]); w.z = mk::pk2(y1[0], y1[1]); w.w = mk::pk2(y1[2], y1[3]); *(u32x4*)(xo + off + o) = w;
	v_lshlrev_b32_e32 v182, 16, v186
	v_and_b32_e32 v183, 0xffff0000, v186
	v_lshlrev_b32_e32 v184, 16, v187
	v_and_b32_e32 v185, 0xffff0000, v187
	v_lshlrev_b32_e32 v186, 16, v188
	v_and_b32_e32 v187, 0xffff0000, v188
	v_lshlrev_b32_e32 v188, 16, v189
	v_and_b32_e32 v189, 0xffff0000, v189
	v_lshl_add_u64 v[194:195], s[14:15], 0, v[190:191]
	v_lshl_add_u64 v[190:191], s[8:9], 0, v[190:191]
	s_waitcnt vmcnt(3)
	v_pk_mul_f32 v[168:169], v[84:85], v[168:169]
	v_pk_mul_f32 v[166:167], v[82:83], v[166:167]
	s_waitcnt vmcnt(2)
	v_pk_mul_f32 v[170:171], v[74:75], v[170:171]
	s_waitcnt vmcnt(1)
	v_pk_fma_f32 v[168:169], v[168:169], v[176:177], v[184:185]
	v_pk_fma_f32 v[166:167], v[166:167], v[174:175], v[182:183]
	s_waitcnt vmcnt(0)
	v_pk_fma_f32 v[170:171], v[170:171], v[178:179], v[186:187]
	v_cvt_pk_bf16_f32 v166, v166, v167
	v_cvt_pk_bf16_f32 v167, v168, v169
	v_pk_mul_f32 v[172:173], v[76:77], v[172:173]
	v_cvt_pk_bf16_f32 v168, v170, v171
	v_add_u32_e32 v170, 0xffffe030, v148
	v_lshrrev_b32_e32 v170, 3, v170
	v_add_u32_e32 v170, 4, v170
	v_pk_fma_f32 v[172:173], v[172:173], v[180:181], v[188:189]
	v_cndmask_b32_e32 v165, v170, v165, vcc
	v_cvt_pk_bf16_f32 v169, v172, v173
	global_store_dwordx4 v[192:193], v[166:169], off offset:256
	v_mad_i64_i32 v[178:179], s[58:59], v165, s81, v[156:157]
	global_load_dwordx4 v[166:169], v[194:195], off
	global_load_dwordx4 v[170:173], v[152:153], off offset:16
	global_load_dwordx4 v[174:177], v[152:153], off
	v_lshl_add_u64 v[192:193], v[178:179], 0, v[154:155]
	global_load_dwordx4 v[178:181], v[192:193], off
	global_load_dwordx4 v[182:185], v[192:193], off offset:16
	global_load_dwordx4 v[186:189], v[194:195], off offset:256
	v_cmp_gt_i32_e32 vcc, s10, v148
	s_movk_i32 s10, 0x1f70
	s_waitcnt vmcnt(5)
	v_lshlrev_b32_e32 v194, 16, v166
	v_and_b32_e32 v195, 0xffff0000, v166
	v_lshlrev_b32_e32 v166, 16, v167
	v_and_b32_e32 v167, 0xffff0000, v167
	v_lshlrev_b32_e32 v196, 16, v168
	v_and_b32_e32 v197, 0xffff0000, v168
	v_lshlrev_b32_e32 v168, 16, v169
	v_and_b32_e32 v169, 0xffff0000, v169
	s_waitcnt vmcnt(3)
	v_pk_mul_f32 v[176:177], v[88:89], v[176:177]
	v_pk_mul_f32 v[174:175], v[86:87], v[174:175]
	v_pk_mul_f32 v[172:173], v[80:81], v[172:173]
	v_pk_mul_f32 v[170:171], v[78:79], v[170:171]
	s_waitcnt vmcnt(2)
	v_pk_fma_f32 v[176:177], v[176:177], v[180:181], v[166:167]
	v_pk_fma_f32 v[166:167], v[174:175], v[178:179], v[194:195]
	s_waitcnt vmcnt(1)
	v_pk_fma_f32 v[172:173], v[172:173], v[184:185], v[168:169]
	v_pk_fma_f32 v[168:169], v[170:171], v[182:183], v[196:197]
	v_cvt_pk_bf16_f32 v166, v166, v167
	v_cvt_pk_bf16_f32 v167, v176, v177
	v_add_u32_e32 v182, 0x80, v148
	v_cvt_pk_bf16_f32 v168, v168, v169
	v_cvt_pk_bf16_f32 v169, v172, v173
	global_store_dwordx4 v[190:191], v[166:169], off
	global_load_dwordx4 v[166:169], v[152:153], off offset:512
	s_nop 0
	global_load_dwordx4 v[170:173], v[152:153], off offset:528
	global_load_dwordx4 v[174:177], v[192:193], off offset:512
	global_load_dwordx4 v[178:181], v[192:193], off offset:528
	v_ashrrev_i32_e32 v183, 31, v182
	v_lshlrev_b64 v[184:185], 11, v[182:183]
	v_lshl_add_u64 v[184:185], v[184:185], 0, v[150:151]
	v_lshlrev_b64 v[192:193], 1, v[184:185]
	s_waitcnt vmcnt(5)
	v_lshlrev_b32_e32 v184, 16, v186
	v_and_b32_e32 v185, 0xffff0000, v186
	v_lshlrev_b32_e32 v186, 16, v187
	v_and_b32_e32 v187, 0xffff0000, v187
	v_lshlrev_b32_e32 v196, 16, v188
	v_and_b32_e32 v197, 0xffff0000, v188
	v_lshlrev_b32_e32 v188, 16, v189
	v_and_b32_e32 v189, 0xffff0000, v189
	v_ashrrev_i32_e32 v165, 11, v182
	v_lshl_add_u64 v[194:195], s[14:15], 0, v[192:193]
	v_lshl_add_u64 v[192:193], s[8:9], 0, v[192:193]
	s_waitcnt vmcnt(3)
	v_pk_mul_f32 v[168:169], v[72:73], v[168:169]
	v_pk_mul_f32 v[166:167], v[70:71], v[166:167]
	s_waitcnt vmcnt(2)
	v_pk_mul_f32 v[170:171], v[66:67], v[170:171]
	s_waitcnt vmcnt(1)
	v_pk_fma_f32 v[168:169], v[168:169], v[176:177], v[186:187]
	v_pk_fma_f32 v[166:167], v[166:167], v[174:175], v[184:185]
	s_waitcnt vmcnt(0)
	v_pk_fma_f32 v[170:171], v[170:171], v[178:179], v[196:197]
	v_cvt_pk_bf16_f32 v166, v166, v167
	v_cvt_pk_bf16_f32 v167, v168, v169
	v_pk_mul_f32 v[172:173], v[68:69], v[172:173]
	v_cvt_pk_bf16_f32 v168, v170, v171
	v_lshrrev_b32_e32 v170, 3, v198
	v_or_b32_e32 v170, 4, v170
	v_pk_fma_f32 v[172:173], v[172:173], v[180:181], v[188:189]
	v_cndmask_b32_e32 v178, v170, v165, vcc
	v_cvt_pk_bf16_f32 v169, v172, v173
	global_store_dwordx4 v[190:191], v[166:169], off offset:256
	v_mad_i64_i32 v[178:179], s[58:59], v178, s81, v[156:157]
	global_load_dwordx4 v[166:169], v[194:195], off
	global_load_dwordx4 v[170:173], v[152:153], off offset:16
	global_load_dwordx4 v[174:177], v[152:153], off
	v_lshl_add_u64 v[190:191], v[178:179], 0, v[154:155]
	global_load_dwordx4 v[178:181], v[190:191], off
	global_load_dwordx4 v[182:185], v[190:191], off offset:16
	global_load_dwordx4 v[186:189], v[194:195], off offset:256
	v_cmp_gt_i32_e32 vcc, s10, v148
	s_movk_i32 s10, 0x1f60
	s_waitcnt vmcnt(5)
	v_lshlrev_b32_e32 v194, 16, v166
	v_and_b32_e32 v195, 0xffff0000, v166
	v_lshlrev_b32_e32 v166, 16, v167
	v_and_b32_e32 v167, 0xffff0000, v167
	v_lshlrev_b32_e32 v196, 16, v168
	v_and_b32_e32 v197, 0xffff0000, v168
	v_lshlrev_b32_e32 v168, 16, v169
	v_and_b32_e32 v169, 0xffff0000, v169
	s_waitcnt vmcnt(3)
	v_pk_mul_f32 v[176:177], v[64:65], v[176:177]
	v_pk_mul_f32 v[174:175], v[62:63], v[174:175]
	v_pk_mul_f32 v[172:173], v[60:61], v[172:173]
	v_pk_mul_f32 v[170:171], v[58:59], v[170:171]
	s_waitcnt vmcnt(2)
	v_pk_fma_f32 v[176:177], v[176:177], v[180:181], v[166:167]
	v_pk_fma_f32 v[166:167], v[174:175], v[178:179], v[194:195]
	s_waitcnt vmcnt(1)
; __device__ __forceinline__ unsigned pk2(float lo, float hi) { unsigned r; asm("v_cvt_pk_bf16_f32 %0, %1, %2" : "=v"(r) : "v"(lo), "v"(hi)); return r; }
;     __device__ __forceinline__ void operator()(const f32x4 (&acc)[2][2][4][2], const Unit& u, int wr, int wc, int fr, int fq) const {
;     ...
;         for (int ai = 0; ai < 2; ++ai)
; #pragma unroll
;             for (int m = 0; m < 4; ++m) { const int r = row0 + ai * HALF + m * 16; const size_t off = (size_t)r * mk::D + col0; const float* gp = gate + (size_t)mk::seq_of(r) * mk::NMOD + col0;
;                 float ss = 0.f;
; #pragma unroll
;                 for (int bj = 0; bj < 2; ++bj) { const int o = bj * HALF;
;                     f32x4 x0, x1;
;                     if constexpr (XIF32) { x0 = *(const f32x4*)((const float*)xi + off + o); x1 = *(const f32x4*)((const float*)xi + off + o + 4); }
;                     else { const u32x4 w = *(const u32x4*)((const bf16*)xi + off + o);
;                         x0 = (f32x4){__uint_as_float(w.x << 16), __uint_as_float(w.x & 0xffff0000u), __uint_as_float(w.y << 16), __uint_as_float(w.y & 0xffff0000u)};
;                         x1 = (f32x4){__uint_as_float(w.z << 16), __uint_as_float(w.z & 0xffff0000u), __uint_as_float(w.w << 16), __uint_as_float(w.w & 0xffff0000u)}; }
;                     f32x4 v0 = acc[ai][bj][m][0] * ascale, v1 = acc[ai][bj][m][1] * ascale;
;                     if constexpr (MODE == 1) { v0 *= *(const f32x4*)(extra + col0 + o); v1 *= *(const f32x4*)(extra + col0 + o + 4); }
;                     const f32x4 y0 = x0 + *(const f32x4*)(gp + o) * v0, y1 = x1 + *(const f32x4*)(gp + o + 4) * v1;
;                     u32x4 w; w.x = mk::pk2(y0[0], y0[1]); w.y = mk::pk2(y0[2], y0[3]); w.z = mk::pk2(y1[0], y1[1]); w.w = mk::pk2(y1[2], y1[3]); *(u32x4*)(xo + off + o) = w;
	v_pk_fma_f32 v[172:173], v[172:173], v[184:185], v[168:169]
	v_pk_fma_f32 v[168:169], v[170:171], v[182:183], v[196:197]
	v_cvt_pk_bf16_f32 v166, v166, v167
	v_cvt_pk_bf16_f32 v167, v176, v177
	s_waitcnt vmcnt(0)
	v_lshlrev_b32_e32 v182, 16, v186
	v_cvt_pk_bf16_f32 v168, v168, v169
	v_cvt_pk_bf16_f32 v169, v172, v173
	global_store_dwordx4 v[192:193], v[166:169], off
	global_load_dwordx4 v[166:169], v[152:153], off offset:512
	s_nop 0
	global_load_dwordx4 v[170:173], v[152:153], off offset:528
	global_load_dwordx4 v[174:177], v[190:191], off offset:512
	global_load_dwordx4 v[178:181], v[190:191], off offset:528
	v_and_b32_e32 v183, 0xffff0000, v186
	v_lshlrev_b32_e32 v184, 16, v187
	v_and_b32_e32 v185, 0xffff0000, v187
	v_lshlrev_b32_e32 v186, 16, v188
	v_and_b32_e32 v187, 0xffff0000, v188
	v_lshlrev_b32_e32 v188, 16, v189
	v_and_b32_e32 v189, 0xffff0000, v189
	v_lshl_add_u64 v[190:191], v[158:159], 0, s[22:23]
	v_lshl_add_u64 v[194:195], s[14:15], 0, v[190:191]
	v_lshl_add_u64 v[190:191], s[8:9], 0, v[190:191]
	s_waitcnt vmcnt(3)
	v_pk_mul_f32 v[168:169], v[52:53], v[168:169]
	v_pk_mul_f32 v[166:167], v[50:51], v[166:167]
	s_waitcnt vmcnt(2)
	v_pk_mul_f32 v[170:171], v[42:43], v[170:171]
	s_waitcnt vmcnt(1)
	v_pk_fma_f32 v[168:169], v[168:169], v[176:177], v[184:185]
	v_pk_fma_f32 v[166:167], v[166:167], v[174:175], v[182:183]
	s_waitcnt vmcnt(0)
	v_pk_fma_f32 v[170:171], v[170:171], v[178:179], v[186:187]
	v_cvt_pk_bf16_f32 v166, v166, v167
	v_cvt_pk_bf16_f32 v167, v168, v169
	v_pk_mul_f32 v[172:173], v[44:45], v[172:173]
	v_cvt_pk_bf16_f32 v168, v170, v171
	v_add_u32_e32 v170, 0xffffe090, v148
	v_lshrrev_b32_e32 v170, 3, v170
	v_or_b32_e32 v170, 4, v170
	v_pk_fma_f32 v[172:173], v[172:173], v[180:181], v[188:189]
	v_cndmask_b32_e32 v178, v170, v165, vcc
	v_cvt_pk_bf16_f32 v169, v172, v173
	global_store_dwordx4 v[192:193], v[166:169], off offset:256
	v_mad_i64_i32 v[178:179], s[58:59], v178, s81, v[156:157]
	global_load_dwordx4 v[166:169], v[194:195], off
	global_load_dwordx4 v[170:173], v[152:153], off offset:16
	global_load_dwordx4 v[174:177], v[152:153], off
	v_lshl_add_u64 v[192:193], v[178:179], 0, v[154:155]
	global_load_dwordx4 v[178:181], v[192:193], off
	global_load_dwordx4 v[182:185], v[192:193], off offset:16
	global_load_dwordx4 v[186:189], v[194:195], off offset:256
	v_cmp_gt_i32_e32 vcc, s10, v148
	s_movk_i32 s10, 0x1f50
	s_waitcnt vmcnt(5)
	v_lshlrev_b32_e32 v194, 16, v166
	v_and_b32_e32 v195, 0xffff0000, v166
	v_lshlrev_b32_e32 v166, 16, v167
	v_and_b32_e32 v167, 0xffff0000, v167
	v_lshlrev_b32_e32 v196, 16, v168
	v_and_b32_e32 v197, 0xffff0000, v168
	v_lshlrev_b32_e32 v168, 16, v169
	v_and_b32_e32 v169, 0xffff0000, v169
	s_waitcnt vmcnt(3)
	v_pk_mul_f32 v[176:177], v[56:57], v[176:177]
	v_pk_mul_f32 v[174:175], v[54:55], v[174:175]
	v_pk_mul_f32 v[172:173], v[48:49], v[172:173]
	v_pk_mul_f32 v[170:171], v[46:47], v[170:171]
	s_waitcnt vmcnt(2)
	v_pk_fma_f32 v[176:177], v[176:177], v[180:181], v[166:167]
	v_pk_fma_f32 v[166:167], v[174:175], v[178:179], v[194:195]
	s_waitcnt vmcnt(1)
	v_pk_fma_f32 v[172:173], v[172:173], v[184:185], v[168:169]
	v_pk_fma_f32 v[168:169], v[170:171], v[182:183], v[196:197]
	v_cvt_pk_bf16_f32 v166, v166, v167
	v_cvt_pk_bf16_f32 v167, v176, v177
	s_waitcnt vmcnt(0)
	v_lshlrev_b32_e32 v182, 16, v186
	v_cvt_pk_bf16_f32 v168, v168, v169
	v_cvt_pk_bf16_f32 v169, v172, v173
	global_store_dwordx4 v[190:191], v[166:169], off
	global_load_dwordx4 v[166:169], v[152:153], off offset:512
	s_nop 0
	global_load_dwordx4 v[170:173], v[152:153], off offset:528
	global_load_dwordx4 v[174:177], v[192:193], off offset:512
	global_load_dwordx4 v[178:181], v[192:193], off offset:528
	v_and_b32_e32 v183, 0xffff0000, v186
	v_lshlrev_b32_e32 v184, 16, v187
	v_and_b32_e32 v185, 0xffff0000, v187
	v_lshlrev_b32_e32 v186, 16, v188
	v_and_b32_e32 v187, 0xffff0000, v188
	v_lshlrev_b32_e32 v188, 16, v189
	v_and_b32_e32 v189, 0xffff0000, v189
	v_lshl_add_u64 v[192:193], v[158:159], 0, s[96:97]
	v_lshl_add_u64 v[194:195], s[14:15], 0, v[192:193]
	v_lshl_add_u64 v[192:193], s[8:9], 0, v[192:193]
	v_lshl_add_u64 v[158:159], v[158:159], 0, s[34:35]
	s_waitcnt vmcnt(3)
	v_pk_mul_f32 v[168:169], v[36:37], v[168:169]
	v_pk_mul_f32 v[166:167], v[34:35], v[166:167]
	s_waitcnt vmcnt(2)
	v_pk_mul_f32 v[170:171], v[26:27], v[170:171]
	s_waitcnt vmcnt(1)
	v_pk_fma_f32 v[168:169], v[168:169], v[176:177], v[184:185]
	v_pk_fma_f32 v[166:167], v[166:167], v[174:175], v[182:183]
	s_waitcnt vmcnt(0)
	v_pk_fma_f32 v[170:171], v[170:171], v[178:179], v[186:187]
	v_cvt_pk_bf16_f32 v166, v166, v167
	v_cvt_pk_bf16_f32 v167, v168, v169
	v_pk_mul_f32 v[172:173], v[28:29], v[172:173]
	v_cvt_pk_bf16_f32 v168, v170, v171
	v_add_u32_e32 v170, 0xffffe0a0, v148
	v_lshrrev_b32_e32 v170, 3, v170
	v_add_u32_e32 v170, 4, v170
	v_pk_fma_f32 v[172:173], v[172:173], v[180:181], v[188:189]
	v_cndmask_b32_e32 v178, v170, v165, vcc
	v_cvt_pk_bf16_f32 v169, v172, v173
	global_store_dwordx4 v[190:191], v[166:169], off offset:256
	v_mad_i64_i32 v[178:179], s[58:59], v178, s81, v[156:157]
	global_load_dwordx4 v[166:169], v[194:195], off
	global_load_dwordx4 v[170:173], v[152:153], off offset:16
	global_load_dwordx4 v[174:177], v[152:153], off
	v_lshl_add_u64 v[190:191], v[178:179], 0, v[154:155]
	global_load_dwordx4 v[178:181], v[190:191], off
	global_load_dwordx4 v[182:185], v[190:191], off offset:16
	global_load_dwordx4 v[186:189], v[194:195], off offset:256
	v_cmp_gt_i32_e32 vcc, s10, v148
	s_waitcnt vmcnt(5)
; __device__ __forceinline__ unsigned pk2(float lo, float hi) { unsigned r; asm("v_cvt_pk_bf16_f32 %0, %1, %2" : "=v"(r) : "v"(lo), "v"(hi)); return r; }
;     __device__ __forceinline__ void operator()(const f32x4 (&acc)[2][2][4][2], const Unit& u, int wr, int wc, int fr, int fq) const {
;     ...
;         for (int ai = 0; ai < 2; ++ai)
; #pragma unroll
;             for (int m = 0; m < 4; ++m) { const int r = row0 + ai * HALF + m * 16; const size_t off = (size_t)r * mk::D + col0; const float* gp = gate + (size_t)mk::seq_of(r) * mk::NMOD + col0;
;                 float ss = 0.f;
; #pragma unroll
;                 for (int bj = 0; bj < 2; ++bj) { const int o = bj * HALF;
;                     f32x4 x0, x1;
;                     if constexpr (XIF32) { x0 = *(const f32x4*)((const float*)xi + off + o); x1 = *(const f32x4*)((const float*)xi + off + o + 4); }
;                     else { const u32x4 w = *(const u32x4*)((const bf16*)xi + off + o);
;                         x0 = (f32x4){__uint_as_float(w.x << 16), __uint_as_float(w.x & 0xffff0000u), __uint_as_float(w.y << 16), __uint_as_float(w.y & 0xffff0000u)};
;                         x1 = (f32x4){__uint_as_float(w.z << 16), __uint_as_float(w.z & 0xffff0000u), __uint_as_float(w.w << 16), __uint_as_float(w.w & 0xffff0000u)}; }
;                     f32x4 v0 = acc[ai][bj][m][0] * ascale, v1 = acc[ai][bj][m][1] * ascale;
;                     if constexpr (MODE == 1) { v0 *= *(const f32x4*)(extra + col0 + o); v1 *= *(const f32x4*)(extra + col0 + o + 4); }
;                     const f32x4 y0 = x0 + *(const f32x4*)(gp + o) * v0, y1 = x1 + *(const f32x4*)(gp + o + 4) * v1;
;                     u32x4 w; w.x = mk::pk2(y0[0], y0[1]); w.y = mk::pk2(y0[2], y0[3]); w.z = mk::pk2(y1[0], y1[1]); w.w = mk::pk2(y1[2], y1[3]); *(u32x4*)(xo + off + o) = w;
	v_lshlrev_b32_e32 v194, 16, v166
	v_and_b32_e32 v195, 0xffff0000, v166
	v_lshlrev_b32_e32 v166, 16, v167
	v_and_b32_e32 v167, 0xffff0000, v167
	v_lshlrev_b32_e32 v196, 16, v168
	v_and_b32_e32 v197, 0xffff0000, v168
	v_lshlrev_b32_e32 v168, 16, v169
	v_and_b32_e32 v169, 0xffff0000, v169
	s_waitcnt vmcnt(3)
	v_pk_mul_f32 v[176:177], v[40:41], v[176:177]
	v_pk_mul_f32 v[174:175], v[38:39], v[174:175]
	v_pk_mul_f32 v[172:173], v[32:33], v[172:173]
	v_pk_mul_f32 v[170:171], v[30:31], v[170:171]
	s_waitcnt vmcnt(2)
	v_pk_fma_f32 v[176:177], v[176:177], v[180:181], v[166:167]
	v_pk_fma_f32 v[166:167], v[174:175], v[178:179], v[194:195]
	s_waitcnt vmcnt(1)
	v_pk_fma_f32 v[172:173], v[172:173], v[184:185], v[168:169]
	v_pk_fma_f32 v[168:169], v[170:171], v[182:183], v[196:197]
	v_cvt_pk_bf16_f32 v166, v166, v167
	v_cvt_pk_bf16_f32 v167, v176, v177
	s_waitcnt vmcnt(0)
	v_lshlrev_b32_e32 v184, 16, v186
	v_cvt_pk_bf16_f32 v168, v168, v169
	v_cvt_pk_bf16_f32 v169, v172, v173
	global_store_dwordx4 v[192:193], v[166:169], off
	global_load_dwordx4 v[166:169], v[152:153], off offset:512
	s_nop 0
	global_load_dwordx4 v[170:173], v[152:153], off offset:528
	global_load_dwordx4 v[174:177], v[190:191], off offset:512
	global_load_dwordx4 v[178:181], v[190:191], off offset:528
	v_and_b32_e32 v185, 0xffff0000, v186
	v_lshlrev_b32_e32 v186, 16, v187
	v_and_b32_e32 v187, 0xffff0000, v187
	v_lshlrev_b32_e32 v190, 16, v188
	v_and_b32_e32 v191, 0xffff0000, v188
	v_lshlrev_b32_e32 v188, 16, v189
	v_and_b32_e32 v189, 0xffff0000, v189
	v_lshl_add_u64 v[182:183], s[14:15], 0, v[158:159]
	v_lshl_add_u64 v[158:159], s[8:9], 0, v[158:159]
	s_waitcnt vmcnt(3)
	v_pk_mul_f32 v[168:169], v[20:21], v[168:169]
	v_pk_mul_f32 v[166:167], v[18:19], v[166:167]
	s_waitcnt vmcnt(2)
	v_pk_mul_f32 v[170:171], v[10:11], v[170:171]
	s_waitcnt vmcnt(1)
	v_pk_fma_f32 v[168:169], v[168:169], v[176:177], v[186:187]
	v_pk_fma_f32 v[166:167], v[166:167], v[174:175], v[184:185]
	s_waitcnt vmcnt(0)
	v_pk_fma_f32 v[170:171], v[170:171], v[178:179], v[190:191]
	v_cvt_pk_bf16_f32 v166, v166, v167
	v_cvt_pk_bf16_f32 v167, v168, v169
	v_pk_mul_f32 v[172:173], v[12:13], v[172:173]
	v_cvt_pk_bf16_f32 v168, v170, v171
	v_add_u32_e32 v170, 0xffffe0b0, v148
	v_lshrrev_b32_e32 v170, 3, v170
	v_pk_fma_f32 v[172:173], v[172:173], v[180:181], v[188:189]
	v_add_u32_e32 v170, 4, v170
	v_cvt_pk_bf16_f32 v169, v172, v173
	global_store_dwordx4 v[192:193], v[166:169], off offset:256
	v_cndmask_b32_e32 v165, v170, v165, vcc
	global_load_dwordx4 v[166:169], v[182:183], off
	global_load_dwordx4 v[170:173], v[152:153], off offset:16
	global_load_dwordx4 v[174:177], v[152:153], off
	v_mad_i64_i32 v[156:157], s[58:59], v165, s81, v[156:157]
	v_lshl_add_u64 v[186:187], v[156:157], 0, v[154:155]
	global_load_dwordx4 v[154:157], v[186:187], off
	global_load_dwordx4 v[178:181], v[186:187], off offset:16
	s_nop 0
	global_load_dwordx4 v[182:185], v[182:183], off offset:256
	s_waitcnt vmcnt(5)
	v_lshlrev_b32_e32 v188, 16, v166
	v_and_b32_e32 v189, 0xffff0000, v166
	v_lshlrev_b32_e32 v166, 16, v167
	v_and_b32_e32 v167, 0xffff0000, v167
	s_waitcnt vmcnt(3)
	v_pk_mul_f32 v[176:177], v[24:25], v[176:177]
	v_pk_mul_f32 v[174:175], v[22:23], v[174:175]
	v_lshlrev_b32_e32 v190, 16, v168
	v_and_b32_e32 v191, 0xffff0000, v168
	v_lshlrev_b32_e32 v168, 16, v169
	v_and_b32_e32 v169, 0xffff0000, v169
	v_pk_mul_f32 v[172:173], v[16:17], v[172:173]
	v_pk_mul_f32 v[170:171], v[14:15], v[170:171]
	s_waitcnt vmcnt(2)
	v_pk_fma_f32 v[156:157], v[176:177], v[156:157], v[166:167]
	v_pk_fma_f32 v[154:155], v[174:175], v[154:155], v[188:189]
	s_waitcnt vmcnt(1)
	v_pk_fma_f32 v[166:167], v[172:173], v[180:181], v[168:169]
	v_pk_fma_f32 v[168:169], v[170:171], v[178:179], v[190:191]
	v_cvt_pk_bf16_f32 v154, v154, v155
	v_cvt_pk_bf16_f32 v155, v156, v157
	v_cvt_pk_bf16_f32 v157, v166, v167
	s_waitcnt vmcnt(0)
	v_lshlrev_b32_e32 v180, 16, v184
	v_cvt_pk_bf16_f32 v156, v168, v169
	global_store_dwordx4 v[158:159], v[154:157], off
	global_load_dwordx4 v[154:157], v[152:153], off offset:512
	s_nop 0
	global_load_dwordx4 v[166:169], v[152:153], off offset:528
	global_load_dwordx4 v[170:173], v[186:187], off offset:512
	global_load_dwordx4 v[174:177], v[186:187], off offset:528
	v_lshlrev_b32_e32 v152, 16, v182
	v_and_b32_e32 v153, 0xffff0000, v182
	v_and_b32_e32 v181, 0xffff0000, v184
	v_lshlrev_b32_e32 v178, 16, v183
	v_and_b32_e32 v179, 0xffff0000, v183
	v_lshlrev_b32_e32 v182, 16, v185
	v_and_b32_e32 v183, 0xffff0000, v185
	s_waitcnt vmcnt(3)
	v_pk_mul_f32 v[154:155], v[6:7], v[154:155]
	s_waitcnt vmcnt(2)
	v_pk_mul_f32 v[166:167], v[2:3], v[166:167]
	v_pk_mul_f32 v[156:157], v[8:9], v[156:157]
	v_pk_mul_f32 v[168:169], v[4:5], v[168:169]
	s_waitcnt vmcnt(1)
	v_pk_fma_f32 v[152:153], v[154:155], v[170:171], v[152:153]
	s_waitcnt vmcnt(0)
	v_pk_fma_f32 v[154:155], v[166:167], v[174:175], v[180:181]
	v_pk_fma_f32 v[156:157], v[156:157], v[172:173], v[178:179]
	v_pk_fma_f32 v[168:169], v[168:169], v[176:177], v[182:183]
	v_cvt_pk_bf16_f32 v152, v152, v153
	v_cvt_pk_bf16_f32 v153, v156, v157
	v_cvt_pk_bf16_f32 v154, v154, v155
	s_nop 0
	v_cvt_pk_bf16_f32 v155, v168, v169
	global_store_dwordx4 v[158:159], v[152:155], off offset:256
	s_cbranch_execz .LBB0_1682

;     __device__ __forceinline__ void operator()(const f32x4 (&acc)[2][2][4][2], const Unit& u, int wr, int wc, int fr, int fq) const {
;         const int row0 = u.pm * BM + wr * 64 + fr, col0 = u.pn * BM + wc * 32 + 8 * fq;
;         if (u.part >= 0) {
;             bf16* sp = slab + ((ptrdiff_t)u.part * mk::MS - mk::MP) * (ptrdiff_t)mk::D + col0;
; #pragma unroll
;             for (int ai = 0; ai < 2; ++ai)
; #pragma unroll
;                 for (int m = 0; m < 4; ++m) { bf16* rowp = sp + (ptrdiff_t)(row0 + ai * HALF + m * 16) * mk::D;
; #pragma unroll
;                     for (int bj = 0; bj < 2; ++bj) { const f32x4 v0 = acc[ai][bj][m][0] * ascale, v1 = acc[ai][bj][m][1] * ascale;
;                         u32x4 w; w.x = mk::pk2(v0[0], v0[1]); w.y = mk::pk2(v0[2], v0[3]); w.z = mk::pk2(v1[0], v1[1]); w.w = mk::pk2(v1[2], v1[3]); *(u32x4*)(rowp + bj * HALF) = w; } }
;             return;
;         }
; #pragma unroll
;         for (int ai = 0; ai < 2; ++ai)
; #pragma unroll
;             for (int m = 0; m < 4; ++m) { const int r = row0 + ai * HALF + m * 16; const size_t off = (size_t)r * mk::D + col0; const float* gp = gate + (size_t)mk::seq_of(r) * mk::NMOD + col0;
;                 float ss = 0.f;
; #pragma unroll
;                 for (int bj = 0; bj < 2; ++bj) { const int o = bj * HALF;
;                     f32x4 x0, x1;
;                     if constexpr (XIF32) { x0 = *(const f32x4*)((const float*)xi + off + o); x1 = *(const f32x4*)((const float*)xi + off + o + 4); }
;                     else { const u32x4 w = *(const u32x4*)((const bf16*)xi + off + o);
;                         x0 = (f32x4){__uint_as_float(w.x << 16), __uint_as_float(w.x & 0xffff0000u), __uint_as_float(w.y << 16), __uint_as_float(w.y & 0xffff0000u)};
;                         x1 = (f32x4){__uint_as_float(w.z << 16), __uint_as_float(w.z & 0xffff0000u), __uint_as_float(w.w << 16), __uint_as_float(w.w & 0xffff0000u)}; }
;                     f32x4 v0 = acc[ai][bj][m][0] * ascale, v1 = acc[ai][bj][m][1] * ascale;
;                     if constexpr (MODE == 1) { v0 *= *(const f32x4*)(extra + col0 + o); v1 *= *(const f32x4*)(extra + col0 + o + 4); }
;                     const f32x4 y0 = x0 + *(const f32x4*)(gp + o) * v0, y1 = x1 + *(const f32x4*)(gp + o + 4) * v1;
.LBB0_2015:
	s_lshl_b32 s10, s68, 8
	s_add_i32 s10, s10, s65
	s_nop 15
	s_nop 15
	v_or_b32_e32 v8, s10, v1
	v_lshl_or_b32 v10, s69, 8, v183
	v_or_b32_e32 v6, 16, v8
	v_or_b32_e32 v4, 32, v8
	v_or_b32_e32 v2, 48, v8
	s_mov_b64 s[52:53], -1
	s_cmp_gt_i32 s12, -1
	v_ashrrev_i32_e32 v11, 31, v10
	v_ashrrev_i32_e32 v9, 31, v8
	v_ashrrev_i32_e32 v7, 31, v6
	v_ashrrev_i32_e32 v5, 31, v4
	v_ashrrev_i32_e32 v3, 31, v2
	s_cbranch_scc1 .LBB0_2018
	v_lshl_add_u32 v12, v8, 11, v10
	v_lshlrev_b32_e32 v12, 1, v12
	global_load_dword v28, v12, s[8:9]
	global_load_dword v28, v12, s[8:9] offset:256
	v_add_u32_e32 v13, 0x10000, v12
	global_load_dword v28, v13, s[8:9]
	global_load_dword v28, v13, s[8:9] offset:256
	v_add_u32_e32 v13, 0x20000, v12
	global_load_dword v28, v13, s[8:9]
	global_load_dword v28, v13, s[8:9] offset:256
	v_add_u32_e32 v13, 0x30000, v12
	global_load_dword v28, v13, s[8:9]
	global_load_dword v28, v13, s[8:9] offset:256
	v_add_u32_e32 v13, 0x80000, v12
	global_load_dword v28, v13, s[8:9]
	global_load_dword v28, v13, s[8:9] offset:256
	v_add_u32_e32 v13, 0x90000, v12
	global_load_dword v28, v13, s[8:9]
	global_load_dword v28, v13, s[8:9] offset:256
	v_add_u32_e32 v13, 0xa0000, v12
	global_load_dword v28, v13, s[8:9]
	global_load_dword v28, v13, s[8:9] offset:256
	v_add_u32_e32 v13, 0xb0000, v12
	global_load_dword v28, v13, s[8:9]
	global_load_dword v28, v13, s[8:9] offset:256
	s_nop 0
	s_nop 0
	s_nop 0
	s_nop 0
	s_nop 0
	s_nop 0
	s_nop 0
	s_nop 0
	s_nop 0
	s_nop 0
	s_nop 0
	s_nop 0
	s_nop 0
	s_nop 0
	s_nop 0
	v_add_u32_e32 v14, 0xffffe000, v8
	s_ashr_i32 s10, s10, 11
	v_lshlrev_b64 v[12:13], 11, v[8:9]
	v_lshrrev_b32_e32 v14, 3, v14
	v_lshl_add_u64 v[12:13], v[12:13], 0, v[10:11]
	v_or_b32_e32 v14, 4, v14
	v_mov_b32_e32 v18, s10
	v_cmp_gt_i32_e32 vcc, s64, v8
	v_lshlrev_b64 v[16:17], 1, v[12:13]
	v_mov_b64_e32 v[12:13], s[20:21]
	v_cndmask_b32_e32 v14, v14, v18, vcc
	v_lshl_add_u64 v[32:33], s[8:9], 0, v[16:17]
	v_mad_i64_i32 v[24:25], s[52:53], v14, s74, v[12:13]
	v_lshlrev_b64 v[14:15], 2, v[10:11]
	global_load_dwordx4 v[20:23], v[32:33], off
	v_lshl_add_u64 v[178:179], v[24:25], 0, v[14:15]
	global_load_dwordx4 v[24:27], v[178:179], off
	global_load_dwordx4 v[28:31], v[178:179], off offset:16
	v_pk_mul_f32 v[180:181], v[160:161], s[38:39] op_sel_hi:[1,0]
	v_pk_mul_f32 v[188:189], v[158:159], s[38:39] op_sel_hi:[1,0]
	v_pk_mul_f32 v[190:191], v[156:157], s[38:39] op_sel_hi:[1,0]
	v_pk_mul_f32 v[192:193], v[154:155], s[38:39] op_sel_hi:[1,0]
	global_load_dwordx4 v[174:177], v[32:33], off offset:256
	v_lshl_add_u64 v[194:195], s[14:15], 0, v[16:17]
	v_add_u32_e32 v19, 0xffffe010, v8
	v_lshrrev_b32_e32 v19, 3, v19
	v_or_b32_e32 v19, 4, v19
	v_cmp_gt_i32_e32 vcc, s64, v6
	s_movk_i32 s10, 0x1f80
	s_waitcnt vmcnt(0)
	v_lshlrev_b32_e32 v32, 16, v20
	v_and_b32_e32 v33, 0xffff0000, v20
	v_lshlrev_b32_e32 v20, 16, v21
	v_and_b32_e32 v21, 0xffff0000, v21
	v_lshlrev_b32_e32 v196, 16, v22
	v_and_b32_e32 v197, 0xffff0000, v22
	v_lshlrev_b32_e32 v22, 16, v23
	v_and_b32_e32 v23, 0xffff0000, v23
	v_pk_fma_f32 v[26:27], v[180:181], v[26:27], v[20:21]
	v_pk_fma_f32 v[20:21], v[188:189], v[24:25], v[32:33]
	v_pk_fma_f32 v[24:25], v[190:191], v[30:31], v[22:23]
	v_pk_fma_f32 v[22:23], v[192:193], v[28:29], v[196:197]
	v_cvt_pk_bf16_f32 v20, v20, v21
	v_cvt_pk_bf16_f32 v21, v26, v27
	v_pk_mul_f32 v[28:29], v[152:153], s[38:39] op_sel_hi:[1,0]
	v_cvt_pk_bf16_f32 v22, v22, v23
	v_cvt_pk_bf16_f32 v23, v24, v25
	global_store_dwordx4 v[194:195], v[20:23], off
	global_load_dwordx4 v[20:23], v[178:179], off offset:512
	s_nop 0
	global_load_dwordx4 v[24:27], v[178:179], off offset:528
	v_pk_mul_f32 v[30:31], v[150:151], s[38:39] op_sel_hi:[1,0]
	v_lshlrev_b64 v[180:181], 11, v[6:7]
	v_lshlrev_b32_e32 v190, 16, v174
	v_and_b32_e32 v191, 0xffff0000, v174
	v_lshlrev_b32_e32 v174, 16, v175
	v_and_b32_e32 v175, 0xffff0000, v175
	v_pk_mul_f32 v[32:33], v[144:145], s[38:39] op_sel_hi:[1,0]
	v_pk_mul_f32 v[178:179], v[142:143], s[38:39] op_sel_hi:[1,0]
	v_lshl_add_u64 v[180:181], v[180:181], 0, v[10:11]
	v_lshlrev_b32_e32 v192, 16, v176
	v_and_b32_e32 v193, 0xffff0000, v176
	v_lshlrev_b32_e32 v176, 16, v177
	v_and_b32_e32 v177, 0xffff0000, v177
	v_lshlrev_b64 v[180:181], 1, v[180:181]
	v_cndmask_b32_e32 v19, v19, v18, vcc
	v_lshl_add_u64 v[188:189], s[8:9], 0, v[180:181]
	v_lshl_add_u64 v[180:181], s[14:15], 0, v[180:181]
	v_cmp_gt_i32_e32 vcc, s64, v4
	s_waitcnt vmcnt(1)
	v_pk_fma_f32 v[22:23], v[28:29], v[22:23], v[174:175]
	v_pk_fma_f32 v[20:21], v[30:31], v[20:21], v[190:191]
	s_waitcnt vmcnt(0)
	v_pk_fma_f32 v[26:27], v[32:33], v[26:27], v[176:177]
	v_pk_fma_f32 v[24:25], v[178:179], v[24:25], v[192:193]
	v_cvt_pk_bf16_f32 v20, v20, v21
	v_cvt_pk_bf16_f32 v21, v22, v23
	v_cvt_pk_bf16_f32 v23, v26, v27
	v_pk_mul_f32 v[178:179], v[148:149], s[38:39] op_sel_hi:[1,0]
	v_cvt_pk_bf16_f32 v22, v24, v25
	global_store_dwordx4 v[194:195], v[20:23], off offset:256
	v_mad_i64_i32 v[24:25], s[52:53], v19, s74, v[12:13]
	global_load_dwordx4 v[20:23], v[188:189], off
	v_lshl_add_u64 v[32:33], v[24:25], 0, v[14:15]
	global_load_dwordx4 v[24:27], v[32:33], off
	global_load_dwordx4 v[28:31], v[32:33], off offset:16
	v_pk_mul_f32 v[190:191], v[146:147], s[38:39] op_sel_hi:[1,0]
	v_pk_mul_f32 v[192:193], v[140:141], s[38:39] op_sel_hi:[1,0]
	v_pk_mul_f32 v[194:195], v[138:139], s[38:39] op_sel_hi:[1,0]
	global_load_dwordx4 v[174:177], v[188:189], off offset:256
	v_add_u32_e32 v19, 0xffffe020, v8
	v_lshrrev_b32_e32 v19, 3, v19
	v_add_u32_e32 v19, 4, v19
	v_cndmask_b32_e32 v19, v19, v18, vcc
	v_cmp_gt_i32_e32 vcc, s64, v2
	s_waitcnt vmcnt(3)
; __device__ __forceinline__ unsigned pk2(float lo, float hi) { unsigned r; asm("v_cvt_pk_bf16_f32 %0, %1, %2" : "=v"(r) : "v"(lo), "v"(hi)); return r; }
;     __device__ __forceinline__ void operator()(const f32x4 (&acc)[2][2][4][2], const Unit& u, int wr, int wc, int fr, int fq) const {
;     ...
;         for (int ai = 0; ai < 2; ++ai)
; #pragma unroll
;             for (int m = 0; m < 4; ++m) { const int r = row0 + ai * HALF + m * 16; const size_t off = (size_t)r * mk::D + col0; const float* gp = gate + (size_t)mk::seq_of(r) * mk::NMOD + col0;
;                 float ss = 0.f;
; #pragma unroll
;                 for (int bj = 0; bj < 2; ++bj) { const int o = bj * HALF;
;                     f32x4 x0, x1;
;                     if constexpr (XIF32) { x0 = *(const f32x4*)((const float*)xi + off + o); x1 = *(const f32x4*)((const float*)xi + off + o + 4); }
;                     else { const u32x4 w = *(const u32x4*)((const bf16*)xi + off + o);
;                         x0 = (f32x4){__uint_as_float(w.x << 16), __uint_as_float(w.x & 0xffff0000u), __uint_as_float(w.y << 16), __uint_as_float(w.y & 0xffff0000u)};
;                         x1 = (f32x4){__uint_as_float(w.z << 16), __uint_as_float(w.z & 0xffff0000u), __uint_as_float(w.w << 16), __uint_as_float(w.w & 0xffff0000u)}; }
;                     f32x4 v0 = acc[ai][bj][m][0] * ascale, v1 = acc[ai][bj][m][1] * ascale;
;                     if constexpr (MODE == 1) { v0 *= *(const f32x4*)(extra + col0 + o); v1 *= *(const f32x4*)(extra + col0 + o + 4); }
;                     const f32x4 y0 = x0 + *(const f32x4*)(gp + o) * v0, y1 = x1 + *(const f32x4*)(gp + o + 4) * v1;
;                     u32x4 w; w.x = mk::pk2(y0[0], y0[1]); w.y = mk::pk2(y0[2], y0[3]); w.z = mk::pk2(y1[0], y1[1]); w.w = mk::pk2(y1[2], y1[3]); *(u32x4*)(xo + off + o) = w;
	v_lshlrev_b32_e32 v188, 16, v20
	v_and_b32_e32 v189, 0xffff0000, v20
	v_lshlrev_b32_e32 v20, 16, v21
	v_and_b32_e32 v21, 0xffff0000, v21
	v_lshlrev_b32_e32 v196, 16, v22
	v_and_b32_e32 v197, 0xffff0000, v22
	v_lshlrev_b32_e32 v22, 16, v23
	v_and_b32_e32 v23, 0xffff0000, v23
	s_waitcnt vmcnt(2)
	v_pk_fma_f32 v[26:27], v[178:179], v[26:27], v[20:21]
	v_pk_fma_f32 v[20:21], v[190:191], v[24:25], v[188:189]
	s_waitcnt vmcnt(1)
	v_pk_fma_f32 v[24:25], v[192:193], v[30:31], v[22:23]
	v_pk_fma_f32 v[22:23], v[194:195], v[28:29], v[196:197]
	v_cvt_pk_bf16_f32 v20, v20, v21
	v_cvt_pk_bf16_f32 v21, v26, v27
	v_pk_mul_f32 v[28:29], v[136:137], s[38:39] op_sel_hi:[1,0]
	v_cvt_pk_bf16_f32 v22, v22, v23
	v_cvt_pk_bf16_f32 v23, v24, v25
	global_store_dwordx4 v[180:181], v[20:23], off
	global_load_dwordx4 v[20:23], v[32:33], off offset:512
	s_nop 0
	global_load_dwordx4 v[24:27], v[32:33], off offset:528
	v_pk_mul_f32 v[30:31], v[134:135], s[38:39] op_sel_hi:[1,0]
	v_lshlrev_b64 v[188:189], 11, v[4:5]
	s_waitcnt vmcnt(3)
	v_lshlrev_b32_e32 v192, 16, v174
	v_and_b32_e32 v193, 0xffff0000, v174
	v_lshlrev_b32_e32 v174, 16, v175
	v_and_b32_e32 v175, 0xffff0000, v175
	v_pk_mul_f32 v[32:33], v[128:129], s[38:39] op_sel_hi:[1,0]
	v_pk_mul_f32 v[178:179], v[126:127], s[38:39] op_sel_hi:[1,0]
	v_lshl_add_u64 v[188:189], v[188:189], 0, v[10:11]
	v_lshlrev_b32_e32 v194, 16, v176
	v_and_b32_e32 v195, 0xffff0000, v176
	v_lshlrev_b32_e32 v176, 16, v177
	v_and_b32_e32 v177, 0xffff0000, v177
	v_lshlrev_b64 v[188:189], 1, v[188:189]
	v_lshl_add_u64 v[190:191], s[8:9], 0, v[188:189]
	v_lshl_add_u64 v[188:189], s[14:15], 0, v[188:189]
	s_waitcnt vmcnt(1)
	v_pk_fma_f32 v[22:23], v[28:29], v[22:23], v[174:175]
	v_pk_fma_f32 v[20:21], v[30:31], v[20:21], v[192:193]
	s_waitcnt vmcnt(0)
	v_pk_fma_f32 v[26:27], v[32:33], v[26:27], v[176:177]
	v_pk_fma_f32 v[24:25], v[178:179], v[24:25], v[194:195]
	v_cvt_pk_bf16_f32 v20, v20, v21
	v_cvt_pk_bf16_f32 v21, v22, v23
	v_cvt_pk_bf16_f32 v23, v26, v27
	v_pk_mul_f32 v[178:179], v[132:133], s[38:39] op_sel_hi:[1,0]
	v_cvt_pk_bf16_f32 v22, v24, v25
	global_store_dwordx4 v[180:181], v[20:23], off offset:256
	v_mad_i64_i32 v[24:25], s[52:53], v19, s74, v[12:13]
	global_load_dwordx4 v[20:23], v[190:191], off
	v_lshl_add_u64 v[32:33], v[24:25], 0, v[14:15]
	global_load_dwordx4 v[24:27], v[32:33], off
	global_load_dwordx4 v[28:31], v[32:33], off offset:16
	v_pk_mul_f32 v[180:181], v[130:131], s[38:39] op_sel_hi:[1,0]
	v_pk_mul_f32 v[192:193], v[124:125], s[38:39] op_sel_hi:[1,0]
	v_pk_mul_f32 v[194:195], v[122:123], s[38:39] op_sel_hi:[1,0]
	global_load_dwordx4 v[174:177], v[190:191], off offset:256
	v_add_u32_e32 v19, 0xffffe030, v8
	v_lshrrev_b32_e32 v19, 3, v19
	v_add_u32_e32 v19, 4, v19
	v_cndmask_b32_e32 v18, v19, v18, vcc
	v_mad_i64_i32 v[18:19], s[52:53], v18, s74, v[12:13]
	v_cmp_gt_i32_e32 vcc, s10, v8
	s_movk_i32 s10, 0x1f70
	s_waitcnt vmcnt(3)
	v_lshlrev_b32_e32 v190, 16, v20
	v_and_b32_e32 v191, 0xffff0000, v20
	v_lshlrev_b32_e32 v20, 16, v21
	v_and_b32_e32 v21, 0xffff0000, v21
	v_lshlrev_b32_e32 v196, 16, v22
	v_and_b32_e32 v197, 0xffff0000, v22
	v_lshlrev_b32_e32 v22, 16, v23
	v_and_b32_e32 v23, 0xffff0000, v23
	s_waitcnt vmcnt(2)
	v_pk_fma_f32 v[26:27], v[178:179], v[26:27], v[20:21]
	v_pk_fma_f32 v[20:21], v[180:181], v[24:25], v[190:191]
	s_waitcnt vmcnt(1)
	v_pk_fma_f32 v[24:25], v[192:193], v[30:31], v[22:23]
	v_pk_fma_f32 v[22:23], v[194:195], v[28:29], v[196:197]
	v_cvt_pk_bf16_f32 v20, v20, v21
	v_cvt_pk_bf16_f32 v21, v26, v27
	v_pk_mul_f32 v[28:29], v[120:121], s[38:39] op_sel_hi:[1,0]
	v_cvt_pk_bf16_f32 v22, v22, v23
	v_cvt_pk_bf16_f32 v23, v24, v25
	global_store_dwordx4 v[188:189], v[20:23], off
	global_load_dwordx4 v[20:23], v[32:33], off offset:512
	s_nop 0
	global_load_dwordx4 v[24:27], v[32:33], off offset:528
	v_pk_mul_f32 v[30:31], v[118:119], s[38:39] op_sel_hi:[1,0]
	v_lshlrev_b64 v[180:181], 11, v[2:3]
	s_waitcnt vmcnt(3)
	v_lshlrev_b32_e32 v192, 16, v174
	v_and_b32_e32 v193, 0xffff0000, v174
	v_lshlrev_b32_e32 v174, 16, v175
	v_and_b32_e32 v175, 0xffff0000, v175
	v_pk_mul_f32 v[32:33], v[112:113], s[38:39] op_sel_hi:[1,0]
	v_pk_mul_f32 v[178:179], v[110:111], s[38:39] op_sel_hi:[1,0]
	v_lshl_add_u64 v[180:181], v[180:181], 0, v[10:11]
	v_lshlrev_b32_e32 v194, 16, v176
	v_and_b32_e32 v195, 0xffff0000, v176
	v_lshlrev_b32_e32 v176, 16, v177
	v_and_b32_e32 v177, 0xffff0000, v177
	v_lshlrev_b64 v[180:181], 1, v[180:181]
	v_lshl_add_u64 v[190:191], s[8:9], 0, v[180:181]
	v_lshl_add_u64 v[180:181], s[14:15], 0, v[180:181]
	s_waitcnt vmcnt(1)
	v_pk_fma_f32 v[22:23], v[28:29], v[22:23], v[174:175]
	v_pk_fma_f32 v[20:21], v[30:31], v[20:21], v[192:193]
	s_waitcnt vmcnt(0)
	v_pk_fma_f32 v[26:27], v[32:33], v[26:27], v[176:177]
	v_pk_fma_f32 v[24:25], v[178:179], v[24:25], v[194:195]
	v_cvt_pk_bf16_f32 v20, v20, v21
	v_cvt_pk_bf16_f32 v21, v22, v23
	v_cvt_pk_bf16_f32 v23, v26, v27
	v_lshl_add_u64 v[32:33], v[18:19], 0, v[14:15]
	v_cvt_pk_bf16_f32 v22, v24, v25
	global_store_dwordx4 v[188:189], v[20:23], off offset:256
	global_load_dwordx4 v[20:23], v[190:191], off
	global_load_dwordx4 v[24:27], v[32:33], off
	global_load_dwordx4 v[28:31], v[32:33], off offset:16
	v_pk_mul_f32 v[18:19], v[116:117], s[38:39] op_sel_hi:[1,0]
	v_pk_mul_f32 v[178:179], v[114:115], s[38:39] op_sel_hi:[1,0]
	global_load_dwordx4 v[174:177], v[190:191], off offset:256
	v_pk_mul_f32 v[188:189], v[108:109], s[38:39] op_sel_hi:[1,0]
	v_pk_mul_f32 v[192:193], v[106:107], s[38:39] op_sel_hi:[1,0]
	s_waitcnt vmcnt(3)
; __device__ __forceinline__ unsigned pk2(float lo, float hi) { unsigned r; asm("v_cvt_pk_bf16_f32 %0, %1, %2" : "=v"(r) : "v"(lo), "v"(hi)); return r; }
;     __device__ __forceinline__ void operator()(const f32x4 (&acc)[2][2][4][2], const Unit& u, int wr, int wc, int fr, int fq) const {
;     ...
;         for (int ai = 0; ai < 2; ++ai)
; #pragma unroll
;             for (int m = 0; m < 4; ++m) { const int r = row0 + ai * HALF + m * 16; const size_t off = (size_t)r * mk::D + col0; const float* gp = gate + (size_t)mk::seq_of(r) * mk::NMOD + col0;
;                 float ss = 0.f;
; #pragma unroll
;                 for (int bj = 0; bj < 2; ++bj) { const int o = bj * HALF;
;                     f32x4 x0, x1;
;                     if constexpr (XIF32) { x0 = *(const f32x4*)((const float*)xi + off + o); x1 = *(const f32x4*)((const float*)xi + off + o + 4); }
;                     else { const u32x4 w = *(const u32x4*)((const bf16*)xi + off + o);
;                         x0 = (f32x4){__uint_as_float(w.x << 16), __uint_as_float(w.x & 0xffff0000u), __uint_as_float(w.y << 16), __uint_as_float(w.y & 0xffff0000u)};
;                         x1 = (f32x4){__uint_as_float(w.z << 16), __uint_as_float(w.z & 0xffff0000u), __uint_as_float(w.w << 16), __uint_as_float(w.w & 0xffff0000u)}; }
;                     f32x4 v0 = acc[ai][bj][m][0] * ascale, v1 = acc[ai][bj][m][1] * ascale;
;                     if constexpr (MODE == 1) { v0 *= *(const f32x4*)(extra + col0 + o); v1 *= *(const f32x4*)(extra + col0 + o + 4); }
;                     const f32x4 y0 = x0 + *(const f32x4*)(gp + o) * v0, y1 = x1 + *(const f32x4*)(gp + o + 4) * v1;
;                     u32x4 w; w.x = mk::pk2(y0[0], y0[1]); w.y = mk::pk2(y0[2], y0[3]); w.z = mk::pk2(y1[0], y1[1]); w.w = mk::pk2(y1[2], y1[3]); *(u32x4*)(xo + off + o) = w;
	v_lshlrev_b32_e32 v190, 16, v20
	v_and_b32_e32 v191, 0xffff0000, v20
	v_lshlrev_b32_e32 v20, 16, v21
	v_and_b32_e32 v21, 0xffff0000, v21
	v_lshlrev_b32_e32 v194, 16, v22
	v_and_b32_e32 v195, 0xffff0000, v22
	v_lshlrev_b32_e32 v22, 16, v23
	v_and_b32_e32 v23, 0xffff0000, v23
	s_waitcnt vmcnt(2)
	v_pk_fma_f32 v[20:21], v[18:19], v[26:27], v[20:21]
	v_pk_fma_f32 v[18:19], v[178:179], v[24:25], v[190:191]
	s_waitcnt vmcnt(1)
	v_pk_fma_f32 v[22:23], v[188:189], v[30:31], v[22:23]
	v_pk_fma_f32 v[24:25], v[192:193], v[28:29], v[194:195]
	v_cvt_pk_bf16_f32 v18, v18, v19
	v_cvt_pk_bf16_f32 v19, v20, v21
	v_cvt_pk_bf16_f32 v21, v22, v23
	v_add_u32_e32 v188, 0x80, v8
	v_cvt_pk_bf16_f32 v20, v24, v25
	global_store_dwordx4 v[180:181], v[18:21], off
	global_load_dwordx4 v[20:23], v[32:33], off offset:512
	s_nop 0
	global_load_dwordx4 v[24:27], v[32:33], off offset:528
	v_add_u32_e32 v19, 0xffffe080, v8
	v_ashrrev_i32_e32 v189, 31, v188
	v_pk_mul_f32 v[28:29], v[104:105], s[38:39] op_sel_hi:[1,0]
	v_pk_mul_f32 v[30:31], v[102:103], s[38:39] op_sel_hi:[1,0]
	v_ashrrev_i32_e32 v18, 11, v188
	v_lshlrev_b64 v[188:189], 11, v[188:189]
	s_waitcnt vmcnt(3)
	v_lshlrev_b32_e32 v192, 16, v174
	v_and_b32_e32 v193, 0xffff0000, v174
	v_lshlrev_b32_e32 v174, 16, v175
	v_and_b32_e32 v175, 0xffff0000, v175
	v_lshrrev_b32_e32 v19, 3, v19
	v_pk_mul_f32 v[32:33], v[100:101], s[38:39] op_sel_hi:[1,0]
	v_pk_mul_f32 v[178:179], v[98:99], s[38:39] op_sel_hi:[1,0]
	v_lshl_add_u64 v[188:189], v[188:189], 0, v[10:11]
	v_lshlrev_b32_e32 v194, 16, v176
	v_and_b32_e32 v195, 0xffff0000, v176
	v_lshlrev_b32_e32 v176, 16, v177
	v_and_b32_e32 v177, 0xffff0000, v177
	v_or_b32_e32 v19, 4, v19
	v_lshlrev_b64 v[188:189], 1, v[188:189]
	v_cndmask_b32_e32 v19, v19, v18, vcc
	v_lshl_add_u64 v[190:191], s[8:9], 0, v[188:189]
	v_lshl_add_u64 v[188:189], s[14:15], 0, v[188:189]
	v_cmp_gt_i32_e32 vcc, s10, v8
	s_waitcnt vmcnt(1)
	v_pk_fma_f32 v[22:23], v[28:29], v[22:23], v[174:175]
	v_pk_fma_f32 v[20:21], v[30:31], v[20:21], v[192:193]
	s_waitcnt vmcnt(0)
	v_pk_fma_f32 v[26:27], v[32:33], v[26:27], v[176:177]
	v_pk_fma_f32 v[24:25], v[178:179], v[24:25], v[194:195]
	v_cvt_pk_bf16_f32 v20, v20, v21
	v_cvt_pk_bf16_f32 v21, v22, v23
	v_cvt_pk_bf16_f32 v23, v26, v27
	v_pk_mul_f32 v[178:179], v[96:97], s[38:39] op_sel_hi:[1,0]
	v_cvt_pk_bf16_f32 v22, v24, v25
	global_store_dwordx4 v[180:181], v[20:23], off offset:256
	v_mad_i64_i32 v[24:25], s[52:53], v19, s74, v[12:13]
	global_load_dwordx4 v[20:23], v[190:191], off
	v_lshl_add_u64 v[32:33], v[24:25], 0, v[14:15]
	global_load_dwordx4 v[24:27], v[32:33], off
	global_load_dwordx4 v[28:31], v[32:33], off offset:16
	v_pk_mul_f32 v[180:181], v[94:95], s[38:39] op_sel_hi:[1,0]
	v_pk_mul_f32 v[192:193], v[92:93], s[38:39] op_sel_hi:[1,0]
	v_pk_mul_f32 v[194:195], v[90:91], s[38:39] op_sel_hi:[1,0]
	global_load_dwordx4 v[174:177], v[190:191], off offset:256
	v_add_u32_e32 v19, 0xffffe090, v8
	v_lshrrev_b32_e32 v19, 3, v19
	v_or_b32_e32 v19, 4, v19
	v_cndmask_b32_e32 v19, v19, v18, vcc
	v_cmp_gt_i32_e32 vcc, s75, v8
	s_waitcnt vmcnt(3)
	v_lshlrev_b32_e32 v190, 16, v20
	v_and_b32_e32 v191, 0xffff0000, v20
	v_lshlrev_b32_e32 v20, 16, v21
	v_and_b32_e32 v21, 0xffff0000, v21
	v_lshlrev_b32_e32 v196, 16, v22
	v_and_b32_e32 v197, 0xffff0000, v22
	v_lshlrev_b32_e32 v22, 16, v23
	v_and_b32_e32 v23, 0xffff0000, v23
	s_waitcnt vmcnt(2)
	v_pk_fma_f32 v[26:27], v[178:179], v[26:27], v[20:21]
	v_pk_fma_f32 v[20:21], v[180:181], v[24:25], v[190:191]
	s_waitcnt vmcnt(1)
	v_pk_fma_f32 v[24:25], v[192:193], v[30:31], v[22:23]
	v_pk_fma_f32 v[22:23], v[194:195], v[28:29], v[196:197]
	v_cvt_pk_bf16_f32 v20, v20, v21
	v_cvt_pk_bf16_f32 v21, v26, v27
	v_pk_mul_f32 v[28:29], v[88:89], s[38:39] op_sel_hi:[1,0]
	v_cvt_pk_bf16_f32 v22, v22, v23
	v_cvt_pk_bf16_f32 v23, v24, v25
	global_store_dwordx4 v[188:189], v[20:23], off
	global_load_dwordx4 v[20:23], v[32:33], off offset:512
	s_nop 0
	global_load_dwordx4 v[24:27], v[32:33], off offset:528
	v_pk_mul_f32 v[30:31], v[86:87], s[38:39] op_sel_hi:[1,0]
	s_waitcnt vmcnt(3)
	v_lshlrev_b32_e32 v192, 16, v174
	v_and_b32_e32 v193, 0xffff0000, v174
	v_lshlrev_b32_e32 v174, 16, v175
	v_and_b32_e32 v175, 0xffff0000, v175
	v_pk_mul_f32 v[32:33], v[80:81], s[38:39] op_sel_hi:[1,0]
	v_pk_mul_f32 v[178:179], v[78:79], s[38:39] op_sel_hi:[1,0]
	v_lshlrev_b32_e32 v194, 16, v176
	v_and_b32_e32 v195, 0xffff0000, v176
	v_lshlrev_b32_e32 v176, 16, v177
	v_and_b32_e32 v177, 0xffff0000, v177
	v_lshl_add_u64 v[180:181], v[16:17], 0, s[40:41]
	v_lshl_add_u64 v[190:191], s[8:9], 0, v[180:181]
	v_lshl_add_u64 v[180:181], s[14:15], 0, v[180:181]
	s_waitcnt vmcnt(1)
	v_pk_fma_f32 v[22:23], v[28:29], v[22:23], v[174:175]
	v_pk_fma_f32 v[20:21], v[30:31], v[20:21], v[192:193]
	s_waitcnt vmcnt(0)
	v_pk_fma_f32 v[26:27], v[32:33], v[26:27], v[176:177]
	v_pk_fma_f32 v[24:25], v[178:179], v[24:25], v[194:195]
	v_cvt_pk_bf16_f32 v20, v20, v21
	v_cvt_pk_bf16_f32 v21, v22, v23
	v_cvt_pk_bf16_f32 v23, v26, v27
	v_pk_mul_f32 v[178:179], v[84:85], s[38:39] op_sel_hi:[1,0]
	v_cvt_pk_bf16_f32 v22, v24, v25
	global_store_dwordx4 v[188:189], v[20:23], off offset:256
	v_mad_i64_i32 v[24:25], s[52:53], v19, s74, v[12:13]
	global_load_dwordx4 v[20:23], v[190:191], off
	v_lshl_add_u64 v[32:33], v[24:25], 0, v[14:15]
	global_load_dwordx4 v[24:27], v[32:33], off
	global_load_dwordx4 v[28:31], v[32:33], off offset:16
	v_pk_mul_f32 v[188:189], v[82:83], s[38:39] op_sel_hi:[1,0]
	v_pk_mul_f32 v[192:193], v[76:77], s[38:39] op_sel_hi:[1,0]
	v_pk_mul_f32 v[194:195], v[74:75], s[38:39] op_sel_hi:[1,0]
	global_load_dwordx4 v[174:177], v[190:191], off offset:256
	v_add_u32_e32 v19, 0xffffe0a0, v8
	v_lshrrev_b32_e32 v19, 3, v19
	v_add_u32_e32 v19, 4, v19
	v_cndmask_b32_e32 v19, v19, v18, vcc
	v_cmp_gt_i32_e32 vcc, s76, v8
	s_waitcnt vmcnt(3)
; __device__ __forceinline__ unsigned pk2(float lo, float hi) { unsigned r; asm("v_cvt_pk_bf16_f32 %0, %1, %2" : "=v"(r) : "v"(lo), "v"(hi)); return r; }
;     __device__ __forceinline__ void operator()(const f32x4 (&acc)[2][2][4][2], const Unit& u, int wr, int wc, int fr, int fq) const {
;     ...
;         for (int ai = 0; ai < 2; ++ai)
; #pragma unroll
;             for (int m = 0; m < 4; ++m) { const int r = row0 + ai * HALF + m * 16; const size_t off = (size_t)r * mk::D + col0; const float* gp = gate + (size_t)mk::seq_of(r) * mk::NMOD + col0;
;                 float ss = 0.f;
; #pragma unroll
;                 for (int bj = 0; bj < 2; ++bj) { const int o = bj * HALF;
;                     f32x4 x0, x1;
;                     if constexpr (XIF32) { x0 = *(const f32x4*)((const float*)xi + off + o); x1 = *(const f32x4*)((const float*)xi + off + o + 4); }
;                     else { const u32x4 w = *(const u32x4*)((const bf16*)xi + off + o);
;                         x0 = (f32x4){__uint_as_float(w.x << 16), __uint_as_float(w.x & 0xffff0000u), __uint_as_float(w.y << 16), __uint_as_float(w.y & 0xffff0000u)};
;                         x1 = (f32x4){__uint_as_float(w.z << 16), __uint_as_float(w.z & 0xffff0000u), __uint_as_float(w.w << 16), __uint_as_float(w.w & 0xffff0000u)}; }
;                     f32x4 v0 = acc[ai][bj][m][0] * ascale, v1 = acc[ai][bj][m][1] * ascale;
;                     if constexpr (MODE == 1) { v0 *= *(const f32x4*)(extra + col0 + o); v1 *= *(const f32x4*)(extra + col0 + o + 4); }
;                     const f32x4 y0 = x0 + *(const f32x4*)(gp + o) * v0, y1 = x1 + *(const f32x4*)(gp + o + 4) * v1;
;                     u32x4 w; w.x = mk::pk2(y0[0], y0[1]); w.y = mk::pk2(y0[2], y0[3]); w.z = mk::pk2(y1[0], y1[1]); w.w = mk::pk2(y1[2], y1[3]); *(u32x4*)(xo + off + o) = w;
	v_lshlrev_b32_e32 v190, 16, v20
	v_and_b32_e32 v191, 0xffff0000, v20
	v_lshlrev_b32_e32 v20, 16, v21
	v_and_b32_e32 v21, 0xffff0000, v21
	v_lshlrev_b32_e32 v196, 16, v22
	v_and_b32_e32 v197, 0xffff0000, v22
	v_lshlrev_b32_e32 v22, 16, v23
	v_and_b32_e32 v23, 0xffff0000, v23
	s_waitcnt vmcnt(2)
	v_pk_fma_f32 v[26:27], v[178:179], v[26:27], v[20:21]
	v_pk_fma_f32 v[20:21], v[188:189], v[24:25], v[190:191]
	s_waitcnt vmcnt(1)
	v_pk_fma_f32 v[24:25], v[192:193], v[30:31], v[22:23]
	v_pk_fma_f32 v[22:23], v[194:195], v[28:29], v[196:197]
	v_cvt_pk_bf16_f32 v20, v20, v21
	v_cvt_pk_bf16_f32 v21, v26, v27
	v_pk_mul_f32 v[28:29], v[72:73], s[38:39] op_sel_hi:[1,0]
	v_cvt_pk_bf16_f32 v22, v22, v23
	v_cvt_pk_bf16_f32 v23, v24, v25
	global_store_dwordx4 v[180:181], v[20:23], off
	global_load_dwordx4 v[20:23], v[32:33], off offset:512
	s_nop 0
	global_load_dwordx4 v[24:27], v[32:33], off offset:528
	v_pk_mul_f32 v[30:31], v[70:71], s[38:39] op_sel_hi:[1,0]
	s_waitcnt vmcnt(3)
	v_lshlrev_b32_e32 v192, 16, v174
	v_and_b32_e32 v193, 0xffff0000, v174
	v_lshlrev_b32_e32 v174, 16, v175
	v_and_b32_e32 v175, 0xffff0000, v175
	v_pk_mul_f32 v[32:33], v[64:65], s[38:39] op_sel_hi:[1,0]
	v_pk_mul_f32 v[178:179], v[62:63], s[38:39] op_sel_hi:[1,0]
	v_lshlrev_b32_e32 v194, 16, v176
	v_and_b32_e32 v195, 0xffff0000, v176
	v_lshlrev_b32_e32 v176, 16, v177
	v_and_b32_e32 v177, 0xffff0000, v177
	v_lshl_add_u64 v[188:189], v[16:17], 0, s[42:43]
	v_lshl_add_u64 v[190:191], s[8:9], 0, v[188:189]
	v_lshl_add_u64 v[188:189], s[14:15], 0, v[188:189]
	s_waitcnt vmcnt(1)
	v_pk_fma_f32 v[22:23], v[28:29], v[22:23], v[174:175]
	v_pk_fma_f32 v[20:21], v[30:31], v[20:21], v[192:193]
	s_waitcnt vmcnt(0)
	v_pk_fma_f32 v[26:27], v[32:33], v[26:27], v[176:177]
	v_pk_fma_f32 v[24:25], v[178:179], v[24:25], v[194:195]
	v_cvt_pk_bf16_f32 v20, v20, v21
	v_cvt_pk_bf16_f32 v21, v22, v23
	v_cvt_pk_bf16_f32 v23, v26, v27
	v_pk_mul_f32 v[178:179], v[68:69], s[38:39] op_sel_hi:[1,0]
	v_cvt_pk_bf16_f32 v22, v24, v25
	global_store_dwordx4 v[180:181], v[20:23], off offset:256
	v_mad_i64_i32 v[24:25], s[52:53], v19, s74, v[12:13]
	global_load_dwordx4 v[20:23], v[190:191], off
	v_lshl_add_u64 v[32:33], v[24:25], 0, v[14:15]
	global_load_dwordx4 v[24:27], v[32:33], off
	global_load_dwordx4 v[28:31], v[32:33], off offset:16
	v_pk_mul_f32 v[180:181], v[66:67], s[38:39] op_sel_hi:[1,0]
	v_pk_mul_f32 v[192:193], v[60:61], s[38:39] op_sel_hi:[1,0]
	v_pk_mul_f32 v[194:195], v[58:59], s[38:39] op_sel_hi:[1,0]
	global_load_dwordx4 v[174:177], v[190:191], off offset:256
	v_add_u32_e32 v19, 0xffffe0b0, v8
	s_waitcnt vmcnt(3)
	v_lshlrev_b32_e32 v190, 16, v20
	v_and_b32_e32 v191, 0xffff0000, v20
	v_lshlrev_b32_e32 v20, 16, v21
	v_and_b32_e32 v21, 0xffff0000, v21
	v_lshlrev_b32_e32 v196, 16, v22
	v_and_b32_e32 v197, 0xffff0000, v22
	v_lshlrev_b32_e32 v22, 16, v23
	v_and_b32_e32 v23, 0xffff0000, v23
	s_waitcnt vmcnt(2)
	v_pk_fma_f32 v[26:27], v[178:179], v[26:27], v[20:21]
	v_pk_fma_f32 v[20:21], v[180:181], v[24:25], v[190:191]
	s_waitcnt vmcnt(1)
	v_pk_fma_f32 v[24:25], v[192:193], v[30:31], v[22:23]
	v_pk_fma_f32 v[22:23], v[194:195], v[28:29], v[196:197]
	v_cvt_pk_bf16_f32 v20, v20, v21
	v_cvt_pk_bf16_f32 v21, v26, v27
	v_pk_mul_f32 v[30:31], v[54:55], s[38:39] op_sel_hi:[1,0]
	v_cvt_pk_bf16_f32 v22, v22, v23
	v_cvt_pk_bf16_f32 v23, v24, v25
	global_store_dwordx4 v[188:189], v[20:23], off
	global_load_dwordx4 v[20:23], v[32:33], off offset:512
	s_nop 0
	global_load_dwordx4 v[24:27], v[32:33], off offset:528
	v_lshl_add_u64 v[180:181], v[16:17], 0, s[16:17]
	s_waitcnt vmcnt(3)
; __device__ __forceinline__ unsigned pk2(float lo, float hi) { unsigned r; asm("v_cvt_pk_bf16_f32 %0, %1, %2" : "=v"(r) : "v"(lo), "v"(hi)); return r; }
;     __device__ __forceinline__ void operator()(const f32x4 (&acc)[2][2][4][2], const Unit& u, int wr, int wc, int fr, int fq) const {
;     ...
;         for (int ai = 0; ai < 2; ++ai)
; #pragma unroll
;             for (int m = 0; m < 4; ++m) { const int r = row0 + ai * HALF + m * 16; const size_t off = (size_t)r * mk::D + col0; const float* gp = gate + (size_t)mk::seq_of(r) * mk::NMOD + col0;
;                 float ss = 0.f;
; #pragma unroll
;                 for (int bj = 0; bj < 2; ++bj) { const int o = bj * HALF;
;                     f32x4 x0, x1;
;                     if constexpr (XIF32) { x0 = *(const f32x4*)((const float*)xi + off + o); x1 = *(const f32x4*)((const float*)xi + off + o + 4); }
;                     else { const u32x4 w = *(const u32x4*)((const bf16*)xi + off + o);
;                         x0 = (f32x4){__uint_as_float(w.x << 16), __uint_as_float(w.x & 0xffff0000u), __uint_as_float(w.y << 16), __uint_as_float(w.y & 0xffff0000u)};
;                         x1 = (f32x4){__uint_as_float(w.z << 16), __uint_as_float(w.z & 0xffff0000u), __uint_as_float(w.w << 16), __uint_as_float(w.w & 0xffff0000u)}; }
;                     f32x4 v0 = acc[ai][bj][m][0] * ascale, v1 = acc[ai][bj][m][1] * ascale;
;                     if constexpr (MODE == 1) { v0 *= *(const f32x4*)(extra + col0 + o); v1 *= *(const f32x4*)(extra + col0 + o + 4); }
;                     const f32x4 y0 = x0 + *(const f32x4*)(gp + o) * v0, y1 = x1 + *(const f32x4*)(gp + o + 4) * v1;
;                     u32x4 w; w.x = mk::pk2(y0[0], y0[1]); w.y = mk::pk2(y0[2], y0[3]); w.z = mk::pk2(y1[0], y1[1]); w.w = mk::pk2(y1[2], y1[3]); *(u32x4*)(xo + off + o) = w;
	v_lshlrev_b32_e32 v16, 16, v174
	v_and_b32_e32 v17, 0xffff0000, v174
	v_pk_mul_f32 v[28:29], v[56:57], s[38:39] op_sel_hi:[1,0]
	v_lshlrev_b32_e32 v174, 16, v175
	v_and_b32_e32 v175, 0xffff0000, v175
	v_pk_mul_f32 v[32:33], v[48:49], s[38:39] op_sel_hi:[1,0]
	v_pk_mul_f32 v[178:179], v[46:47], s[38:39] op_sel_hi:[1,0]
	v_lshlrev_b32_e32 v192, 16, v176
	v_and_b32_e32 v193, 0xffff0000, v176
	v_lshlrev_b32_e32 v176, 16, v177
	v_and_b32_e32 v177, 0xffff0000, v177
	v_lshl_add_u64 v[190:191], s[8:9], 0, v[180:181]
	s_waitcnt vmcnt(1)
	v_pk_fma_f32 v[16:17], v[30:31], v[20:21], v[16:17]
	v_pk_fma_f32 v[22:23], v[28:29], v[22:23], v[174:175]
	v_cvt_pk_bf16_f32 v20, v16, v17
	v_lshrrev_b32_e32 v16, 3, v19
	s_waitcnt vmcnt(0)
	v_pk_fma_f32 v[26:27], v[32:33], v[26:27], v[176:177]
	v_pk_fma_f32 v[24:25], v[178:179], v[24:25], v[192:193]
	v_cvt_pk_bf16_f32 v21, v22, v23
	v_cvt_pk_bf16_f32 v23, v26, v27
	v_add_u32_e32 v16, 4, v16
	v_cvt_pk_bf16_f32 v22, v24, v25
	global_store_dwordx4 v[188:189], v[20:23], off offset:256
	v_cndmask_b32_e32 v16, v16, v18, vcc
	global_load_dwordx4 v[20:23], v[190:191], off
	v_mad_i64_i32 v[12:13], s[52:53], v16, s74, v[12:13]
	v_lshl_add_u64 v[28:29], v[12:13], 0, v[14:15]
	global_load_dwordx4 v[12:15], v[28:29], off
	global_load_dwordx4 v[16:19], v[28:29], off offset:16
	v_pk_mul_f32 v[30:31], v[52:53], s[38:39] op_sel_hi:[1,0]
	v_pk_mul_f32 v[32:33], v[50:51], s[38:39] op_sel_hi:[1,0]
	v_lshl_add_u64 v[178:179], s[14:15], 0, v[180:181]
	v_pk_mul_f32 v[174:175], v[44:45], s[38:39] op_sel_hi:[1,0]
	v_pk_mul_f32 v[176:177], v[42:43], s[38:39] op_sel_hi:[1,0]
	global_load_dwordx4 v[24:27], v[190:191], off offset:256
	s_waitcnt vmcnt(3)
	v_lshlrev_b32_e32 v180, 16, v20
	v_and_b32_e32 v181, 0xffff0000, v20
	v_lshlrev_b32_e32 v20, 16, v21
	v_and_b32_e32 v21, 0xffff0000, v21
	v_lshlrev_b32_e32 v188, 16, v22
	v_and_b32_e32 v189, 0xffff0000, v22
	v_lshlrev_b32_e32 v22, 16, v23
	v_and_b32_e32 v23, 0xffff0000, v23
	s_waitcnt vmcnt(2)
	v_pk_fma_f32 v[14:15], v[30:31], v[14:15], v[20:21]
	v_pk_fma_f32 v[12:13], v[32:33], v[12:13], v[180:181]
	s_waitcnt vmcnt(1)
	v_pk_fma_f32 v[18:19], v[174:175], v[18:19], v[22:23]
	v_pk_fma_f32 v[16:17], v[176:177], v[16:17], v[188:189]
	v_cvt_pk_bf16_f32 v12, v12, v13
	v_cvt_pk_bf16_f32 v13, v14, v15
	v_cvt_pk_bf16_f32 v15, v18, v19
	v_pk_mul_f32 v[20:21], v[40:41], s[38:39] op_sel_hi:[1,0]
	v_cvt_pk_bf16_f32 v14, v16, v17
	global_store_dwordx4 v[178:179], v[12:15], off
	global_load_dwordx4 v[12:15], v[28:29], off offset:512
	s_nop 0
	global_load_dwordx4 v[16:19], v[28:29], off offset:528
	v_pk_mul_f32 v[22:23], v[38:39], s[38:39] op_sel_hi:[1,0]
	s_waitcnt vmcnt(3)
	v_lshlrev_b32_e32 v32, 16, v24
	v_and_b32_e32 v33, 0xffff0000, v24
	v_lshlrev_b32_e32 v24, 16, v25
	v_and_b32_e32 v25, 0xffff0000, v25
	v_pk_mul_f32 v[28:29], v[36:37], s[38:39] op_sel_hi:[1,0]
	v_pk_mul_f32 v[30:31], v[34:35], s[38:39] op_sel_hi:[1,0]
	v_lshlrev_b32_e32 v174, 16, v26
	v_and_b32_e32 v175, 0xffff0000, v26
	v_lshlrev_b32_e32 v26, 16, v27
	v_and_b32_e32 v27, 0xffff0000, v27
	s_waitcnt vmcnt(1)
	v_pk_fma_f32 v[14:15], v[20:21], v[14:15], v[24:25]
	v_pk_fma_f32 v[12:13], v[22:23], v[12:13], v[32:33]
	s_waitcnt vmcnt(0)
	v_pk_fma_f32 v[18:19], v[28:29], v[18:19], v[26:27]
	v_pk_fma_f32 v[16:17], v[30:31], v[16:17], v[174:175]
	v_cvt_pk_bf16_f32 v12, v12, v13
	v_cvt_pk_bf16_f32 v13, v14, v15
	v_cvt_pk_bf16_f32 v15, v18, v19
	s_nop 0
	v_cvt_pk_bf16_f32 v14, v16, v17
	global_store_dwordx4 v[178:179], v[12:15], off offset:256
	s_cbranch_execz .LBB0_2019
